# v76 + back-edge rotation in the 7 GEMM K loops (loop-back barrier becomes the loop head; branch resolved in front of it; exit path keeps a barrier copy)
# baseline (speedup 1.0000x reference)
; template <class Epi, class S_t>
; __device__ __forceinline__ void gemm_phase(LAS unsigned char* lds, int lda, int ldb, const S_t& S, const Epi& E) {
;     ...
; #pragma unroll
;         for (int a = 0; a < 2; ++a)
; #pragma unroll
;             for (int b = 0; b < 2; ++b)
; #pragma unroll
;                 for (int m = 0; m < 4; ++m)
; #pragma unroll
;                     for (int n = 0; n < 2; ++n) acc[a][b][m][n] = (f32x4){0.f, 0.f, 0.f, 0.f};
;         cur = nxt; cA = nA; cB = nB; ++ui;
.LBB0_132:
	s_add_u32 s16, s16, 0x80080
	s_addc_u32 s17, s17, 0
	s_add_u32 s0, s18, 0x100
	s_addc_u32 s1, s19, 0
	s_mov_b32 s9, -2
	v_mov_b64_e32 v[0:1], 0
	v_mov_b64_e32 v[2:3], 0
	v_mov_b64_e32 v[4:5], 0
	v_mov_b64_e32 v[6:7], 0
	v_mov_b64_e32 v[8:9], 0
	v_mov_b64_e32 v[10:11], 0
	v_mov_b64_e32 v[12:13], 0
	v_mov_b64_e32 v[14:15], 0
	v_mov_b64_e32 v[16:17], 0
	v_mov_b64_e32 v[18:19], 0
	v_mov_b64_e32 v[20:21], 0
	v_mov_b64_e32 v[22:23], 0
	v_mov_b64_e32 v[24:25], 0
	v_mov_b64_e32 v[26:27], 0
	v_mov_b64_e32 v[28:29], 0
	v_mov_b64_e32 v[30:31], 0
	v_mov_b64_e32 v[32:33], 0
	v_mov_b64_e32 v[34:35], 0
	v_mov_b64_e32 v[36:37], 0
	v_mov_b64_e32 v[38:39], 0
	v_mov_b64_e32 v[40:41], 0
	v_mov_b64_e32 v[42:43], 0
	v_mov_b64_e32 v[44:45], 0
	v_mov_b64_e32 v[46:47], 0
	v_mov_b64_e32 v[48:49], 0
	v_mov_b64_e32 v[50:51], 0
	v_mov_b64_e32 v[52:53], 0
	v_mov_b64_e32 v[54:55], 0
	v_mov_b64_e32 v[56:57], 0
	v_mov_b64_e32 v[58:59], 0
	v_mov_b64_e32 v[60:61], 0
	v_mov_b64_e32 v[62:63], 0
	v_mov_b64_e32 v[64:65], 0
	v_mov_b64_e32 v[66:67], 0
	v_mov_b64_e32 v[68:69], 0
	v_mov_b64_e32 v[70:71], 0
	v_mov_b64_e32 v[72:73], 0
	v_mov_b64_e32 v[74:75], 0
	v_mov_b64_e32 v[76:77], 0
	v_mov_b64_e32 v[78:79], 0
	v_mov_b64_e32 v[80:81], 0
	v_mov_b64_e32 v[82:83], 0
	v_mov_b64_e32 v[84:85], 0
	v_mov_b64_e32 v[86:87], 0
	v_mov_b64_e32 v[88:89], 0
	v_mov_b64_e32 v[90:91], 0
	v_mov_b64_e32 v[92:93], 0
	v_mov_b64_e32 v[94:95], 0
	v_mov_b64_e32 v[96:97], 0
	v_mov_b64_e32 v[98:99], 0
	v_mov_b64_e32 v[100:101], 0
	v_mov_b64_e32 v[102:103], 0
	v_mov_b64_e32 v[104:105], 0
	v_mov_b64_e32 v[106:107], 0
	v_mov_b64_e32 v[108:109], 0
	v_mov_b64_e32 v[110:111], 0
	v_mov_b64_e32 v[112:113], 0
	v_mov_b64_e32 v[114:115], 0
	v_mov_b64_e32 v[116:117], 0
	v_mov_b64_e32 v[118:119], 0
	v_mov_b64_e32 v[120:121], 0
	v_mov_b64_e32 v[122:123], 0
	v_mov_b64_e32 v[124:125], 0
	v_mov_b64_e32 v[126:127], 0
	s_branch .LBB0_133

; #define PG8_STAGE(bufoff, gbase, voff) do { _Pragma("unroll") for (int _i = 0; _i < 2; ++_i) \
;         __builtin_amdgcn_global_load_lds((const unsigned*)((const char*)(gbase) + (voff)[_i]), (LAS unsigned*)(lds + (bufoff) + ldsw + _i * 8192), 16, 0, 0); } while (0)
; #define PG8_LDA(dst, b, h) do { _Pragma("unroll") for (int m = 0; m < 4; ++m) _Pragma("unroll") for (int k = 0; k < 2; ++k) dst[m][k] = *(const LAS bf16x8*)(lds + PG8_SA(b, h) + aoff + m * 2048 + k * 1024); } while (0)
; #define PG8_LDB(dst, b, h) do { _Pragma("unroll") for (int n = 0; n < 2; ++n) _Pragma("unroll") for (int k = 0; k < 2; ++k) dst[n][k] = *(const LAS bf16x8*)(lds + PG8_SB(b, h) + boff + n * 2048 + k * 1024); } while (0)
; #define PG8_MMA(ai, bj, At, Bt) do { __builtin_amdgcn_s_setprio(1); _Pragma("unroll") for (int m = 0; m < 4; ++m) _Pragma("unroll") for (int n = 0; n < 2; ++n) _Pragma("unroll") for (int k = 0; k < 2; ++k) \
;         acc[ai][bj][m][n] = __builtin_amdgcn_mfma_f32_16x16x32_bf16(Bt[n][k], At[m][k], acc[ai][bj][m][n], 0, 0, 0); __builtin_amdgcn_s_setprio(0); } while (0)
; #define PG8_WAIT_V(n) asm volatile("s_waitcnt vmcnt(" #n ")" ::: "memory")
; #define PG8_WAIT_L(n) asm volatile("s_waitcnt lgkmcnt(" #n ")" ::: "memory")
; #define PG8_BAR __builtin_amdgcn_s_barrier()
; #define PG8_SCHED __builtin_amdgcn_sched_barrier(0)
; template <class Epi, class S_t>
; __device__ __forceinline__ void gemm_phase(LAS unsigned char* lds, int lda, int ldb, const S_t& S, const Epi& E) {
;     ...
;             PG8_LDB(B0, 0, 0); PG8_SCHED; PG8_LDA(At, 0, 0); PG8_STAGE(PG8_SA(1, 1), a1 + hstepA, voffA);
;             PG8_WAIT_L(8); PG8_BAR; PG8_WAIT_L(0); PG8_MMA(0, 0, At, B0); PG8_BAR; PG8_SCHED;
;             PG8_LDB(B1, 0, 1); PG8_STAGE(PG8_SB(0, 0), b2, voffB);
;             PG8_BAR; PG8_WAIT_L(0); PG8_MMA(0, 1, At, B1); PG8_BAR;
;             PG8_LDA(At, 0, 1); PG8_STAGE(PG8_SA(0, 0), a2, voffA);
;             PG8_BAR; PG8_WAIT_L(0); PG8_MMA(1, 0, At, B0); PG8_BAR; PG8_SCHED;
;             PG8_STAGE(PG8_SB(0, 1), b2 + hstepB, voffB);
;             PG8_WAIT_V(6); PG8_BAR; PG8_MMA(1, 1, At, B1); PG8_BAR;
.LBB0_133:
	ds_read_b128 v[152:155], v175
	ds_read_b128 v[156:159], v175 offset:1024
	ds_read_b128 v[160:163], v175 offset:2048
	ds_read_b128 v[164:167], v175 offset:3072
	s_add_u32 s18, s16, 0xfff80080
	s_addc_u32 s19, s17, -1
	s_cmp_eq_u32 s9, 28
	s_cselect_b32 s21, s11, s19
	s_cselect_b32 s20, s10, s18
	s_cselect_b32 s19, s13, s1
	s_cselect_b32 s18, s12, s0
	s_add_i32 m0, s53, 0xc000
	ds_read_b128 v[186:189], v178
	ds_read_b128 v[190:193], v178 offset:1024
	ds_read_b128 v[194:197], v178 offset:2048
	ds_read_b128 v[198:201], v178 offset:3072
	ds_read_b128 v[202:205], v178 offset:4096
	ds_read_b128 v[206:209], v178 offset:5120
	ds_read_b128 v[214:217], v178 offset:6144
	ds_read_b128 v[218:221], v178 offset:7168
	global_load_lds_dwordx4 v148, s[16:17]
	s_add_i32 m0, s53, 0xe000
	s_nop 0
	global_load_lds_dwordx4 v150, s[16:17]
	s_waitcnt lgkmcnt(8)
	s_barrier
	s_waitcnt lgkmcnt(0)
	s_setprio 1
	v_mfma_f32_16x16x32_bf16 v[124:127], v[152:155], v[186:189], v[124:127]
	v_mfma_f32_16x16x32_bf16 v[92:95], v[160:163], v[186:189], v[92:95]
	v_mfma_f32_16x16x32_bf16 v[120:123], v[152:155], v[194:197], v[120:123]
	v_mfma_f32_16x16x32_bf16 v[88:91], v[160:163], v[194:197], v[88:91]
	v_mfma_f32_16x16x32_bf16 v[116:119], v[152:155], v[202:205], v[116:119]
	v_mfma_f32_16x16x32_bf16 v[84:87], v[160:163], v[202:205], v[84:87]
	v_mfma_f32_16x16x32_bf16 v[112:115], v[152:155], v[214:217], v[112:115]
	v_mfma_f32_16x16x32_bf16 v[80:83], v[160:163], v[214:217], v[80:83]
	v_mfma_f32_16x16x32_bf16 v[124:127], v[156:159], v[190:193], v[124:127]
	v_mfma_f32_16x16x32_bf16 v[92:95], v[164:167], v[190:193], v[92:95]
	v_mfma_f32_16x16x32_bf16 v[120:123], v[156:159], v[198:201], v[120:123]
	v_mfma_f32_16x16x32_bf16 v[88:91], v[164:167], v[198:201], v[88:91]
	v_mfma_f32_16x16x32_bf16 v[116:119], v[156:159], v[206:209], v[116:119]
	v_mfma_f32_16x16x32_bf16 v[84:87], v[164:167], v[206:209], v[84:87]
	v_mfma_f32_16x16x32_bf16 v[112:115], v[156:159], v[218:221], v[112:115]
	v_mfma_f32_16x16x32_bf16 v[80:83], v[164:167], v[218:221], v[80:83]
	s_setprio 0
	s_barrier
	s_add_i32 s33, s62, s43
	s_add_u32 s98, s18, s6
	s_addc_u32 s99, s19, s7
	s_mov_b32 m0, s33
	ds_read_b128 v[222:225], v179
	ds_read_b128 v[226:229], v179 offset:1024
	ds_read_b128 v[230:233], v179 offset:2048
	ds_read_b128 v[234:237], v179 offset:3072
	global_load_lds_dwordx4 v128, s[18:19]
	s_add_i32 m0, s33, 0x2000
	s_nop 0
	global_load_lds_dwordx4 v130, s[18:19]
	s_barrier
	s_waitcnt lgkmcnt(0)
	s_setprio 1
	v_mfma_f32_16x16x32_bf16 v[60:63], v[222:225], v[186:189], v[60:63]
	v_mfma_f32_16x16x32_bf16 v[28:31], v[230:233], v[186:189], v[28:31]
	v_mfma_f32_16x16x32_bf16 v[56:59], v[222:225], v[194:197], v[56:59]
	v_mfma_f32_16x16x32_bf16 v[24:27], v[230:233], v[194:197], v[24:27]
	v_mfma_f32_16x16x32_bf16 v[52:55], v[222:225], v[202:205], v[52:55]
	v_mfma_f32_16x16x32_bf16 v[20:23], v[230:233], v[202:205], v[20:23]
	v_mfma_f32_16x16x32_bf16 v[48:51], v[222:225], v[214:217], v[48:51]
	v_mfma_f32_16x16x32_bf16 v[16:19], v[230:233], v[214:217], v[16:19]
	v_mfma_f32_16x16x32_bf16 v[60:63], v[226:229], v[190:193], v[60:63]
	v_mfma_f32_16x16x32_bf16 v[28:31], v[234:237], v[190:193], v[28:31]
	v_mfma_f32_16x16x32_bf16 v[56:59], v[226:229], v[198:201], v[56:59]
	v_mfma_f32_16x16x32_bf16 v[24:27], v[234:237], v[198:201], v[24:27]
	v_mfma_f32_16x16x32_bf16 v[52:55], v[226:229], v[206:209], v[52:55]
	v_mfma_f32_16x16x32_bf16 v[20:23], v[234:237], v[206:209], v[20:23]
	v_mfma_f32_16x16x32_bf16 v[48:51], v[226:229], v[218:221], v[48:51]
	v_mfma_f32_16x16x32_bf16 v[16:19], v[234:237], v[218:221], v[16:19]
	s_setprio 0
	s_mov_b32 m0, s53
	s_add_u32 s100, s20, s6
	s_addc_u32 s101, s21, s7
	s_barrier
	ds_read_b128 v[186:189], v178 offset:16384
	ds_read_b128 v[190:193], v178 offset:17408
	ds_read_b128 v[194:197], v178 offset:18432
	ds_read_b128 v[198:201], v178 offset:19456
	ds_read_b128 v[202:205], v178 offset:20480
	ds_read_b128 v[206:209], v178 offset:21504
	ds_read_b128 v[214:217], v178 offset:22528
	ds_read_b128 v[218:221], v178 offset:23552
	global_load_lds_dwordx4 v128, s[20:21]
	s_mov_b32 m0, s54
	s_nop 0
	global_load_lds_dwordx4 v130, s[20:21]
	s_barrier
	s_waitcnt lgkmcnt(0)
	s_setprio 1
	v_mfma_f32_16x16x32_bf16 v[108:111], v[152:155], v[186:189], v[108:111]
	v_mfma_f32_16x16x32_bf16 v[76:79], v[160:163], v[186:189], v[76:79]
	v_mfma_f32_16x16x32_bf16 v[104:107], v[152:155], v[194:197], v[104:107]
	v_mfma_f32_16x16x32_bf16 v[72:75], v[160:163], v[194:197], v[72:75]
	v_mfma_f32_16x16x32_bf16 v[100:103], v[152:155], v[202:205], v[100:103]
	v_mfma_f32_16x16x32_bf16 v[68:71], v[160:163], v[202:205], v[68:71]
	v_mfma_f32_16x16x32_bf16 v[96:99], v[152:155], v[214:217], v[96:99]
	v_mfma_f32_16x16x32_bf16 v[64:67], v[160:163], v[214:217], v[64:67]
	v_mfma_f32_16x16x32_bf16 v[108:111], v[156:159], v[190:193], v[108:111]
	v_mfma_f32_16x16x32_bf16 v[76:79], v[164:167], v[190:193], v[76:79]
	v_mfma_f32_16x16x32_bf16 v[104:107], v[156:159], v[198:201], v[104:107]
	v_mfma_f32_16x16x32_bf16 v[72:75], v[164:167], v[198:201], v[72:75]
	v_mfma_f32_16x16x32_bf16 v[100:103], v[156:159], v[206:209], v[100:103]
	v_mfma_f32_16x16x32_bf16 v[68:71], v[164:167], v[206:209], v[68:71]
	v_mfma_f32_16x16x32_bf16 v[96:99], v[156:159], v[218:221], v[96:99]
	v_mfma_f32_16x16x32_bf16 v[64:67], v[164:167], v[218:221], v[64:67]
	s_setprio 0
	s_barrier
	s_add_u32 s66, s18, 0x80000
	s_addc_u32 s67, s19, 0
	s_add_i32 s33, s63, s43
	s_mov_b32 m0, s33
	s_nop 0
	global_load_lds_dwordx4 v128, s[66:67]
	s_add_i32 m0, s33, 0x2000
	s_nop 0
	global_load_lds_dwordx4 v130, s[66:67]
	s_waitcnt vmcnt(6)
	s_barrier
; #define PG8_STAGE(bufoff, gbase, voff) do { _Pragma("unroll") for (int _i = 0; _i < 2; ++_i) \
;         __builtin_amdgcn_global_load_lds((const unsigned*)((const char*)(gbase) + (voff)[_i]), (LAS unsigned*)(lds + (bufoff) + ldsw + _i * 8192), 16, 0, 0); } while (0)
; #define PG8_LDA(dst, b, h) do { _Pragma("unroll") for (int m = 0; m < 4; ++m) _Pragma("unroll") for (int k = 0; k < 2; ++k) dst[m][k] = *(const LAS bf16x8*)(lds + PG8_SA(b, h) + aoff + m * 2048 + k * 1024); } while (0)
; #define PG8_LDB(dst, b, h) do { _Pragma("unroll") for (int n = 0; n < 2; ++n) _Pragma("unroll") for (int k = 0; k < 2; ++k) dst[n][k] = *(const LAS bf16x8*)(lds + PG8_SB(b, h) + boff + n * 2048 + k * 1024); } while (0)
; #define PG8_MMA(ai, bj, At, Bt) do { __builtin_amdgcn_s_setprio(1); _Pragma("unroll") for (int m = 0; m < 4; ++m) _Pragma("unroll") for (int n = 0; n < 2; ++n) _Pragma("unroll") for (int k = 0; k < 2; ++k) \
;         acc[ai][bj][m][n] = __builtin_amdgcn_mfma_f32_16x16x32_bf16(Bt[n][k], At[m][k], acc[ai][bj][m][n], 0, 0, 0); __builtin_amdgcn_s_setprio(0); } while (0)
; #define PG8_WAIT_V(n) asm volatile("s_waitcnt vmcnt(" #n ")" ::: "memory")
; #define PG8_WAIT_L(n) asm volatile("s_waitcnt lgkmcnt(" #n ")" ::: "memory")
; #define PG8_BAR __builtin_amdgcn_s_barrier()
; #define PG8_SCHED __builtin_amdgcn_sched_barrier(0)
; template <class Epi, class S_t>
; __device__ __forceinline__ void gemm_phase(LAS unsigned char* lds, int lda, int ldb, const S_t& S, const Epi& E) {
;     ...
;             PG8_WAIT_V(6); PG8_BAR; PG8_MMA(1, 1, At, B1); PG8_BAR;
;             PG8_LDB(B0, 1, 0); PG8_SCHED; PG8_LDA(At, 1, 0); PG8_STAGE(PG8_SA(0, 1), a2 + hstepA, voffA);
;             PG8_WAIT_L(8); PG8_BAR; PG8_WAIT_L(0); PG8_MMA(0, 0, At, B0); PG8_BAR; PG8_SCHED;
;             PG8_LDB(B1, 1, 1); PG8_STAGE(PG8_SB(1, 0), b3, voffB);
;             PG8_BAR; PG8_WAIT_L(0); PG8_MMA(0, 1, At, B1); PG8_BAR;
;             PG8_LDA(At, 1, 1); PG8_STAGE(PG8_SA(1, 0), a3, voffA);
;             PG8_BAR; PG8_WAIT_L(0); PG8_MMA(1, 0, At, B0); PG8_BAR; PG8_SCHED;
	s_setprio 1
	v_mfma_f32_16x16x32_bf16 v[44:47], v[222:225], v[186:189], v[44:47]
	v_mfma_f32_16x16x32_bf16 v[12:15], v[230:233], v[186:189], v[12:15]
	v_mfma_f32_16x16x32_bf16 v[40:43], v[222:225], v[194:197], v[40:43]
	v_mfma_f32_16x16x32_bf16 v[8:11], v[230:233], v[194:197], v[8:11]
	v_mfma_f32_16x16x32_bf16 v[36:39], v[222:225], v[202:205], v[36:39]
	v_mfma_f32_16x16x32_bf16 v[4:7], v[230:233], v[202:205], v[4:7]
	v_mfma_f32_16x16x32_bf16 v[32:35], v[222:225], v[214:217], v[32:35]
	v_mfma_f32_16x16x32_bf16 v[0:3], v[230:233], v[214:217], v[0:3]
	v_mfma_f32_16x16x32_bf16 v[44:47], v[226:229], v[190:193], v[44:47]
	v_mfma_f32_16x16x32_bf16 v[12:15], v[234:237], v[190:193], v[12:15]
	v_mfma_f32_16x16x32_bf16 v[40:43], v[226:229], v[198:201], v[40:43]
	v_mfma_f32_16x16x32_bf16 v[8:11], v[234:237], v[198:201], v[8:11]
	v_mfma_f32_16x16x32_bf16 v[36:39], v[226:229], v[206:209], v[36:39]
	v_mfma_f32_16x16x32_bf16 v[4:7], v[234:237], v[206:209], v[4:7]
	v_mfma_f32_16x16x32_bf16 v[32:35], v[226:229], v[218:221], v[32:35]
	v_mfma_f32_16x16x32_bf16 v[0:3], v[234:237], v[218:221], v[0:3]
	s_setprio 0
	s_add_i32 s33, 0, 0x18000
	v_add_u32_e32 v164, s33, v171
	s_barrier
	ds_read_b128 v[152:155], v164
	ds_read_b128 v[156:159], v164 offset:1024
	ds_read_b128 v[160:163], v164 offset:2048
	ds_read_b128 v[164:167], v164 offset:3072
	s_add_u32 s20, s20, 0x80000
	s_addc_u32 s21, s21, 0
	s_mov_b32 m0, s55
	ds_read_b128 v[186:189], v178 offset:32768
	ds_read_b128 v[190:193], v178 offset:33792
	ds_read_b128 v[194:197], v178 offset:34816
	ds_read_b128 v[198:201], v178 offset:35840
	ds_read_b128 v[202:205], v178 offset:36864
	ds_read_b128 v[206:209], v178 offset:37888
	ds_read_b128 v[214:217], v178 offset:38912
	ds_read_b128 v[218:221], v178 offset:39936
	global_load_lds_dwordx4 v128, s[20:21]
	s_mov_b32 m0, s56
	s_nop 0
	global_load_lds_dwordx4 v130, s[20:21]
	s_waitcnt lgkmcnt(8)
	s_barrier
	s_waitcnt lgkmcnt(0)
	s_setprio 1
	v_mfma_f32_16x16x32_bf16 v[124:127], v[152:155], v[186:189], v[124:127]
	v_mfma_f32_16x16x32_bf16 v[92:95], v[160:163], v[186:189], v[92:95]
	v_mfma_f32_16x16x32_bf16 v[120:123], v[152:155], v[194:197], v[120:123]
	v_mfma_f32_16x16x32_bf16 v[88:91], v[160:163], v[194:197], v[88:91]
	v_mfma_f32_16x16x32_bf16 v[116:119], v[152:155], v[202:205], v[116:119]
	v_mfma_f32_16x16x32_bf16 v[84:87], v[160:163], v[202:205], v[84:87]
	v_mfma_f32_16x16x32_bf16 v[112:115], v[152:155], v[214:217], v[112:115]
	v_mfma_f32_16x16x32_bf16 v[80:83], v[160:163], v[214:217], v[80:83]
	v_mfma_f32_16x16x32_bf16 v[124:127], v[156:159], v[190:193], v[124:127]
	v_mfma_f32_16x16x32_bf16 v[92:95], v[164:167], v[190:193], v[92:95]
	v_mfma_f32_16x16x32_bf16 v[120:123], v[156:159], v[198:201], v[120:123]
	v_mfma_f32_16x16x32_bf16 v[88:91], v[164:167], v[198:201], v[88:91]
	v_mfma_f32_16x16x32_bf16 v[116:119], v[156:159], v[206:209], v[116:119]
	v_mfma_f32_16x16x32_bf16 v[84:87], v[164:167], v[206:209], v[84:87]
	v_mfma_f32_16x16x32_bf16 v[112:115], v[156:159], v[218:221], v[112:115]
	v_mfma_f32_16x16x32_bf16 v[80:83], v[164:167], v[218:221], v[80:83]
	s_setprio 0
	s_barrier
	s_add_i32 s20, 0, 0x1c000
	s_add_i32 s21, s33, s43
	v_add_u32_e32 v170, s20, v171
	s_mov_b32 m0, s21
	ds_read_b128 v[222:225], v170
	ds_read_b128 v[226:229], v170 offset:1024
	ds_read_b128 v[230:233], v170 offset:2048
	ds_read_b128 v[234:237], v170 offset:3072
	global_load_lds_dwordx4 v128, s[98:99]
	s_add_i32 m0, s21, 0x2000
	s_nop 0
	global_load_lds_dwordx4 v130, s[98:99]
	s_barrier
	s_waitcnt lgkmcnt(0)
	s_setprio 1
	v_mfma_f32_16x16x32_bf16 v[60:63], v[222:225], v[186:189], v[60:63]
	v_mfma_f32_16x16x32_bf16 v[28:31], v[230:233], v[186:189], v[28:31]
	v_mfma_f32_16x16x32_bf16 v[56:59], v[222:225], v[194:197], v[56:59]
	v_mfma_f32_16x16x32_bf16 v[24:27], v[230:233], v[194:197], v[24:27]
	v_mfma_f32_16x16x32_bf16 v[52:55], v[222:225], v[202:205], v[52:55]
	v_mfma_f32_16x16x32_bf16 v[20:23], v[230:233], v[202:205], v[20:23]
	v_mfma_f32_16x16x32_bf16 v[48:51], v[222:225], v[214:217], v[48:51]
	v_mfma_f32_16x16x32_bf16 v[16:19], v[230:233], v[214:217], v[16:19]
	v_mfma_f32_16x16x32_bf16 v[60:63], v[226:229], v[190:193], v[60:63]
	v_mfma_f32_16x16x32_bf16 v[28:31], v[234:237], v[190:193], v[28:31]
	v_mfma_f32_16x16x32_bf16 v[56:59], v[226:229], v[198:201], v[56:59]
	v_mfma_f32_16x16x32_bf16 v[24:27], v[234:237], v[198:201], v[24:27]
	v_mfma_f32_16x16x32_bf16 v[52:55], v[226:229], v[206:209], v[52:55]
	v_mfma_f32_16x16x32_bf16 v[20:23], v[234:237], v[206:209], v[20:23]
	v_mfma_f32_16x16x32_bf16 v[48:51], v[226:229], v[218:221], v[48:51]
	v_mfma_f32_16x16x32_bf16 v[16:19], v[234:237], v[218:221], v[16:19]
	s_setprio 0
	s_mov_b32 m0, s58
	s_barrier
; #define PG8_STAGE(bufoff, gbase, voff) do { _Pragma("unroll") for (int _i = 0; _i < 2; ++_i) \
;         __builtin_amdgcn_global_load_lds((const unsigned*)((const char*)(gbase) + (voff)[_i]), (LAS unsigned*)(lds + (bufoff) + ldsw + _i * 8192), 16, 0, 0); } while (0)
; #define PG8_LDA(dst, b, h) do { _Pragma("unroll") for (int m = 0; m < 4; ++m) _Pragma("unroll") for (int k = 0; k < 2; ++k) dst[m][k] = *(const LAS bf16x8*)(lds + PG8_SA(b, h) + aoff + m * 2048 + k * 1024); } while (0)
; #define PG8_MMA(ai, bj, At, Bt) do { __builtin_amdgcn_s_setprio(1); _Pragma("unroll") for (int m = 0; m < 4; ++m) _Pragma("unroll") for (int n = 0; n < 2; ++n) _Pragma("unroll") for (int k = 0; k < 2; ++k) \
;         acc[ai][bj][m][n] = __builtin_amdgcn_mfma_f32_16x16x32_bf16(Bt[n][k], At[m][k], acc[ai][bj][m][n], 0, 0, 0); __builtin_amdgcn_s_setprio(0); } while (0)
; #define PG8_WAIT_V(n) asm volatile("s_waitcnt vmcnt(" #n ")" ::: "memory")
; #define PG8_WAIT_L(n) asm volatile("s_waitcnt lgkmcnt(" #n ")" ::: "memory")
; #define PG8_BAR __builtin_amdgcn_s_barrier()
; #define PG8_SCHED __builtin_amdgcn_sched_barrier(0)
; template <class Epi, class S_t>
; __device__ __forceinline__ void gemm_phase(LAS unsigned char* lds, int lda, int ldb, const S_t& S, const Epi& E) {
;     ...
;             PG8_BAR; PG8_WAIT_L(0); PG8_MMA(0, 1, At, B1); PG8_BAR;
;             PG8_LDA(At, 1, 1); PG8_STAGE(PG8_SA(1, 0), a3, voffA);
;             PG8_BAR; PG8_WAIT_L(0); PG8_MMA(1, 0, At, B0); PG8_BAR; PG8_SCHED;
;             PG8_STAGE(PG8_SB(1, 1), b3 + hstepB, voffB);
;             PG8_WAIT_V(6); PG8_BAR; PG8_MMA(1, 1, At, B1); PG8_BAR;
;         }
;         E(acc, cur, wr, wc, fr, fq);
;         if (!has_next) break;
	ds_read_b128 v[186:189], v178 offset:49152
	ds_read_b128 v[190:193], v178 offset:50176
	ds_read_b128 v[194:197], v178 offset:51200
	ds_read_b128 v[198:201], v178 offset:52224
	ds_read_b128 v[202:205], v178 offset:53248
	ds_read_b128 v[206:209], v178 offset:54272
	ds_read_b128 v[214:217], v178 offset:55296
	ds_read_b128 v[218:221], v178 offset:56320
	global_load_lds_dwordx4 v128, s[100:101]
	s_mov_b32 m0, s59
	s_nop 0
	global_load_lds_dwordx4 v130, s[100:101]
	s_barrier
	s_waitcnt lgkmcnt(0)
	s_setprio 1
	v_mfma_f32_16x16x32_bf16 v[108:111], v[152:155], v[186:189], v[108:111]
	v_mfma_f32_16x16x32_bf16 v[76:79], v[160:163], v[186:189], v[76:79]
	v_mfma_f32_16x16x32_bf16 v[104:107], v[152:155], v[194:197], v[104:107]
	v_mfma_f32_16x16x32_bf16 v[72:75], v[160:163], v[194:197], v[72:75]
	v_mfma_f32_16x16x32_bf16 v[100:103], v[152:155], v[202:205], v[100:103]
	v_mfma_f32_16x16x32_bf16 v[68:71], v[160:163], v[202:205], v[68:71]
	v_mfma_f32_16x16x32_bf16 v[96:99], v[152:155], v[214:217], v[96:99]
	v_mfma_f32_16x16x32_bf16 v[64:67], v[160:163], v[214:217], v[64:67]
	v_mfma_f32_16x16x32_bf16 v[108:111], v[156:159], v[190:193], v[108:111]
	v_mfma_f32_16x16x32_bf16 v[76:79], v[164:167], v[190:193], v[76:79]
	v_mfma_f32_16x16x32_bf16 v[104:107], v[156:159], v[198:201], v[104:107]
	v_mfma_f32_16x16x32_bf16 v[72:75], v[164:167], v[198:201], v[72:75]
	v_mfma_f32_16x16x32_bf16 v[100:103], v[156:159], v[206:209], v[100:103]
	v_mfma_f32_16x16x32_bf16 v[68:71], v[164:167], v[206:209], v[68:71]
	v_mfma_f32_16x16x32_bf16 v[96:99], v[156:159], v[218:221], v[96:99]
	v_mfma_f32_16x16x32_bf16 v[64:67], v[164:167], v[218:221], v[64:67]
	s_setprio 0
	s_barrier
	s_add_u32 s18, s18, 0x80080
	s_addc_u32 s19, s19, 0
	s_add_i32 s20, s20, s43
	s_mov_b32 m0, s20
	s_nop 0
	global_load_lds_dwordx4 v128, s[18:19]
	s_add_i32 m0, s20, 0x2000
	s_nop 0
	global_load_lds_dwordx4 v130, s[18:19]
	s_waitcnt vmcnt(6)
	s_barrier
	s_setprio 1
	v_mfma_f32_16x16x32_bf16 v[44:47], v[222:225], v[186:189], v[44:47]
	v_mfma_f32_16x16x32_bf16 v[12:15], v[230:233], v[186:189], v[12:15]
	v_mfma_f32_16x16x32_bf16 v[40:43], v[222:225], v[194:197], v[40:43]
	v_mfma_f32_16x16x32_bf16 v[8:11], v[230:233], v[194:197], v[8:11]
	v_mfma_f32_16x16x32_bf16 v[36:39], v[222:225], v[202:205], v[36:39]
	v_mfma_f32_16x16x32_bf16 v[4:7], v[230:233], v[202:205], v[4:7]
	v_mfma_f32_16x16x32_bf16 v[32:35], v[222:225], v[214:217], v[32:35]
	v_mfma_f32_16x16x32_bf16 v[0:3], v[230:233], v[214:217], v[0:3]
	v_mfma_f32_16x16x32_bf16 v[44:47], v[226:229], v[190:193], v[44:47]
	v_mfma_f32_16x16x32_bf16 v[12:15], v[234:237], v[190:193], v[12:15]
	v_mfma_f32_16x16x32_bf16 v[40:43], v[226:229], v[198:201], v[40:43]
	v_mfma_f32_16x16x32_bf16 v[8:11], v[234:237], v[198:201], v[8:11]
	v_mfma_f32_16x16x32_bf16 v[36:39], v[226:229], v[206:209], v[36:39]
	v_mfma_f32_16x16x32_bf16 v[4:7], v[234:237], v[206:209], v[4:7]
	v_mfma_f32_16x16x32_bf16 v[32:35], v[226:229], v[218:221], v[32:35]
	v_mfma_f32_16x16x32_bf16 v[0:3], v[234:237], v[218:221], v[0:3]
	s_setprio 0
	s_add_i32 s9, s9, 2
	s_add_u32 s16, s16, 0x100
	s_addc_u32 s17, s17, 0
	s_add_u32 s0, s0, 0x100
	s_addc_u32 s1, s1, 0
	s_cmp_gt_u32 s9, 29
	s_cbranch_scc0 .Lrot_133
	s_barrier
	s_ashr_i32 s9, s64, 3
	s_cmp_lt_i32 s9, 4
	s_cbranch_scc1 .LBB0_138
	v_readlane_b32 s68, v254, 17
	v_readlane_b32 s76, v254, 25
	v_readlane_b32 s77, v254, 26
	s_cmp_gt_i32 s9, 4
	s_mov_b64 s[18:19], 0
	s_mov_b64 s[16:17], s[76:77]
	s_mov_b64 s[0:1], 0
	v_readlane_b32 s69, v254, 18
	v_readlane_b32 s70, v254, 19
	v_readlane_b32 s71, v254, 20
	v_readlane_b32 s72, v254, 21
	v_readlane_b32 s73, v254, 22
	v_readlane_b32 s74, v254, 23
	v_readlane_b32 s75, v254, 24
	v_readlane_b32 s78, v254, 27
	v_readlane_b32 s79, v254, 28
	v_readlane_b32 s80, v254, 29
	v_readlane_b32 s81, v254, 30
	v_readlane_b32 s82, v254, 31
	v_readlane_b32 s83, v254, 32
	s_cbranch_scc0 .LBB0_139
	s_cmp_eq_u32 s9, 5
	s_mov_b64 s[0:1], -1
	s_cbranch_scc0 .LBB0_139
	v_readlane_b32 s68, v254, 17
	v_readlane_b32 s78, v254, 27
	v_readlane_b32 s79, v254, 28
	s_mov_b64 s[0:1], 0
	v_readlane_b32 s69, v254, 18
	v_readlane_b32 s70, v254, 19
	v_readlane_b32 s71, v254, 20
	v_readlane_b32 s72, v254, 21
	v_readlane_b32 s73, v254, 22
	v_readlane_b32 s74, v254, 23
	v_readlane_b32 s75, v254, 24
	v_readlane_b32 s76, v254, 25
	v_readlane_b32 s77, v254, 26
	v_readlane_b32 s80, v254, 29
	v_readlane_b32 s81, v254, 30
	v_readlane_b32 s82, v254, 31
	v_readlane_b32 s83, v254, 32
	s_mov_b64 s[16:17], s[78:79]
	s_branch .LBB0_139

; template <class Epi, class S_t>
; __device__ __forceinline__ void gemm_phase(LAS unsigned char* lds, int lda, int ldb, const S_t& S, const Epi& E) {
;     ...
; #pragma unroll
;         for (int a = 0; a < 2; ++a)
; #pragma unroll
;             for (int b = 0; b < 2; ++b)
; #pragma unroll
;                 for (int m = 0; m < 4; ++m)
; #pragma unroll
;                     for (int n = 0; n < 2; ++n) acc[a][b][m][n] = (f32x4){0.f, 0.f, 0.f, 0.f};
;         cur = nxt; cA = nA; cB = nB; ++ui;
.LBB0_235:
	s_add_u32 s54, s54, 0x80080
	s_addc_u32 s55, s55, 0
	s_add_u32 s0, s56, 0x100
	s_addc_u32 s1, s57, 0
	s_mov_b32 s7, -2
	v_mov_b64_e32 v[0:1], 0
	v_mov_b64_e32 v[2:3], 0
	v_mov_b64_e32 v[4:5], 0
	v_mov_b64_e32 v[6:7], 0
	v_mov_b64_e32 v[8:9], 0
	v_mov_b64_e32 v[10:11], 0
	v_mov_b64_e32 v[12:13], 0
	v_mov_b64_e32 v[14:15], 0
	v_mov_b64_e32 v[16:17], 0
	v_mov_b64_e32 v[18:19], 0
	v_mov_b64_e32 v[20:21], 0
	v_mov_b64_e32 v[22:23], 0
	v_mov_b64_e32 v[24:25], 0
	v_mov_b64_e32 v[26:27], 0
	v_mov_b64_e32 v[28:29], 0
	v_mov_b64_e32 v[30:31], 0
	v_mov_b64_e32 v[32:33], 0
	v_mov_b64_e32 v[34:35], 0
	v_mov_b64_e32 v[36:37], 0
	v_mov_b64_e32 v[38:39], 0
	v_mov_b64_e32 v[40:41], 0
	v_mov_b64_e32 v[42:43], 0
	v_mov_b64_e32 v[44:45], 0
	v_mov_b64_e32 v[46:47], 0
	v_mov_b64_e32 v[48:49], 0
	v_mov_b64_e32 v[50:51], 0
	v_mov_b64_e32 v[52:53], 0
	v_mov_b64_e32 v[54:55], 0
	v_mov_b64_e32 v[56:57], 0
	v_mov_b64_e32 v[58:59], 0
	v_mov_b64_e32 v[60:61], 0
	v_mov_b64_e32 v[62:63], 0
	v_mov_b64_e32 v[64:65], 0
	v_mov_b64_e32 v[66:67], 0
	v_mov_b64_e32 v[68:69], 0
	v_mov_b64_e32 v[70:71], 0
	v_mov_b64_e32 v[72:73], 0
	v_mov_b64_e32 v[74:75], 0
	v_mov_b64_e32 v[76:77], 0
	v_mov_b64_e32 v[78:79], 0
	v_mov_b64_e32 v[80:81], 0
	v_mov_b64_e32 v[82:83], 0
	v_mov_b64_e32 v[84:85], 0
	v_mov_b64_e32 v[86:87], 0
	v_mov_b64_e32 v[88:89], 0
	v_mov_b64_e32 v[90:91], 0
	v_mov_b64_e32 v[92:93], 0
	v_mov_b64_e32 v[94:95], 0
	v_mov_b64_e32 v[96:97], 0
	v_mov_b64_e32 v[98:99], 0
	v_mov_b64_e32 v[100:101], 0
	v_mov_b64_e32 v[102:103], 0
	v_mov_b64_e32 v[104:105], 0
	v_mov_b64_e32 v[106:107], 0
	v_mov_b64_e32 v[108:109], 0
	v_mov_b64_e32 v[110:111], 0
	v_mov_b64_e32 v[112:113], 0
	v_mov_b64_e32 v[114:115], 0
	v_mov_b64_e32 v[116:117], 0
	v_mov_b64_e32 v[118:119], 0
	v_mov_b64_e32 v[120:121], 0
	v_mov_b64_e32 v[122:123], 0
	v_mov_b64_e32 v[124:125], 0
	v_mov_b64_e32 v[126:127], 0
	s_branch .LBB0_236

; #define PG8_STAGE(bufoff, gbase, voff) do { _Pragma("unroll") for (int _i = 0; _i < 2; ++_i) \
;         __builtin_amdgcn_global_load_lds((const unsigned*)((const char*)(gbase) + (voff)[_i]), (LAS unsigned*)(lds + (bufoff) + ldsw + _i * 8192), 16, 0, 0); } while (0)
; #define PG8_LDA(dst, b, h) do { _Pragma("unroll") for (int m = 0; m < 4; ++m) _Pragma("unroll") for (int k = 0; k < 2; ++k) dst[m][k] = *(const LAS bf16x8*)(lds + PG8_SA(b, h) + aoff + m * 2048 + k * 1024); } while (0)
; #define PG8_LDB(dst, b, h) do { _Pragma("unroll") for (int n = 0; n < 2; ++n) _Pragma("unroll") for (int k = 0; k < 2; ++k) dst[n][k] = *(const LAS bf16x8*)(lds + PG8_SB(b, h) + boff + n * 2048 + k * 1024); } while (0)
; #define PG8_MMA(ai, bj, At, Bt) do { __builtin_amdgcn_s_setprio(1); _Pragma("unroll") for (int m = 0; m < 4; ++m) _Pragma("unroll") for (int n = 0; n < 2; ++n) _Pragma("unroll") for (int k = 0; k < 2; ++k) \
;         acc[ai][bj][m][n] = __builtin_amdgcn_mfma_f32_16x16x32_bf16(Bt[n][k], At[m][k], acc[ai][bj][m][n], 0, 0, 0); __builtin_amdgcn_s_setprio(0); } while (0)
; #define PG8_WAIT_V(n) asm volatile("s_waitcnt vmcnt(" #n ")" ::: "memory")
; #define PG8_WAIT_L(n) asm volatile("s_waitcnt lgkmcnt(" #n ")" ::: "memory")
; #define PG8_BAR __builtin_amdgcn_s_barrier()
; #define PG8_SCHED __builtin_amdgcn_sched_barrier(0)
; template <class Epi, class S_t>
; __device__ __forceinline__ void gemm_phase(LAS unsigned char* lds, int lda, int ldb, const S_t& S, const Epi& E) {
;     ...
;             PG8_LDB(B0, 0, 0); PG8_SCHED; PG8_LDA(At, 0, 0); PG8_STAGE(PG8_SA(1, 1), a1 + hstepA, voffA);
;             PG8_WAIT_L(8); PG8_BAR; PG8_WAIT_L(0); PG8_MMA(0, 0, At, B0); PG8_BAR; PG8_SCHED;
;             PG8_LDB(B1, 0, 1); PG8_STAGE(PG8_SB(0, 0), b2, voffB);
;             PG8_BAR; PG8_WAIT_L(0); PG8_MMA(0, 1, At, B1); PG8_BAR;
;             PG8_LDA(At, 0, 1); PG8_STAGE(PG8_SA(0, 0), a2, voffA);
;             PG8_BAR; PG8_WAIT_L(0); PG8_MMA(1, 0, At, B0); PG8_BAR; PG8_SCHED;
;             PG8_STAGE(PG8_SB(0, 1), b2 + hstepB, voffB);
;             PG8_WAIT_V(6); PG8_BAR; PG8_MMA(1, 1, At, B1); PG8_BAR;
;             PG8_LDB(B0, 1, 0); PG8_SCHED; PG8_LDA(At, 1, 0); PG8_STAGE(PG8_SA(0, 1), a2 + hstepA, voffA);
;             PG8_WAIT_L(8); PG8_BAR; PG8_WAIT_L(0); PG8_MMA(0, 0, At, B0); PG8_BAR; PG8_SCHED;
.LBB0_236:
	ds_read_b128 v[142:145], v149
	ds_read_b128 v[152:155], v149 offset:1024
	ds_read_b128 v[156:159], v149 offset:2048
	ds_read_b128 v[160:163], v149 offset:3072
	s_add_u32 s11, s54, 0xfff80080
	s_addc_u32 s13, s55, -1
	s_cmp_eq_u32 s7, 28
	s_cselect_b32 s59, s15, s13
	s_cselect_b32 s58, s14, s11
	s_cselect_b32 s57, s19, s1
	s_cselect_b32 s56, s18, s0
	s_add_i32 m0, s21, 0xc000
	ds_read_b128 v[164:167], v150
	ds_read_b128 v[168:171], v150 offset:1024
	ds_read_b128 v[172:175], v150 offset:2048
	ds_read_b128 v[176:179], v150 offset:3072
	ds_read_b128 v[180:183], v150 offset:4096
	ds_read_b128 v[186:189], v150 offset:5120
	ds_read_b128 v[190:193], v150 offset:6144
	ds_read_b128 v[194:197], v150 offset:7168
	global_load_lds_dwordx4 v136, s[54:55]
	s_add_i32 m0, s21, 0xe000
	s_nop 0
	global_load_lds_dwordx4 v138, s[54:55]
	s_waitcnt lgkmcnt(8)
	s_barrier
	s_waitcnt lgkmcnt(0)
	s_setprio 1
	v_mfma_f32_16x16x32_bf16 v[124:127], v[142:145], v[164:167], v[124:127]
	v_mfma_f32_16x16x32_bf16 v[120:123], v[156:159], v[164:167], v[120:123]
	v_mfma_f32_16x16x32_bf16 v[108:111], v[142:145], v[172:175], v[108:111]
	v_mfma_f32_16x16x32_bf16 v[104:107], v[156:159], v[172:175], v[104:107]
	v_mfma_f32_16x16x32_bf16 v[92:95], v[142:145], v[180:183], v[92:95]
	v_mfma_f32_16x16x32_bf16 v[88:91], v[156:159], v[180:183], v[88:91]
	v_mfma_f32_16x16x32_bf16 v[76:79], v[142:145], v[190:193], v[76:79]
	v_mfma_f32_16x16x32_bf16 v[72:75], v[156:159], v[190:193], v[72:75]
	v_mfma_f32_16x16x32_bf16 v[124:127], v[152:155], v[168:171], v[124:127]
	v_mfma_f32_16x16x32_bf16 v[120:123], v[160:163], v[168:171], v[120:123]
	v_mfma_f32_16x16x32_bf16 v[108:111], v[152:155], v[176:179], v[108:111]
	v_mfma_f32_16x16x32_bf16 v[104:107], v[160:163], v[176:179], v[104:107]
	v_mfma_f32_16x16x32_bf16 v[92:95], v[152:155], v[186:189], v[92:95]
	v_mfma_f32_16x16x32_bf16 v[88:91], v[160:163], v[186:189], v[88:91]
	v_mfma_f32_16x16x32_bf16 v[76:79], v[152:155], v[194:197], v[76:79]
	v_mfma_f32_16x16x32_bf16 v[72:75], v[160:163], v[194:197], v[72:75]
	s_setprio 0
	s_barrier
	s_add_i32 s11, s67, s20
	s_add_u32 s98, s56, s8
	s_addc_u32 s99, s57, s9
	s_mov_b32 m0, s11
	ds_read_b128 v[198:201], v151
	ds_read_b128 v[202:205], v151 offset:1024
	ds_read_b128 v[206:209], v151 offset:2048
	ds_read_b128 v[220:223], v151 offset:3072
	global_load_lds_dwordx4 v130, s[56:57]
	s_add_i32 m0, s11, 0x2000
	s_nop 0
	global_load_lds_dwordx4 v134, s[56:57]
	s_barrier
	s_waitcnt lgkmcnt(0)
	s_setprio 1
	v_mfma_f32_16x16x32_bf16 v[116:119], v[198:201], v[164:167], v[116:119]
	v_mfma_f32_16x16x32_bf16 v[112:115], v[206:209], v[164:167], v[112:115]
	v_mfma_f32_16x16x32_bf16 v[100:103], v[198:201], v[172:175], v[100:103]
	v_mfma_f32_16x16x32_bf16 v[96:99], v[206:209], v[172:175], v[96:99]
	v_mfma_f32_16x16x32_bf16 v[84:87], v[198:201], v[180:183], v[84:87]
	v_mfma_f32_16x16x32_bf16 v[80:83], v[206:209], v[180:183], v[80:83]
	v_mfma_f32_16x16x32_bf16 v[68:71], v[198:201], v[190:193], v[68:71]
	v_mfma_f32_16x16x32_bf16 v[64:67], v[206:209], v[190:193], v[64:67]
	v_mfma_f32_16x16x32_bf16 v[116:119], v[202:205], v[168:171], v[116:119]
	v_mfma_f32_16x16x32_bf16 v[112:115], v[220:223], v[168:171], v[112:115]
	v_mfma_f32_16x16x32_bf16 v[100:103], v[202:205], v[176:179], v[100:103]
	v_mfma_f32_16x16x32_bf16 v[96:99], v[220:223], v[176:179], v[96:99]
	v_mfma_f32_16x16x32_bf16 v[84:87], v[202:205], v[186:189], v[84:87]
	v_mfma_f32_16x16x32_bf16 v[80:83], v[220:223], v[186:189], v[80:83]
	v_mfma_f32_16x16x32_bf16 v[68:71], v[202:205], v[194:197], v[68:71]
	v_mfma_f32_16x16x32_bf16 v[64:67], v[220:223], v[194:197], v[64:67]
	s_setprio 0
	s_mov_b32 m0, s21
	s_add_u32 s100, s58, s8
	s_addc_u32 s101, s59, s9
	s_barrier
	ds_read_b128 v[164:167], v150 offset:16384
	ds_read_b128 v[168:171], v150 offset:17408
	ds_read_b128 v[172:175], v150 offset:18432
	ds_read_b128 v[176:179], v150 offset:19456
	ds_read_b128 v[180:183], v150 offset:20480
	ds_read_b128 v[186:189], v150 offset:21504
	ds_read_b128 v[190:193], v150 offset:22528
	ds_read_b128 v[194:197], v150 offset:23552
	global_load_lds_dwordx4 v128, s[58:59]
	s_mov_b32 m0, s35
	s_nop 0
	global_load_lds_dwordx4 v132, s[58:59]
	s_barrier
	s_waitcnt lgkmcnt(0)
	s_setprio 1
	v_mfma_f32_16x16x32_bf16 v[60:63], v[142:145], v[164:167], v[60:63]
	v_mfma_f32_16x16x32_bf16 v[56:59], v[156:159], v[164:167], v[56:59]
	v_mfma_f32_16x16x32_bf16 v[44:47], v[142:145], v[172:175], v[44:47]
	v_mfma_f32_16x16x32_bf16 v[40:43], v[156:159], v[172:175], v[40:43]
	v_mfma_f32_16x16x32_bf16 v[28:31], v[142:145], v[180:183], v[28:31]
	v_mfma_f32_16x16x32_bf16 v[24:27], v[156:159], v[180:183], v[24:27]
	v_mfma_f32_16x16x32_bf16 v[12:15], v[142:145], v[190:193], v[12:15]
	v_mfma_f32_16x16x32_bf16 v[8:11], v[156:159], v[190:193], v[8:11]
	v_mfma_f32_16x16x32_bf16 v[60:63], v[152:155], v[168:171], v[60:63]
	v_mfma_f32_16x16x32_bf16 v[56:59], v[160:163], v[168:171], v[56:59]
	v_mfma_f32_16x16x32_bf16 v[44:47], v[152:155], v[176:179], v[44:47]
	v_mfma_f32_16x16x32_bf16 v[40:43], v[160:163], v[176:179], v[40:43]
	v_mfma_f32_16x16x32_bf16 v[28:31], v[152:155], v[186:189], v[28:31]
	v_mfma_f32_16x16x32_bf16 v[24:27], v[160:163], v[186:189], v[24:27]
	v_mfma_f32_16x16x32_bf16 v[12:15], v[152:155], v[194:197], v[12:15]
	v_mfma_f32_16x16x32_bf16 v[8:11], v[160:163], v[194:197], v[8:11]
	s_setprio 0
	s_barrier
	s_add_u32 s42, s56, 0x80000
	s_addc_u32 s43, s57, 0
	s_add_i32 s11, s74, s20
	s_mov_b32 m0, s11
	s_nop 0
	global_load_lds_dwordx4 v130, s[42:43]
	s_add_i32 m0, s11, 0x2000
	s_nop 0
	global_load_lds_dwordx4 v134, s[42:43]
	s_waitcnt vmcnt(6)
	s_barrier
; #define PG8_STAGE(bufoff, gbase, voff) do { _Pragma("unroll") for (int _i = 0; _i < 2; ++_i) \
;         __builtin_amdgcn_global_load_lds((const unsigned*)((const char*)(gbase) + (voff)[_i]), (LAS unsigned*)(lds + (bufoff) + ldsw + _i * 8192), 16, 0, 0); } while (0)
; #define PG8_LDA(dst, b, h) do { _Pragma("unroll") for (int m = 0; m < 4; ++m) _Pragma("unroll") for (int k = 0; k < 2; ++k) dst[m][k] = *(const LAS bf16x8*)(lds + PG8_SA(b, h) + aoff + m * 2048 + k * 1024); } while (0)
; #define PG8_LDB(dst, b, h) do { _Pragma("unroll") for (int n = 0; n < 2; ++n) _Pragma("unroll") for (int k = 0; k < 2; ++k) dst[n][k] = *(const LAS bf16x8*)(lds + PG8_SB(b, h) + boff + n * 2048 + k * 1024); } while (0)
; #define PG8_MMA(ai, bj, At, Bt) do { __builtin_amdgcn_s_setprio(1); _Pragma("unroll") for (int m = 0; m < 4; ++m) _Pragma("unroll") for (int n = 0; n < 2; ++n) _Pragma("unroll") for (int k = 0; k < 2; ++k) \
;         acc[ai][bj][m][n] = __builtin_amdgcn_mfma_f32_16x16x32_bf16(Bt[n][k], At[m][k], acc[ai][bj][m][n], 0, 0, 0); __builtin_amdgcn_s_setprio(0); } while (0)
; #define PG8_WAIT_L(n) asm volatile("s_waitcnt lgkmcnt(" #n ")" ::: "memory")
; #define PG8_BAR __builtin_amdgcn_s_barrier()
; #define PG8_SCHED __builtin_amdgcn_sched_barrier(0)
; template <class Epi, class S_t>
; __device__ __forceinline__ void gemm_phase(LAS unsigned char* lds, int lda, int ldb, const S_t& S, const Epi& E) {
;     ...
;             PG8_LDB(B0, 1, 0); PG8_SCHED; PG8_LDA(At, 1, 0); PG8_STAGE(PG8_SA(0, 1), a2 + hstepA, voffA);
;             PG8_WAIT_L(8); PG8_BAR; PG8_WAIT_L(0); PG8_MMA(0, 0, At, B0); PG8_BAR; PG8_SCHED;
;             PG8_LDB(B1, 1, 1); PG8_STAGE(PG8_SB(1, 0), b3, voffB);
;             PG8_BAR; PG8_WAIT_L(0); PG8_MMA(0, 1, At, B1); PG8_BAR;
;             PG8_LDA(At, 1, 1); PG8_STAGE(PG8_SA(1, 0), a3, voffA);
;             PG8_BAR; PG8_WAIT_L(0); PG8_MMA(1, 0, At, B0); PG8_BAR; PG8_SCHED;
	s_setprio 1
	v_mfma_f32_16x16x32_bf16 v[52:55], v[198:201], v[164:167], v[52:55]
	v_mfma_f32_16x16x32_bf16 v[48:51], v[206:209], v[164:167], v[48:51]
	v_mfma_f32_16x16x32_bf16 v[36:39], v[198:201], v[172:175], v[36:39]
	v_mfma_f32_16x16x32_bf16 v[32:35], v[206:209], v[172:175], v[32:35]
	v_mfma_f32_16x16x32_bf16 v[20:23], v[198:201], v[180:183], v[20:23]
	v_mfma_f32_16x16x32_bf16 v[16:19], v[206:209], v[180:183], v[16:19]
	v_mfma_f32_16x16x32_bf16 v[4:7], v[198:201], v[190:193], v[4:7]
	v_mfma_f32_16x16x32_bf16 v[0:3], v[206:209], v[190:193], v[0:3]
	v_mfma_f32_16x16x32_bf16 v[52:55], v[202:205], v[168:171], v[52:55]
	v_mfma_f32_16x16x32_bf16 v[48:51], v[220:223], v[168:171], v[48:51]
	v_mfma_f32_16x16x32_bf16 v[36:39], v[202:205], v[176:179], v[36:39]
	v_mfma_f32_16x16x32_bf16 v[32:35], v[220:223], v[176:179], v[32:35]
	v_mfma_f32_16x16x32_bf16 v[20:23], v[202:205], v[186:189], v[20:23]
	v_mfma_f32_16x16x32_bf16 v[16:19], v[220:223], v[186:189], v[16:19]
	v_mfma_f32_16x16x32_bf16 v[4:7], v[202:205], v[194:197], v[4:7]
	v_mfma_f32_16x16x32_bf16 v[0:3], v[220:223], v[194:197], v[0:3]
	s_setprio 0
	s_add_i32 s11, 0, 0x18000
	v_add_u32_e32 v160, s11, v147
	s_barrier
	ds_read_b128 v[142:145], v160
	ds_read_b128 v[152:155], v160 offset:1024
	ds_read_b128 v[156:159], v160 offset:2048
	ds_read_b128 v[160:163], v160 offset:3072
	s_add_u32 s42, s58, 0x80000
	s_addc_u32 s43, s59, 0
	s_mov_b32 m0, s52
	ds_read_b128 v[164:167], v150 offset:32768
	ds_read_b128 v[168:171], v150 offset:33792
	ds_read_b128 v[172:175], v150 offset:34816
	ds_read_b128 v[176:179], v150 offset:35840
	ds_read_b128 v[180:183], v150 offset:36864
	ds_read_b128 v[186:189], v150 offset:37888
	ds_read_b128 v[190:193], v150 offset:38912
	ds_read_b128 v[194:197], v150 offset:39936
	global_load_lds_dwordx4 v128, s[42:43]
	s_mov_b32 m0, s53
	s_nop 0
	global_load_lds_dwordx4 v132, s[42:43]
	s_waitcnt lgkmcnt(8)
	s_barrier
	s_waitcnt lgkmcnt(0)
	s_setprio 1
	v_mfma_f32_16x16x32_bf16 v[124:127], v[142:145], v[164:167], v[124:127]
	v_mfma_f32_16x16x32_bf16 v[120:123], v[156:159], v[164:167], v[120:123]
	v_mfma_f32_16x16x32_bf16 v[108:111], v[142:145], v[172:175], v[108:111]
	v_mfma_f32_16x16x32_bf16 v[104:107], v[156:159], v[172:175], v[104:107]
	v_mfma_f32_16x16x32_bf16 v[92:95], v[142:145], v[180:183], v[92:95]
	v_mfma_f32_16x16x32_bf16 v[88:91], v[156:159], v[180:183], v[88:91]
	v_mfma_f32_16x16x32_bf16 v[76:79], v[142:145], v[190:193], v[76:79]
	v_mfma_f32_16x16x32_bf16 v[72:75], v[156:159], v[190:193], v[72:75]
	v_mfma_f32_16x16x32_bf16 v[124:127], v[152:155], v[168:171], v[124:127]
	v_mfma_f32_16x16x32_bf16 v[120:123], v[160:163], v[168:171], v[120:123]
	v_mfma_f32_16x16x32_bf16 v[108:111], v[152:155], v[176:179], v[108:111]
	v_mfma_f32_16x16x32_bf16 v[104:107], v[160:163], v[176:179], v[104:107]
	v_mfma_f32_16x16x32_bf16 v[92:95], v[152:155], v[186:189], v[92:95]
	v_mfma_f32_16x16x32_bf16 v[88:91], v[160:163], v[186:189], v[88:91]
	v_mfma_f32_16x16x32_bf16 v[76:79], v[152:155], v[194:197], v[76:79]
	v_mfma_f32_16x16x32_bf16 v[72:75], v[160:163], v[194:197], v[72:75]
	s_setprio 0
	s_barrier
	s_add_i32 s13, 0, 0x1c000
	s_add_i32 s11, s11, s20
	v_add_u32_e32 v215, s13, v147
	s_mov_b32 m0, s11
	ds_read_b128 v[198:201], v215
	ds_read_b128 v[202:205], v215 offset:1024
	ds_read_b128 v[206:209], v215 offset:2048
	ds_read_b128 v[220:223], v215 offset:3072
	global_load_lds_dwordx4 v130, s[98:99]
	s_add_i32 m0, s11, 0x2000
	s_nop 0
	global_load_lds_dwordx4 v134, s[98:99]
	s_barrier
	s_waitcnt lgkmcnt(0)
	s_setprio 1
	v_mfma_f32_16x16x32_bf16 v[116:119], v[198:201], v[164:167], v[116:119]
	v_mfma_f32_16x16x32_bf16 v[112:115], v[206:209], v[164:167], v[112:115]
	v_mfma_f32_16x16x32_bf16 v[100:103], v[198:201], v[172:175], v[100:103]
	v_mfma_f32_16x16x32_bf16 v[96:99], v[206:209], v[172:175], v[96:99]
	v_mfma_f32_16x16x32_bf16 v[84:87], v[198:201], v[180:183], v[84:87]
	v_mfma_f32_16x16x32_bf16 v[80:83], v[206:209], v[180:183], v[80:83]
	v_mfma_f32_16x16x32_bf16 v[68:71], v[198:201], v[190:193], v[68:71]
	v_mfma_f32_16x16x32_bf16 v[64:67], v[206:209], v[190:193], v[64:67]
	v_mfma_f32_16x16x32_bf16 v[116:119], v[202:205], v[168:171], v[116:119]
	v_mfma_f32_16x16x32_bf16 v[112:115], v[220:223], v[168:171], v[112:115]
	v_mfma_f32_16x16x32_bf16 v[100:103], v[202:205], v[176:179], v[100:103]
	v_mfma_f32_16x16x32_bf16 v[96:99], v[220:223], v[176:179], v[96:99]
	v_mfma_f32_16x16x32_bf16 v[84:87], v[202:205], v[186:189], v[84:87]
	v_mfma_f32_16x16x32_bf16 v[80:83], v[220:223], v[186:189], v[80:83]
	v_mfma_f32_16x16x32_bf16 v[68:71], v[202:205], v[194:197], v[68:71]
	v_mfma_f32_16x16x32_bf16 v[64:67], v[220:223], v[194:197], v[64:67]
	s_setprio 0
	s_mov_b32 m0, s61
	s_barrier
; __device__ __forceinline__ float sigmoidf_(float x) { return __builtin_amdgcn_rcpf(1.0f + __expf(-x)); }
; #define PG8_STAGE(bufoff, gbase, voff) do { _Pragma("unroll") for (int _i = 0; _i < 2; ++_i) \
;         __builtin_amdgcn_global_load_lds((const unsigned*)((const char*)(gbase) + (voff)[_i]), (LAS unsigned*)(lds + (bufoff) + ldsw + _i * 8192), 16, 0, 0); } while (0)
; #define PG8_MMA(ai, bj, At, Bt) do { __builtin_amdgcn_s_setprio(1); _Pragma("unroll") for (int m = 0; m < 4; ++m) _Pragma("unroll") for (int n = 0; n < 2; ++n) _Pragma("unroll") for (int k = 0; k < 2; ++k) \
;         acc[ai][bj][m][n] = __builtin_amdgcn_mfma_f32_16x16x32_bf16(Bt[n][k], At[m][k], acc[ai][bj][m][n], 0, 0, 0); __builtin_amdgcn_s_setprio(0); } while (0)
; #define PG8_WAIT_V(n) asm volatile("s_waitcnt vmcnt(" #n ")" ::: "memory")
; #define PG8_WAIT_L(n) asm volatile("s_waitcnt lgkmcnt(" #n ")" ::: "memory")
; #define PG8_BAR __builtin_amdgcn_s_barrier()
; #define PG8_SCHED __builtin_amdgcn_sched_barrier(0)
; template <class Epi, class S_t>
; __device__ __forceinline__ void gemm_phase(LAS unsigned char* lds, int lda, int ldb, const S_t& S, const Epi& E) {
;     ...
;             PG8_BAR; PG8_WAIT_L(0); PG8_MMA(1, 0, At, B0); PG8_BAR; PG8_SCHED;
;             PG8_STAGE(PG8_SB(1, 1), b3 + hstepB, voffB);
;             PG8_WAIT_V(6); PG8_BAR; PG8_MMA(1, 1, At, B1); PG8_BAR;
;         }
;         E(acc, cur, wr, wc, fr, fq);
;     __device__ __forceinline__ void operator()(const f32x4 (&acc)[2][2][4][2], const Unit& u, int wr, int wc, int fr, int fq) const {
;     ...
;                     if (sg) {
; #pragma unroll
;                         for (int j = 0; j < 4; ++j) { v0[j] = sigmoidf_(v0[j]); v1[j] = sigmoidf_(v1[j]); } }
	ds_read_b128 v[164:167], v150 offset:49152
	ds_read_b128 v[168:171], v150 offset:50176
	ds_read_b128 v[172:175], v150 offset:51200
	ds_read_b128 v[176:179], v150 offset:52224
	ds_read_b128 v[180:183], v150 offset:53248
	ds_read_b128 v[186:189], v150 offset:54272
	ds_read_b128 v[190:193], v150 offset:55296
	ds_read_b128 v[194:197], v150 offset:56320
	global_load_lds_dwordx4 v128, s[100:101]
	s_mov_b32 m0, s62
	s_nop 0
	global_load_lds_dwordx4 v132, s[100:101]
	s_barrier
	s_waitcnt lgkmcnt(0)
	s_setprio 1
	v_mfma_f32_16x16x32_bf16 v[60:63], v[142:145], v[164:167], v[60:63]
	v_mfma_f32_16x16x32_bf16 v[56:59], v[156:159], v[164:167], v[56:59]
	v_mfma_f32_16x16x32_bf16 v[44:47], v[142:145], v[172:175], v[44:47]
	v_mfma_f32_16x16x32_bf16 v[40:43], v[156:159], v[172:175], v[40:43]
	v_mfma_f32_16x16x32_bf16 v[28:31], v[142:145], v[180:183], v[28:31]
	v_mfma_f32_16x16x32_bf16 v[24:27], v[156:159], v[180:183], v[24:27]
	v_mfma_f32_16x16x32_bf16 v[12:15], v[142:145], v[190:193], v[12:15]
	v_mfma_f32_16x16x32_bf16 v[8:11], v[156:159], v[190:193], v[8:11]
	v_mfma_f32_16x16x32_bf16 v[60:63], v[152:155], v[168:171], v[60:63]
	v_mfma_f32_16x16x32_bf16 v[56:59], v[160:163], v[168:171], v[56:59]
	v_mfma_f32_16x16x32_bf16 v[44:47], v[152:155], v[176:179], v[44:47]
	v_mfma_f32_16x16x32_bf16 v[40:43], v[160:163], v[176:179], v[40:43]
	v_mfma_f32_16x16x32_bf16 v[28:31], v[152:155], v[186:189], v[28:31]
	v_mfma_f32_16x16x32_bf16 v[24:27], v[160:163], v[186:189], v[24:27]
	v_mfma_f32_16x16x32_bf16 v[12:15], v[152:155], v[194:197], v[12:15]
	v_mfma_f32_16x16x32_bf16 v[8:11], v[160:163], v[194:197], v[8:11]
	s_setprio 0
	s_barrier
	s_add_u32 s42, s56, 0x80080
	s_addc_u32 s43, s57, 0
	s_add_i32 s11, s13, s20
	s_mov_b32 m0, s11
	s_nop 0
	global_load_lds_dwordx4 v130, s[42:43]
	s_add_i32 m0, s11, 0x2000
	s_nop 0
	global_load_lds_dwordx4 v134, s[42:43]
	s_waitcnt vmcnt(6)
	s_barrier
	s_setprio 1
	v_mfma_f32_16x16x32_bf16 v[52:55], v[198:201], v[164:167], v[52:55]
	v_mfma_f32_16x16x32_bf16 v[48:51], v[206:209], v[164:167], v[48:51]
	v_mfma_f32_16x16x32_bf16 v[36:39], v[198:201], v[172:175], v[36:39]
	v_mfma_f32_16x16x32_bf16 v[32:35], v[206:209], v[172:175], v[32:35]
	v_mfma_f32_16x16x32_bf16 v[20:23], v[198:201], v[180:183], v[20:23]
	v_mfma_f32_16x16x32_bf16 v[16:19], v[206:209], v[180:183], v[16:19]
	v_mfma_f32_16x16x32_bf16 v[4:7], v[198:201], v[190:193], v[4:7]
	v_mfma_f32_16x16x32_bf16 v[0:3], v[206:209], v[190:193], v[0:3]
	v_mfma_f32_16x16x32_bf16 v[52:55], v[202:205], v[168:171], v[52:55]
	v_mfma_f32_16x16x32_bf16 v[48:51], v[220:223], v[168:171], v[48:51]
	v_mfma_f32_16x16x32_bf16 v[36:39], v[202:205], v[176:179], v[36:39]
	v_mfma_f32_16x16x32_bf16 v[32:35], v[220:223], v[176:179], v[32:35]
	v_mfma_f32_16x16x32_bf16 v[20:23], v[202:205], v[186:189], v[20:23]
	v_mfma_f32_16x16x32_bf16 v[16:19], v[220:223], v[186:189], v[16:19]
	v_mfma_f32_16x16x32_bf16 v[4:7], v[202:205], v[194:197], v[4:7]
	v_mfma_f32_16x16x32_bf16 v[0:3], v[220:223], v[194:197], v[0:3]
	s_setprio 0
	s_add_i32 s7, s7, 2
	s_add_u32 s54, s54, 0x100
	s_addc_u32 s55, s55, 0
	s_add_u32 s0, s0, 0x100
	s_addc_u32 s1, s1, 0
	s_cmp_gt_u32 s7, 29
	s_cbranch_scc0 .Lrot_236
	s_barrier
	s_cmp_gt_i32 s78, 11
	s_cselect_b64 s[0:1], -1, 0
	s_cmp_lt_i32 s78, 12
	s_cbranch_scc1 .LBB0_239
	v_mul_f32_e32 v124, 0xbfb8aa3b, v124
	v_mul_f32_e32 v120, 0xbfb8aa3b, v120
	v_mul_f32_e32 v125, 0xbfb8aa3b, v125
	v_mul_f32_e32 v121, 0xbfb8aa3b, v121
	v_mul_f32_e32 v126, 0xbfb8aa3b, v126
	v_mul_f32_e32 v122, 0xbfb8aa3b, v122
	v_mul_f32_e32 v127, 0xbfb8aa3b, v127
	v_mul_f32_e32 v123, 0xbfb8aa3b, v123
	v_exp_f32_e32 v124, v124
	v_exp_f32_e32 v120, v120
	v_exp_f32_e32 v125, v125
	v_exp_f32_e32 v121, v121
	v_exp_f32_e32 v126, v126
	v_exp_f32_e32 v122, v122
	v_exp_f32_e32 v127, v127
	v_exp_f32_e32 v123, v123
	v_add_f32_e32 v124, 1.0, v124
	v_add_f32_e32 v120, 1.0, v120
	v_add_f32_e32 v125, 1.0, v125
	v_add_f32_e32 v121, 1.0, v121
	v_add_f32_e32 v126, 1.0, v126
	v_add_f32_e32 v122, 1.0, v122
	v_add_f32_e32 v127, 1.0, v127
	v_add_f32_e32 v123, 1.0, v123
	v_rcp_f32_e32 v124, v124
	v_rcp_f32_e32 v120, v120
	v_rcp_f32_e32 v125, v125
	v_rcp_f32_e32 v121, v121
	v_rcp_f32_e32 v126, v126
	v_rcp_f32_e32 v122, v122
	v_rcp_f32_e32 v127, v127
	v_rcp_f32_e32 v123, v123

; template <class Epi, class S_t>
; __device__ __forceinline__ void gemm_phase(LAS unsigned char* lds, int lda, int ldb, const S_t& S, const Epi& E) {
;     ...
; #pragma unroll
;         for (int a = 0; a < 2; ++a)
; #pragma unroll
;             for (int b = 0; b < 2; ++b)
; #pragma unroll
;                 for (int m = 0; m < 4; ++m)
; #pragma unroll
;                     for (int n = 0; n < 2; ++n) acc[a][b][m][n] = (f32x4){0.f, 0.f, 0.f, 0.f};
;         cur = nxt; cA = nA; cB = nB; ++ui;
.LBB0_944:
	s_add_u32 s60, s60, 0x40080
	s_addc_u32 s61, s61, 0
	s_add_u32 s0, s62, 0x100
	s_addc_u32 s1, s63, 0
	s_mov_b32 s43, -2
	v_mov_b64_e32 v[0:1], 0
	v_mov_b64_e32 v[2:3], 0
	v_mov_b64_e32 v[4:5], 0
	v_mov_b64_e32 v[6:7], 0
	v_mov_b64_e32 v[8:9], 0
	v_mov_b64_e32 v[10:11], 0
	v_mov_b64_e32 v[12:13], 0
	v_mov_b64_e32 v[14:15], 0
	v_mov_b64_e32 v[16:17], 0
	v_mov_b64_e32 v[18:19], 0
	v_mov_b64_e32 v[20:21], 0
	v_mov_b64_e32 v[22:23], 0
	v_mov_b64_e32 v[24:25], 0
	v_mov_b64_e32 v[26:27], 0
	v_mov_b64_e32 v[28:29], 0
	v_mov_b64_e32 v[30:31], 0
	v_mov_b64_e32 v[32:33], 0
	v_mov_b64_e32 v[34:35], 0
	v_mov_b64_e32 v[36:37], 0
	v_mov_b64_e32 v[38:39], 0
	v_mov_b64_e32 v[40:41], 0
	v_mov_b64_e32 v[42:43], 0
	v_mov_b64_e32 v[44:45], 0
	v_mov_b64_e32 v[46:47], 0
	v_mov_b64_e32 v[48:49], 0
	v_mov_b64_e32 v[50:51], 0
	v_mov_b64_e32 v[52:53], 0
	v_mov_b64_e32 v[54:55], 0
	v_mov_b64_e32 v[56:57], 0
	v_mov_b64_e32 v[58:59], 0
	v_mov_b64_e32 v[60:61], 0
	v_mov_b64_e32 v[62:63], 0
	v_mov_b64_e32 v[64:65], 0
	v_mov_b64_e32 v[66:67], 0
	v_mov_b64_e32 v[68:69], 0
	v_mov_b64_e32 v[70:71], 0
	v_mov_b64_e32 v[72:73], 0
	v_mov_b64_e32 v[74:75], 0
	v_mov_b64_e32 v[76:77], 0
	v_mov_b64_e32 v[78:79], 0
	v_mov_b64_e32 v[80:81], 0
	v_mov_b64_e32 v[82:83], 0
	v_mov_b64_e32 v[84:85], 0
	v_mov_b64_e32 v[86:87], 0
	v_mov_b64_e32 v[88:89], 0
	v_mov_b64_e32 v[90:91], 0
	v_mov_b64_e32 v[92:93], 0
	v_mov_b64_e32 v[94:95], 0
	v_mov_b64_e32 v[96:97], 0
	v_mov_b64_e32 v[98:99], 0
	v_mov_b64_e32 v[100:101], 0
	v_mov_b64_e32 v[102:103], 0
	v_mov_b64_e32 v[104:105], 0
	v_mov_b64_e32 v[106:107], 0
	v_mov_b64_e32 v[108:109], 0
	v_mov_b64_e32 v[110:111], 0
	v_mov_b64_e32 v[112:113], 0
	v_mov_b64_e32 v[114:115], 0
	v_mov_b64_e32 v[116:117], 0
	v_mov_b64_e32 v[118:119], 0
	v_mov_b64_e32 v[120:121], 0
	v_mov_b64_e32 v[122:123], 0
	v_mov_b64_e32 v[124:125], 0
	v_mov_b64_e32 v[126:127], 0
	s_branch .LBB0_945

; #define PG8_STAGE(bufoff, gbase, voff) do { _Pragma("unroll") for (int _i = 0; _i < 2; ++_i) \
;         __builtin_amdgcn_global_load_lds((const unsigned*)((const char*)(gbase) + (voff)[_i]), (LAS unsigned*)(lds + (bufoff) + ldsw + _i * 8192), 16, 0, 0); } while (0)
; #define PG8_LDA(dst, b, h) do { _Pragma("unroll") for (int m = 0; m < 4; ++m) _Pragma("unroll") for (int k = 0; k < 2; ++k) dst[m][k] = *(const LAS bf16x8*)(lds + PG8_SA(b, h) + aoff + m * 2048 + k * 1024); } while (0)
; #define PG8_LDB(dst, b, h) do { _Pragma("unroll") for (int n = 0; n < 2; ++n) _Pragma("unroll") for (int k = 0; k < 2; ++k) dst[n][k] = *(const LAS bf16x8*)(lds + PG8_SB(b, h) + boff + n * 2048 + k * 1024); } while (0)
; #define PG8_MMA(ai, bj, At, Bt) do { __builtin_amdgcn_s_setprio(1); _Pragma("unroll") for (int m = 0; m < 4; ++m) _Pragma("unroll") for (int n = 0; n < 2; ++n) _Pragma("unroll") for (int k = 0; k < 2; ++k) \
;         acc[ai][bj][m][n] = __builtin_amdgcn_mfma_f32_16x16x32_bf16(Bt[n][k], At[m][k], acc[ai][bj][m][n], 0, 0, 0); __builtin_amdgcn_s_setprio(0); } while (0)
; #define PG8_WAIT_V(n) asm volatile("s_waitcnt vmcnt(" #n ")" ::: "memory")
; #define PG8_WAIT_L(n) asm volatile("s_waitcnt lgkmcnt(" #n ")" ::: "memory")
; #define PG8_BAR __builtin_amdgcn_s_barrier()
; #define PG8_SCHED __builtin_amdgcn_sched_barrier(0)
; template <class Epi, class S_t>
; __device__ __forceinline__ void gemm_phase(LAS unsigned char* lds, int lda, int ldb, const S_t& S, const Epi& E) {
;     ...
;             PG8_LDB(B0, 0, 0); PG8_SCHED; PG8_LDA(At, 0, 0); PG8_STAGE(PG8_SA(1, 1), a1 + hstepA, voffA);
;             PG8_WAIT_L(8); PG8_BAR; PG8_WAIT_L(0); PG8_MMA(0, 0, At, B0); PG8_BAR; PG8_SCHED;
;             PG8_LDB(B1, 0, 1); PG8_STAGE(PG8_SB(0, 0), b2, voffB);
;             PG8_BAR; PG8_WAIT_L(0); PG8_MMA(0, 1, At, B1); PG8_BAR;
;             PG8_LDA(At, 0, 1); PG8_STAGE(PG8_SA(0, 0), a2, voffA);
;             PG8_BAR; PG8_WAIT_L(0); PG8_MMA(1, 0, At, B0); PG8_BAR; PG8_SCHED;
;             PG8_STAGE(PG8_SB(0, 1), b2 + hstepB, voffB);
;             PG8_WAIT_V(6); PG8_BAR; PG8_MMA(1, 1, At, B1); PG8_BAR;
;             PG8_LDB(B0, 1, 0); PG8_SCHED; PG8_LDA(At, 1, 0); PG8_STAGE(PG8_SA(0, 1), a2 + hstepA, voffA);
;             PG8_WAIT_L(8); PG8_BAR; PG8_WAIT_L(0); PG8_MMA(0, 0, At, B0); PG8_BAR; PG8_SCHED;
.LBB0_945:
	ds_read_b128 v[140:143], v149
	ds_read_b128 v[152:155], v149 offset:1024
	ds_read_b128 v[156:159], v149 offset:2048
	ds_read_b128 v[160:163], v149 offset:3072
	s_add_u32 s33, s60, 0xfffc0080
	s_addc_u32 s52, s61, -1
	s_cmp_eq_u32 s43, 12
	s_cselect_b32 s67, s59, s52
	s_cselect_b32 s66, s58, s33
	s_cselect_b32 s63, s57, s1
	s_cselect_b32 s62, s56, s0
	s_add_i32 m0, s16, 0xc000
	ds_read_b128 v[164:167], v150
	ds_read_b128 v[168:171], v150 offset:1024
	ds_read_b128 v[172:175], v150 offset:2048
	ds_read_b128 v[176:179], v150 offset:3072
	ds_read_b128 v[180:183], v150 offset:4096
	ds_read_b128 v[186:189], v150 offset:5120
	ds_read_b128 v[190:193], v150 offset:6144
	ds_read_b128 v[194:197], v150 offset:7168
	global_load_lds_dwordx4 v136, s[60:61]
	s_add_i32 m0, s16, 0xe000
	s_nop 0
	global_load_lds_dwordx4 v138, s[60:61]
	s_waitcnt lgkmcnt(8)
	s_barrier
	s_waitcnt lgkmcnt(0)
	s_setprio 1
	v_mfma_f32_16x16x32_bf16 v[124:127], v[140:143], v[164:167], v[124:127]
	v_mfma_f32_16x16x32_bf16 v[120:123], v[156:159], v[164:167], v[120:123]
	v_mfma_f32_16x16x32_bf16 v[116:119], v[140:143], v[172:175], v[116:119]
	v_mfma_f32_16x16x32_bf16 v[108:111], v[156:159], v[172:175], v[108:111]
	v_mfma_f32_16x16x32_bf16 v[96:99], v[140:143], v[180:183], v[96:99]
	v_mfma_f32_16x16x32_bf16 v[88:91], v[156:159], v[180:183], v[88:91]
	v_mfma_f32_16x16x32_bf16 v[80:83], v[140:143], v[190:193], v[80:83]
	v_mfma_f32_16x16x32_bf16 v[72:75], v[156:159], v[190:193], v[72:75]
	v_mfma_f32_16x16x32_bf16 v[124:127], v[152:155], v[168:171], v[124:127]
	v_mfma_f32_16x16x32_bf16 v[120:123], v[160:163], v[168:171], v[120:123]
	v_mfma_f32_16x16x32_bf16 v[116:119], v[152:155], v[176:179], v[116:119]
	v_mfma_f32_16x16x32_bf16 v[108:111], v[160:163], v[176:179], v[108:111]
	v_mfma_f32_16x16x32_bf16 v[96:99], v[152:155], v[186:189], v[96:99]
	v_mfma_f32_16x16x32_bf16 v[88:91], v[160:163], v[186:189], v[88:91]
	v_mfma_f32_16x16x32_bf16 v[80:83], v[152:155], v[194:197], v[80:83]
	v_mfma_f32_16x16x32_bf16 v[72:75], v[160:163], v[194:197], v[72:75]
	s_setprio 0
	s_barrier
	s_add_i32 s33, s88, s5
	s_add_u32 s98, s62, s10
	s_addc_u32 s99, s63, s11
	s_mov_b32 m0, s33
	ds_read_b128 v[198:201], v151
	ds_read_b128 v[202:205], v151 offset:1024
	ds_read_b128 v[206:209], v151 offset:2048
	ds_read_b128 v[222:225], v151 offset:3072
	global_load_lds_dwordx4 v130, s[62:63]
	s_add_i32 m0, s33, 0x2000
	s_nop 0
	global_load_lds_dwordx4 v134, s[62:63]
	s_barrier
	s_waitcnt lgkmcnt(0)
	s_setprio 1
	v_mfma_f32_16x16x32_bf16 v[112:115], v[198:201], v[164:167], v[112:115]
	v_mfma_f32_16x16x32_bf16 v[104:107], v[206:209], v[164:167], v[104:107]
	v_mfma_f32_16x16x32_bf16 v[100:103], v[198:201], v[172:175], v[100:103]
	v_mfma_f32_16x16x32_bf16 v[92:95], v[206:209], v[172:175], v[92:95]
	v_mfma_f32_16x16x32_bf16 v[84:87], v[198:201], v[180:183], v[84:87]
	v_mfma_f32_16x16x32_bf16 v[76:79], v[206:209], v[180:183], v[76:79]
	v_mfma_f32_16x16x32_bf16 v[68:71], v[198:201], v[190:193], v[68:71]
	v_mfma_f32_16x16x32_bf16 v[64:67], v[206:209], v[190:193], v[64:67]
	v_mfma_f32_16x16x32_bf16 v[112:115], v[202:205], v[168:171], v[112:115]
	v_mfma_f32_16x16x32_bf16 v[104:107], v[222:225], v[168:171], v[104:107]
	v_mfma_f32_16x16x32_bf16 v[100:103], v[202:205], v[176:179], v[100:103]
	v_mfma_f32_16x16x32_bf16 v[92:95], v[222:225], v[176:179], v[92:95]
	v_mfma_f32_16x16x32_bf16 v[84:87], v[202:205], v[186:189], v[84:87]
	v_mfma_f32_16x16x32_bf16 v[76:79], v[222:225], v[186:189], v[76:79]
	v_mfma_f32_16x16x32_bf16 v[68:71], v[202:205], v[194:197], v[68:71]
	v_mfma_f32_16x16x32_bf16 v[64:67], v[222:225], v[194:197], v[64:67]
	s_setprio 0
	s_mov_b32 m0, s16
	s_add_u32 s100, s66, s10
	s_addc_u32 s101, s67, s11
	s_barrier
	ds_read_b128 v[164:167], v150 offset:16384
	ds_read_b128 v[168:171], v150 offset:17408
	ds_read_b128 v[172:175], v150 offset:18432
	ds_read_b128 v[176:179], v150 offset:19456
	ds_read_b128 v[180:183], v150 offset:20480
	ds_read_b128 v[186:189], v150 offset:21504
	ds_read_b128 v[190:193], v150 offset:22528
	ds_read_b128 v[194:197], v150 offset:23552
	global_load_lds_dwordx4 v128, s[66:67]
	s_mov_b32 m0, s17
	s_nop 0
	global_load_lds_dwordx4 v132, s[66:67]
	s_barrier
	s_waitcnt lgkmcnt(0)
	s_setprio 1
	v_mfma_f32_16x16x32_bf16 v[60:63], v[140:143], v[164:167], v[60:63]
	v_mfma_f32_16x16x32_bf16 v[56:59], v[156:159], v[164:167], v[56:59]
	v_mfma_f32_16x16x32_bf16 v[48:51], v[140:143], v[172:175], v[48:51]
	v_mfma_f32_16x16x32_bf16 v[40:43], v[156:159], v[172:175], v[40:43]
	v_mfma_f32_16x16x32_bf16 v[32:35], v[140:143], v[180:183], v[32:35]
	v_mfma_f32_16x16x32_bf16 v[24:27], v[156:159], v[180:183], v[24:27]
	v_mfma_f32_16x16x32_bf16 v[16:19], v[140:143], v[190:193], v[16:19]
	v_mfma_f32_16x16x32_bf16 v[8:11], v[156:159], v[190:193], v[8:11]
	v_mfma_f32_16x16x32_bf16 v[60:63], v[152:155], v[168:171], v[60:63]
	v_mfma_f32_16x16x32_bf16 v[56:59], v[160:163], v[168:171], v[56:59]
	v_mfma_f32_16x16x32_bf16 v[48:51], v[152:155], v[176:179], v[48:51]
	v_mfma_f32_16x16x32_bf16 v[40:43], v[160:163], v[176:179], v[40:43]
	v_mfma_f32_16x16x32_bf16 v[32:35], v[152:155], v[186:189], v[32:35]
	v_mfma_f32_16x16x32_bf16 v[24:27], v[160:163], v[186:189], v[24:27]
	v_mfma_f32_16x16x32_bf16 v[16:19], v[152:155], v[194:197], v[16:19]
	v_mfma_f32_16x16x32_bf16 v[8:11], v[160:163], v[194:197], v[8:11]
	s_setprio 0
	s_barrier
	s_add_u32 s52, s62, 0x40000
	s_addc_u32 s53, s63, 0
	s_add_i32 s33, s89, s5
	s_mov_b32 m0, s33
	s_nop 0
	global_load_lds_dwordx4 v130, s[52:53]
	s_add_i32 m0, s33, 0x2000
	s_nop 0
	global_load_lds_dwordx4 v134, s[52:53]
	s_waitcnt vmcnt(6)
	s_barrier
; #define PG8_STAGE(bufoff, gbase, voff) do { _Pragma("unroll") for (int _i = 0; _i < 2; ++_i) \
;         __builtin_amdgcn_global_load_lds((const unsigned*)((const char*)(gbase) + (voff)[_i]), (LAS unsigned*)(lds + (bufoff) + ldsw + _i * 8192), 16, 0, 0); } while (0)
; #define PG8_LDA(dst, b, h) do { _Pragma("unroll") for (int m = 0; m < 4; ++m) _Pragma("unroll") for (int k = 0; k < 2; ++k) dst[m][k] = *(const LAS bf16x8*)(lds + PG8_SA(b, h) + aoff + m * 2048 + k * 1024); } while (0)
; #define PG8_LDB(dst, b, h) do { _Pragma("unroll") for (int n = 0; n < 2; ++n) _Pragma("unroll") for (int k = 0; k < 2; ++k) dst[n][k] = *(const LAS bf16x8*)(lds + PG8_SB(b, h) + boff + n * 2048 + k * 1024); } while (0)
; #define PG8_MMA(ai, bj, At, Bt) do { __builtin_amdgcn_s_setprio(1); _Pragma("unroll") for (int m = 0; m < 4; ++m) _Pragma("unroll") for (int n = 0; n < 2; ++n) _Pragma("unroll") for (int k = 0; k < 2; ++k) \
;         acc[ai][bj][m][n] = __builtin_amdgcn_mfma_f32_16x16x32_bf16(Bt[n][k], At[m][k], acc[ai][bj][m][n], 0, 0, 0); __builtin_amdgcn_s_setprio(0); } while (0)
; #define PG8_WAIT_L(n) asm volatile("s_waitcnt lgkmcnt(" #n ")" ::: "memory")
; #define PG8_BAR __builtin_amdgcn_s_barrier()
; #define PG8_SCHED __builtin_amdgcn_sched_barrier(0)
; template <class Epi, class S_t>
; __device__ __forceinline__ void gemm_phase(LAS unsigned char* lds, int lda, int ldb, const S_t& S, const Epi& E) {
;     ...
;             PG8_LDB(B0, 1, 0); PG8_SCHED; PG8_LDA(At, 1, 0); PG8_STAGE(PG8_SA(0, 1), a2 + hstepA, voffA);
;             PG8_WAIT_L(8); PG8_BAR; PG8_WAIT_L(0); PG8_MMA(0, 0, At, B0); PG8_BAR; PG8_SCHED;
;             PG8_LDB(B1, 1, 1); PG8_STAGE(PG8_SB(1, 0), b3, voffB);
;             PG8_BAR; PG8_WAIT_L(0); PG8_MMA(0, 1, At, B1); PG8_BAR;
;             PG8_LDA(At, 1, 1); PG8_STAGE(PG8_SA(1, 0), a3, voffA);
;             PG8_BAR; PG8_WAIT_L(0); PG8_MMA(1, 0, At, B0); PG8_BAR; PG8_SCHED;
	s_setprio 1
	v_mfma_f32_16x16x32_bf16 v[52:55], v[198:201], v[164:167], v[52:55]
	v_mfma_f32_16x16x32_bf16 v[44:47], v[206:209], v[164:167], v[44:47]
	v_mfma_f32_16x16x32_bf16 v[36:39], v[198:201], v[172:175], v[36:39]
	v_mfma_f32_16x16x32_bf16 v[28:31], v[206:209], v[172:175], v[28:31]
	v_mfma_f32_16x16x32_bf16 v[20:23], v[198:201], v[180:183], v[20:23]
	v_mfma_f32_16x16x32_bf16 v[12:15], v[206:209], v[180:183], v[12:15]
	v_mfma_f32_16x16x32_bf16 v[4:7], v[198:201], v[190:193], v[4:7]
	v_mfma_f32_16x16x32_bf16 v[0:3], v[206:209], v[190:193], v[0:3]
	v_mfma_f32_16x16x32_bf16 v[52:55], v[202:205], v[168:171], v[52:55]
	v_mfma_f32_16x16x32_bf16 v[44:47], v[222:225], v[168:171], v[44:47]
	v_mfma_f32_16x16x32_bf16 v[36:39], v[202:205], v[176:179], v[36:39]
	v_mfma_f32_16x16x32_bf16 v[28:31], v[222:225], v[176:179], v[28:31]
	v_mfma_f32_16x16x32_bf16 v[20:23], v[202:205], v[186:189], v[20:23]
	v_mfma_f32_16x16x32_bf16 v[12:15], v[222:225], v[186:189], v[12:15]
	v_mfma_f32_16x16x32_bf16 v[4:7], v[202:205], v[194:197], v[4:7]
	v_mfma_f32_16x16x32_bf16 v[0:3], v[222:225], v[194:197], v[0:3]
	s_setprio 0
	v_add_u32_e32 v160, s90, v147
	s_barrier
	ds_read_b128 v[140:143], v160
	ds_read_b128 v[152:155], v160 offset:1024
	ds_read_b128 v[156:159], v160 offset:2048
	ds_read_b128 v[160:163], v160 offset:3072
	s_add_u32 s52, s66, 0x40000
	s_addc_u32 s53, s67, 0
	s_mov_b32 m0, s20
	ds_read_b128 v[164:167], v150 offset:32768
	ds_read_b128 v[168:171], v150 offset:33792
	ds_read_b128 v[172:175], v150 offset:34816
	ds_read_b128 v[176:179], v150 offset:35840
	ds_read_b128 v[180:183], v150 offset:36864
	ds_read_b128 v[186:189], v150 offset:37888
	ds_read_b128 v[190:193], v150 offset:38912
	ds_read_b128 v[194:197], v150 offset:39936
	global_load_lds_dwordx4 v128, s[52:53]
	s_mov_b32 m0, s21
	s_nop 0
	global_load_lds_dwordx4 v132, s[52:53]
	s_waitcnt lgkmcnt(8)
	s_barrier
	s_waitcnt lgkmcnt(0)
	s_setprio 1
	v_mfma_f32_16x16x32_bf16 v[124:127], v[140:143], v[164:167], v[124:127]
	v_mfma_f32_16x16x32_bf16 v[120:123], v[156:159], v[164:167], v[120:123]
	v_mfma_f32_16x16x32_bf16 v[116:119], v[140:143], v[172:175], v[116:119]
	v_mfma_f32_16x16x32_bf16 v[108:111], v[156:159], v[172:175], v[108:111]
	v_mfma_f32_16x16x32_bf16 v[96:99], v[140:143], v[180:183], v[96:99]
	v_mfma_f32_16x16x32_bf16 v[88:91], v[156:159], v[180:183], v[88:91]
	v_mfma_f32_16x16x32_bf16 v[80:83], v[140:143], v[190:193], v[80:83]
	v_mfma_f32_16x16x32_bf16 v[72:75], v[156:159], v[190:193], v[72:75]
	v_mfma_f32_16x16x32_bf16 v[124:127], v[152:155], v[168:171], v[124:127]
	v_mfma_f32_16x16x32_bf16 v[120:123], v[160:163], v[168:171], v[120:123]
	v_mfma_f32_16x16x32_bf16 v[116:119], v[152:155], v[176:179], v[116:119]
	v_mfma_f32_16x16x32_bf16 v[108:111], v[160:163], v[176:179], v[108:111]
	v_mfma_f32_16x16x32_bf16 v[96:99], v[152:155], v[186:189], v[96:99]
	v_mfma_f32_16x16x32_bf16 v[88:91], v[160:163], v[186:189], v[88:91]
	v_mfma_f32_16x16x32_bf16 v[80:83], v[152:155], v[194:197], v[80:83]
	v_mfma_f32_16x16x32_bf16 v[72:75], v[160:163], v[194:197], v[72:75]
	s_setprio 0
	s_barrier
	s_add_i32 s33, s90, s5
	v_add_u32_e32 v185, s91, v147
	s_mov_b32 m0, s33
	ds_read_b128 v[198:201], v185
	ds_read_b128 v[202:205], v185 offset:1024
	ds_read_b128 v[206:209], v185 offset:2048
	ds_read_b128 v[222:225], v185 offset:3072
	global_load_lds_dwordx4 v130, s[98:99]
	s_add_i32 m0, s33, 0x2000
	s_nop 0
	global_load_lds_dwordx4 v134, s[98:99]
	s_barrier
	s_waitcnt lgkmcnt(0)
	s_setprio 1
	v_mfma_f32_16x16x32_bf16 v[112:115], v[198:201], v[164:167], v[112:115]
	v_mfma_f32_16x16x32_bf16 v[104:107], v[206:209], v[164:167], v[104:107]
	v_mfma_f32_16x16x32_bf16 v[100:103], v[198:201], v[172:175], v[100:103]
	v_mfma_f32_16x16x32_bf16 v[92:95], v[206:209], v[172:175], v[92:95]
	v_mfma_f32_16x16x32_bf16 v[84:87], v[198:201], v[180:183], v[84:87]
	v_mfma_f32_16x16x32_bf16 v[76:79], v[206:209], v[180:183], v[76:79]
	v_mfma_f32_16x16x32_bf16 v[68:71], v[198:201], v[190:193], v[68:71]
	v_mfma_f32_16x16x32_bf16 v[64:67], v[206:209], v[190:193], v[64:67]
	v_mfma_f32_16x16x32_bf16 v[112:115], v[202:205], v[168:171], v[112:115]
	v_mfma_f32_16x16x32_bf16 v[104:107], v[222:225], v[168:171], v[104:107]
	v_mfma_f32_16x16x32_bf16 v[100:103], v[202:205], v[176:179], v[100:103]
	v_mfma_f32_16x16x32_bf16 v[92:95], v[222:225], v[176:179], v[92:95]
	v_mfma_f32_16x16x32_bf16 v[84:87], v[202:205], v[186:189], v[84:87]
	v_mfma_f32_16x16x32_bf16 v[76:79], v[222:225], v[186:189], v[76:79]
	v_mfma_f32_16x16x32_bf16 v[68:71], v[202:205], v[194:197], v[68:71]
	v_mfma_f32_16x16x32_bf16 v[64:67], v[222:225], v[194:197], v[64:67]
	s_setprio 0
	s_mov_b32 m0, s35
	s_barrier
	ds_read_b128 v[164:167], v150 offset:49152
	ds_read_b128 v[168:171], v150 offset:50176
	ds_read_b128 v[172:175], v150 offset:51200
	ds_read_b128 v[176:179], v150 offset:52224
	ds_read_b128 v[180:183], v150 offset:53248
	ds_read_b128 v[186:189], v150 offset:54272
	ds_read_b128 v[190:193], v150 offset:55296
	ds_read_b128 v[194:197], v150 offset:56320
	global_load_lds_dwordx4 v128, s[100:101]
	s_mov_b32 m0, s64
	s_nop 0
	global_load_lds_dwordx4 v132, s[100:101]
	s_barrier
; #define PG8_STAGE(bufoff, gbase, voff) do { _Pragma("unroll") for (int _i = 0; _i < 2; ++_i) \
;         __builtin_amdgcn_global_load_lds((const unsigned*)((const char*)(gbase) + (voff)[_i]), (LAS unsigned*)(lds + (bufoff) + ldsw + _i * 8192), 16, 0, 0); } while (0)
; #define PG8_MMA(ai, bj, At, Bt) do { __builtin_amdgcn_s_setprio(1); _Pragma("unroll") for (int m = 0; m < 4; ++m) _Pragma("unroll") for (int n = 0; n < 2; ++n) _Pragma("unroll") for (int k = 0; k < 2; ++k) \
;         acc[ai][bj][m][n] = __builtin_amdgcn_mfma_f32_16x16x32_bf16(Bt[n][k], At[m][k], acc[ai][bj][m][n], 0, 0, 0); __builtin_amdgcn_s_setprio(0); } while (0)
; #define PG8_WAIT_V(n) asm volatile("s_waitcnt vmcnt(" #n ")" ::: "memory")
; #define PG8_WAIT_L(n) asm volatile("s_waitcnt lgkmcnt(" #n ")" ::: "memory")
; #define PG8_BAR __builtin_amdgcn_s_barrier()
; #define PG8_SCHED __builtin_amdgcn_sched_barrier(0)
; template <class Epi, class S_t>
; __device__ __forceinline__ void gemm_phase(LAS unsigned char* lds, int lda, int ldb, const S_t& S, const Epi& E) {
;     ...
;             PG8_BAR; PG8_WAIT_L(0); PG8_MMA(1, 0, At, B0); PG8_BAR; PG8_SCHED;
;             PG8_STAGE(PG8_SB(1, 1), b3 + hstepB, voffB);
;             PG8_WAIT_V(6); PG8_BAR; PG8_MMA(1, 1, At, B1); PG8_BAR;
;         }
;         E(acc, cur, wr, wc, fr, fq);
;     __device__ __forceinline__ void operator()(const f32x4 (&acc)[2][2][4][2], const Unit& u, int wr, int wc, int fr, int fq) const {
;     ...
;         for (int ai = 0; ai < 2; ++ai) {
;             u32x4 gr[4][2], orw[4][2];
;             asm volatile("" ::: "memory");
; #pragma unroll
;             for (int m = 0; m < 4; ++m)
; #pragma unroll
;                 for (int bj = 0; bj < 2; ++bj) { const int row = row0 + ai * HALF + m * 16, col = col0 + bj * HALF;
;                     gr[m][bj] = *(const u32x4*)(Z + (size_t)row * INW + gcol0 + col);
;                     if (ADD) orw[m][bj] = *(const u32x4*)(MG + (size_t)row * DM + col); }
	s_waitcnt lgkmcnt(0)
	s_setprio 1
	v_mfma_f32_16x16x32_bf16 v[60:63], v[140:143], v[164:167], v[60:63]
	v_mfma_f32_16x16x32_bf16 v[56:59], v[156:159], v[164:167], v[56:59]
	v_mfma_f32_16x16x32_bf16 v[48:51], v[140:143], v[172:175], v[48:51]
	v_mfma_f32_16x16x32_bf16 v[40:43], v[156:159], v[172:175], v[40:43]
	v_mfma_f32_16x16x32_bf16 v[32:35], v[140:143], v[180:183], v[32:35]
	v_mfma_f32_16x16x32_bf16 v[24:27], v[156:159], v[180:183], v[24:27]
	v_mfma_f32_16x16x32_bf16 v[16:19], v[140:143], v[190:193], v[16:19]
	v_mfma_f32_16x16x32_bf16 v[8:11], v[156:159], v[190:193], v[8:11]
	v_mfma_f32_16x16x32_bf16 v[60:63], v[152:155], v[168:171], v[60:63]
	v_mfma_f32_16x16x32_bf16 v[56:59], v[160:163], v[168:171], v[56:59]
	v_mfma_f32_16x16x32_bf16 v[48:51], v[152:155], v[176:179], v[48:51]
	v_mfma_f32_16x16x32_bf16 v[40:43], v[160:163], v[176:179], v[40:43]
	v_mfma_f32_16x16x32_bf16 v[32:35], v[152:155], v[186:189], v[32:35]
	v_mfma_f32_16x16x32_bf16 v[24:27], v[160:163], v[186:189], v[24:27]
	v_mfma_f32_16x16x32_bf16 v[16:19], v[152:155], v[194:197], v[16:19]
	v_mfma_f32_16x16x32_bf16 v[8:11], v[160:163], v[194:197], v[8:11]
	s_setprio 0
	s_barrier
	s_add_u32 s52, s62, 0x40080
	s_addc_u32 s53, s63, 0
	s_add_i32 s33, s91, s5
	s_mov_b32 m0, s33
	s_nop 0
	global_load_lds_dwordx4 v130, s[52:53]
	s_add_i32 m0, s33, 0x2000
	s_nop 0
	global_load_lds_dwordx4 v134, s[52:53]
	s_waitcnt vmcnt(6)
	s_barrier
	s_setprio 1
	v_mfma_f32_16x16x32_bf16 v[52:55], v[198:201], v[164:167], v[52:55]
	v_mfma_f32_16x16x32_bf16 v[44:47], v[206:209], v[164:167], v[44:47]
	v_mfma_f32_16x16x32_bf16 v[36:39], v[198:201], v[172:175], v[36:39]
	v_mfma_f32_16x16x32_bf16 v[28:31], v[206:209], v[172:175], v[28:31]
	v_mfma_f32_16x16x32_bf16 v[20:23], v[198:201], v[180:183], v[20:23]
	v_mfma_f32_16x16x32_bf16 v[12:15], v[206:209], v[180:183], v[12:15]
	v_mfma_f32_16x16x32_bf16 v[4:7], v[198:201], v[190:193], v[4:7]
	v_mfma_f32_16x16x32_bf16 v[0:3], v[206:209], v[190:193], v[0:3]
	v_mfma_f32_16x16x32_bf16 v[52:55], v[202:205], v[168:171], v[52:55]
	v_mfma_f32_16x16x32_bf16 v[44:47], v[222:225], v[168:171], v[44:47]
	v_mfma_f32_16x16x32_bf16 v[36:39], v[202:205], v[176:179], v[36:39]
	v_mfma_f32_16x16x32_bf16 v[28:31], v[222:225], v[176:179], v[28:31]
	v_mfma_f32_16x16x32_bf16 v[20:23], v[202:205], v[186:189], v[20:23]
	v_mfma_f32_16x16x32_bf16 v[12:15], v[222:225], v[186:189], v[12:15]
	v_mfma_f32_16x16x32_bf16 v[4:7], v[202:205], v[194:197], v[4:7]
	v_mfma_f32_16x16x32_bf16 v[0:3], v[222:225], v[194:197], v[0:3]
	s_setprio 0
	s_add_i32 s43, s43, 2
	s_add_u32 s60, s60, 0x100
	s_addc_u32 s61, s61, 0
	s_add_u32 s0, s0, 0x100
	s_addc_u32 s1, s1, 0
	s_cmp_gt_u32 s43, 13
	s_cbranch_scc0 .Lrot_945
	s_barrier
	v_lshl_or_b32 v140, s42, 8, v148
	v_lshl_add_u32 v142, s8, 8, v146
	v_ashrrev_i32_e32 v141, 31, v140
	v_mov_b64_e32 v[144:145], s[46:47]
	v_mad_i64_i32 v[152:153], s[0:1], v142, s69, v[144:145]
	v_lshlrev_b64 v[140:141], 1, v[140:141]
	v_or_b32_e32 v168, 16, v142
	v_lshl_add_u64 v[156:157], v[152:153], 0, v[140:141]
	v_mad_i64_i32 v[160:161], s[0:1], v168, s69, v[144:145]
	global_load_dwordx4 v[152:155], v[156:157], off
	s_nop 0
	global_load_dwordx4 v[156:159], v[156:157], off offset:256
	v_lshl_add_u64 v[164:165], v[160:161], 0, v[140:141]
	global_load_dwordx4 v[160:163], v[164:165], off
	v_or_b32_e32 v186, 32, v142
	global_load_dwordx4 v[164:167], v[164:165], off offset:256
	v_or_b32_e32 v188, 48, v142
	v_ashrrev_i32_e32 v143, 31, v142
	v_mad_i64_i32 v[170:171], s[0:1], v186, s69, v[144:145]
	v_mad_i64_i32 v[172:173], s[0:1], v188, s69, v[144:145]
	v_ashrrev_i32_e32 v169, 31, v168
	v_lshlrev_b64 v[174:175], 12, v[142:143]
	v_lshl_add_u64 v[176:177], v[170:171], 0, v[140:141]
	v_lshl_add_u64 v[180:181], v[172:173], 0, v[140:141]
	v_lshl_add_u64 v[190:191], s[44:45], 0, v[174:175]
	v_lshlrev_b64 v[192:193], 12, v[168:169]
	global_load_dwordx4 v[168:171], v[176:177], off
	global_load_dwordx4 v[172:175], v[176:177], off offset:256
	s_nop 0
	global_load_dwordx4 v[176:179], v[180:181], off
	s_nop 0
	global_load_dwordx4 v[180:183], v[180:181], off offset:256
	v_lshl_add_u64 v[190:191], v[190:191], 0, v[140:141]
	v_ashrrev_i32_e32 v187, 31, v186
	v_ashrrev_i32_e32 v189, 31, v188
	s_cmpk_lt_i32 s70, 0x3e8
	s_waitcnt vmcnt(0)
; __device__ __forceinline__ u32x4 pack8(const float (&f)[8]) { u32x4 w; w.x = pk2(f[0], f[1]); w.y = pk2(f[2], f[3]); w.z = pk2(f[4], f[5]); w.w = pk2(f[6], f[7]); return w; }
;     __device__ __forceinline__ void operator()(const f32x4 (&acc)[2][2][4][2], const Unit& u, int wr, int wc, int fr, int fq) const {
;     ...
;             for (int m = 0; m < 4; ++m)
; #pragma unroll
;                 for (int bj = 0; bj < 2; ++bj) { const int row = row0 + ai * HALF + m * 16, col = col0 + bj * HALF;
;                     float g[8], o[8]; unpack8(gr[m][bj], g);
;                     if (ADD) unpack8(orw[m][bj], o);
; #pragma unroll
;                     for (int n = 0; n < 2; ++n)
; #pragma unroll
;                         for (int j = 0; j < 4; ++j) { const int e = 4 * n + j; o[e] = ADD ? o[e] + g[e] * acc[ai][bj][m][n][j] : g[e] * acc[ai][bj][m][n][j]; }
;                     *(u32x4*)(MG + (size_t)row * DM + col) = pack8(o); }
	v_lshlrev_b32_e32 v143, 16, v152
	v_and_b32_e32 v152, 0xffff0000, v152
	v_lshlrev_b32_e32 v185, 16, v153
	v_and_b32_e32 v153, 0xffff0000, v153
	v_lshlrev_b32_e32 v194, 16, v154
	v_and_b32_e32 v154, 0xffff0000, v154
	v_lshlrev_b32_e32 v195, 16, v155
	v_and_b32_e32 v155, 0xffff0000, v155
	v_lshlrev_b32_e32 v196, 16, v156
	v_and_b32_e32 v156, 0xffff0000, v156
	v_lshlrev_b32_e32 v197, 16, v157
	v_and_b32_e32 v157, 0xffff0000, v157
	v_lshlrev_b32_e32 v198, 16, v158
	v_and_b32_e32 v158, 0xffff0000, v158
	v_lshlrev_b32_e32 v199, 16, v159
	v_and_b32_e32 v159, 0xffff0000, v159
	v_lshlrev_b32_e32 v200, 16, v160
	v_and_b32_e32 v160, 0xffff0000, v160
	v_lshlrev_b32_e32 v201, 16, v161
	v_lshlrev_b32_e32 v202, 16, v162
	v_and_b32_e32 v162, 0xffff0000, v162
	v_mul_f32_e32 v124, v124, v143
	v_mul_f32_e32 v125, v125, v152
	v_mul_f32_e32 v126, v126, v185
	v_mul_f32_e32 v127, v127, v153
	v_mul_f32_e32 v120, v120, v194
	v_mul_f32_e32 v121, v121, v154
	v_mul_f32_e32 v122, v122, v195
	v_mul_f32_e32 v123, v123, v155
	v_mul_f32_e32 v112, v112, v196
	v_mul_f32_e32 v113, v113, v156
	v_mul_f32_e32 v114, v114, v197
	v_mul_f32_e32 v115, v115, v157
	v_mul_f32_e32 v143, v104, v198
	v_mul_f32_e32 v152, v105, v158
	v_mul_f32_e32 v153, v106, v199
	v_mul_f32_e32 v154, v107, v159
	v_cvt_pk_bf16_f32 v104, v124, v125
	v_cvt_pk_bf16_f32 v105, v126, v127
	v_cvt_pk_bf16_f32 v106, v120, v121
	v_cvt_pk_bf16_f32 v107, v122, v123
	v_and_b32_e32 v161, 0xffff0000, v161
	v_cvt_pk_bf16_f32 v112, v112, v113
	v_cvt_pk_bf16_f32 v113, v114, v115
	v_cvt_pk_bf16_f32 v114, v143, v152
	v_cvt_pk_bf16_f32 v115, v153, v154
	global_store_dwordx4 v[190:191], v[104:107], off
	global_store_dwordx4 v[190:191], v[112:115], off offset:256
	v_mul_f32_e32 v108, v108, v202
	v_mul_f32_e32 v104, v116, v200
	v_mul_f32_e32 v105, v117, v160
	v_mul_f32_e32 v106, v118, v201
	v_mul_f32_e32 v109, v109, v162
	v_lshlrev_b32_e32 v203, 16, v163
	v_and_b32_e32 v163, 0xffff0000, v163
	v_mul_f32_e32 v107, v119, v161
	v_cvt_pk_bf16_f32 v104, v104, v105
	v_cvt_pk_bf16_f32 v105, v106, v107
	v_cvt_pk_bf16_f32 v106, v108, v109
	v_lshl_add_u64 v[108:109], s[44:45], 0, v[192:193]
	v_mul_f32_e32 v110, v110, v203
	v_mul_f32_e32 v111, v111, v163
	v_cvt_pk_bf16_f32 v107, v110, v111
	v_lshl_add_u64 v[108:109], v[108:109], 0, v[140:141]
	global_store_dwordx4 v[108:109], v[104:107], off
	v_lshlrev_b32_e32 v110, 16, v166
	v_and_b32_e32 v111, 0xffff0000, v166
	v_lshlrev_b32_e32 v104, 16, v164
	v_and_b32_e32 v105, 0xffff0000, v164
	v_lshlrev_b32_e32 v106, 16, v165
	v_and_b32_e32 v107, 0xffff0000, v165
	v_and_b32_e32 v113, 0xffff0000, v167
	v_lshlrev_b32_e32 v112, 16, v167
	v_mul_f32_e32 v100, v100, v104
	v_mul_f32_e32 v101, v101, v105
	v_mul_f32_e32 v102, v102, v106
	v_mul_f32_e32 v103, v103, v107
	v_mul_f32_e32 v104, v92, v110
	v_mul_f32_e32 v105, v93, v111
	v_mul_f32_e32 v95, v95, v113
	v_cvt_pk_bf16_f32 v92, v100, v101
	v_cvt_pk_bf16_f32 v93, v102, v103
	v_mul_f32_e32 v106, v94, v112
	v_cvt_pk_bf16_f32 v94, v104, v105
	v_cvt_pk_bf16_f32 v95, v106, v95
	global_store_dwordx4 v[108:109], v[92:95], off offset:256
	v_and_b32_e32 v105, 0xffff0000, v171
	v_lshlrev_b32_e32 v100, 16, v169
	v_lshlrev_b64 v[92:93], 12, v[186:187]
	v_lshlrev_b32_e32 v94, 16, v168
	v_and_b32_e32 v95, 0xffff0000, v168
	v_and_b32_e32 v101, 0xffff0000, v169
	v_lshlrev_b32_e32 v102, 16, v170
	v_and_b32_e32 v103, 0xffff0000, v170
	v_lshlrev_b32_e32 v104, 16, v171
	v_mul_f32_e32 v91, v91, v105
	v_lshl_add_u64 v[92:93], s[44:45], 0, v[92:93]
	v_mul_f32_e32 v94, v96, v94
	v_mul_f32_e32 v95, v97, v95
	v_mul_f32_e32 v96, v98, v100
	v_mul_f32_e32 v97, v99, v101
	v_mul_f32_e32 v98, v88, v102
	v_mul_f32_e32 v99, v89, v103
	v_mul_f32_e32 v100, v90, v104
	v_cvt_pk_bf16_f32 v88, v94, v95
	v_cvt_pk_bf16_f32 v89, v96, v97
	v_cvt_pk_bf16_f32 v90, v98, v99
	v_cvt_pk_bf16_f32 v91, v100, v91
	v_lshl_add_u64 v[92:93], v[92:93], 0, v[140:141]
	global_store_dwordx4 v[92:93], v[88:91], off
	v_lshlrev_b32_e32 v94, 16, v174
	v_and_b32_e32 v95, 0xffff0000, v174
	v_lshlrev_b32_e32 v88, 16, v172
	v_and_b32_e32 v89, 0xffff0000, v172
	v_lshlrev_b32_e32 v90, 16, v173
	v_and_b32_e32 v91, 0xffff0000, v173
	v_and_b32_e32 v97, 0xffff0000, v175
	v_lshlrev_b32_e32 v96, 16, v175
	v_mul_f32_e32 v84, v84, v88
	v_mul_f32_e32 v85, v85, v89
	v_mul_f32_e32 v86, v86, v90
	v_mul_f32_e32 v87, v87, v91
	v_mul_f32_e32 v88, v76, v94
	v_mul_f32_e32 v89, v77, v95
	v_mul_f32_e32 v79, v79, v97
	v_cvt_pk_bf16_f32 v76, v84, v85
	v_cvt_pk_bf16_f32 v77, v86, v87
	v_mul_f32_e32 v90, v78, v96
	v_cvt_pk_bf16_f32 v78, v88, v89
	v_cvt_pk_bf16_f32 v79, v90, v79
	global_store_dwordx4 v[92:93], v[76:79], off offset:256
	v_and_b32_e32 v89, 0xffff0000, v179
	v_lshlrev_b32_e32 v84, 16, v177
	v_lshlrev_b64 v[76:77], 12, v[188:189]
	v_lshlrev_b32_e32 v78, 16, v176
	v_and_b32_e32 v79, 0xffff0000, v176
	v_and_b32_e32 v85, 0xffff0000, v177
	v_lshlrev_b32_e32 v86, 16, v178
	v_and_b32_e32 v87, 0xffff0000, v178
	v_lshlrev_b32_e32 v88, 16, v179
	v_mul_f32_e32 v75, v75, v89
	v_lshl_add_u64 v[76:77], s[44:45], 0, v[76:77]
	v_mul_f32_e32 v78, v80, v78
	v_mul_f32_e32 v79, v81, v79
	v_mul_f32_e32 v80, v82, v84
	v_mul_f32_e32 v81, v83, v85
	v_mul_f32_e32 v82, v72, v86
	v_mul_f32_e32 v83, v73, v87
	v_mul_f32_e32 v84, v74, v88
	v_cvt_pk_bf16_f32 v72, v78, v79
	v_cvt_pk_bf16_f32 v73, v80, v81
	v_cvt_pk_bf16_f32 v74, v82, v83
	v_cvt_pk_bf16_f32 v75, v84, v75
	v_lshl_add_u64 v[76:77], v[76:77], 0, v[140:141]
	global_store_dwordx4 v[76:77], v[72:75], off
	v_lshlrev_b32_e32 v78, 16, v182
	v_and_b32_e32 v79, 0xffff0000, v182
	v_lshlrev_b32_e32 v72, 16, v180
	v_and_b32_e32 v73, 0xffff0000, v180
	v_lshlrev_b32_e32 v74, 16, v181
	v_and_b32_e32 v75, 0xffff0000, v181
; __device__ __forceinline__ u32x4 pack8(const float (&f)[8]) { u32x4 w; w.x = pk2(f[0], f[1]); w.y = pk2(f[2], f[3]); w.z = pk2(f[4], f[5]); w.w = pk2(f[6], f[7]); return w; }
;     __device__ __forceinline__ void operator()(const f32x4 (&acc)[2][2][4][2], const Unit& u, int wr, int wc, int fr, int fq) const {
;     ...
;             for (int m = 0; m < 4; ++m)
; #pragma unroll
;                 for (int bj = 0; bj < 2; ++bj) { const int row = row0 + ai * HALF + m * 16, col = col0 + bj * HALF;
;                     gr[m][bj] = *(const u32x4*)(Z + (size_t)row * INW + gcol0 + col);
;                     if (ADD) orw[m][bj] = *(const u32x4*)(MG + (size_t)row * DM + col); }
;     ...
;             for (int m = 0; m < 4; ++m)
; #pragma unroll
;                 for (int bj = 0; bj < 2; ++bj) { const int row = row0 + ai * HALF + m * 16, col = col0 + bj * HALF;
;                     float g[8], o[8]; unpack8(gr[m][bj], g);
;                     if (ADD) unpack8(orw[m][bj], o);
; #pragma unroll
;                     for (int n = 0; n < 2; ++n)
; #pragma unroll
;                         for (int j = 0; j < 4; ++j) { const int e = 4 * n + j; o[e] = ADD ? o[e] + g[e] * acc[ai][bj][m][n][j] : g[e] * acc[ai][bj][m][n][j]; }
;                     *(u32x4*)(MG + (size_t)row * DM + col) = pack8(o); }
	v_and_b32_e32 v81, 0xffff0000, v183
	v_lshlrev_b32_e32 v80, 16, v183
	v_mul_f32_e32 v68, v68, v72
	v_mul_f32_e32 v69, v69, v73
	v_mul_f32_e32 v70, v70, v74
	v_mul_f32_e32 v71, v71, v75
	v_mul_f32_e32 v72, v64, v78
	v_mul_f32_e32 v73, v65, v79
	v_mul_f32_e32 v67, v67, v81
	v_cvt_pk_bf16_f32 v64, v68, v69
	v_cvt_pk_bf16_f32 v65, v70, v71
	v_add_u32_e32 v96, 0x80, v142
	v_mul_f32_e32 v74, v66, v80
	v_cvt_pk_bf16_f32 v66, v72, v73
	v_cvt_pk_bf16_f32 v67, v74, v67
	global_store_dwordx4 v[76:77], v[64:67], off offset:256
	v_add_u32_e32 v98, 0x90, v142
	v_mad_i64_i32 v[72:73], s[0:1], v98, s69, v[144:145]
	v_mad_i64_i32 v[64:65], s[0:1], v96, s69, v[144:145]
	v_lshl_add_u64 v[68:69], v[64:65], 0, v[140:141]
	global_load_dwordx4 v[64:67], v[68:69], off
	s_nop 0
	global_load_dwordx4 v[68:71], v[68:69], off offset:256
	v_lshl_add_u64 v[76:77], v[72:73], 0, v[140:141]
	global_load_dwordx4 v[72:75], v[76:77], off
	v_add_u32_e32 v100, 0xa0, v142
	global_load_dwordx4 v[76:79], v[76:77], off offset:256
	v_mad_i64_i32 v[80:81], s[0:1], v100, s69, v[144:145]
	v_lshl_add_u64 v[84:85], v[80:81], 0, v[140:141]
	global_load_dwordx4 v[80:83], v[84:85], off
	s_nop 0
	global_load_dwordx4 v[84:87], v[84:85], off offset:256
	v_add_u32_e32 v102, 0xb0, v142
	v_mad_i64_i32 v[88:89], s[0:1], v102, s69, v[144:145]
	v_lshl_add_u64 v[92:93], v[88:89], 0, v[140:141]
	global_load_dwordx4 v[88:91], v[92:93], off
	s_nop 0
	global_load_dwordx4 v[92:95], v[92:93], off offset:256
	v_ashrrev_i32_e32 v97, 31, v96
	v_lshlrev_b64 v[96:97], 12, v[96:97]
	v_ashrrev_i32_e32 v99, 31, v98
	v_ashrrev_i32_e32 v101, 31, v100
	v_ashrrev_i32_e32 v103, 31, v102
	s_waitcnt vmcnt(0)
; __device__ __forceinline__ u32x4 pack8(const float (&f)[8]) { u32x4 w; w.x = pk2(f[0], f[1]); w.y = pk2(f[2], f[3]); w.z = pk2(f[4], f[5]); w.w = pk2(f[6], f[7]); return w; }
;     __device__ __forceinline__ void operator()(const f32x4 (&acc)[2][2][4][2], const Unit& u, int wr, int wc, int fr, int fq) const {
;     ...
; #pragma unroll
;         for (int ai = 0; ai < 2; ++ai) {
;             u32x4 gr[4][2], orw[4][2];
;             asm volatile("" ::: "memory");
; #pragma unroll
;             for (int m = 0; m < 4; ++m)
; #pragma unroll
;                 for (int bj = 0; bj < 2; ++bj) { const int row = row0 + ai * HALF + m * 16, col = col0 + bj * HALF;
;                     gr[m][bj] = *(const u32x4*)(Z + (size_t)row * INW + gcol0 + col);
;                     if (ADD) orw[m][bj] = *(const u32x4*)(MG + (size_t)row * DM + col); }
;             asm volatile("" ::: "memory");
; #pragma unroll
;             for (int m = 0; m < 4; ++m)
; #pragma unroll
;                 for (int bj = 0; bj < 2; ++bj) { const int row = row0 + ai * HALF + m * 16, col = col0 + bj * HALF;
;                     float g[8], o[8]; unpack8(gr[m][bj], g);
;                     if (ADD) unpack8(orw[m][bj], o);
; #pragma unroll
;                     for (int n = 0; n < 2; ++n)
; #pragma unroll
;                         for (int j = 0; j < 4; ++j) { const int e = 4 * n + j; o[e] = ADD ? o[e] + g[e] * acc[ai][bj][m][n][j] : g[e] * acc[ai][bj][m][n][j]; }
;                     *(u32x4*)(MG + (size_t)row * DM + col) = pack8(o); }
;         }
;         if (!ADD && u.tag >= 1000) {
;             asm volatile("s_waitcnt vmcnt(0)" ::: "memory");
;             __builtin_amdgcn_fence(__ATOMIC_RELEASE, "agent");
;             asm volatile("s_waitcnt vmcnt(0)" ::: "memory");
;             if ((threadIdx.x & 63) == 0) __hip_atomic_fetch_add(flags + P7_FLAG(u.tag - 1000), 1u, __ATOMIC_RELAXED, __HIP_MEMORY_SCOPE_AGENT);
;         }
	v_lshlrev_b32_e32 v104, 16, v64
	v_and_b32_e32 v64, 0xffff0000, v64
	v_lshlrev_b32_e32 v105, 16, v65
	v_and_b32_e32 v65, 0xffff0000, v65
	v_lshlrev_b32_e32 v106, 16, v66
	v_and_b32_e32 v66, 0xffff0000, v66
	v_lshlrev_b32_e32 v107, 16, v67
	v_and_b32_e32 v67, 0xffff0000, v67
	v_mul_f32_e32 v60, v60, v104
	v_mul_f32_e32 v61, v61, v64
	v_mul_f32_e32 v63, v63, v65
	v_mul_f32_e32 v64, v56, v106
	v_mul_f32_e32 v65, v57, v66
	v_mul_f32_e32 v59, v59, v67
	v_cvt_pk_bf16_f32 v56, v60, v61
	v_lshl_add_u64 v[60:61], s[44:45], 0, v[96:97]
	v_mul_f32_e32 v62, v62, v105
	v_mul_f32_e32 v66, v58, v107
	v_cvt_pk_bf16_f32 v57, v62, v63
	v_cvt_pk_bf16_f32 v58, v64, v65
	v_cvt_pk_bf16_f32 v59, v66, v59
	v_lshl_add_u64 v[60:61], v[60:61], 0, v[140:141]
	v_and_b32_e32 v65, 0xffff0000, v71
	global_store_dwordx4 v[60:61], v[56:59], off
	v_lshlrev_b32_e32 v62, 16, v70
	v_and_b32_e32 v63, 0xffff0000, v70
	v_lshlrev_b32_e32 v56, 16, v68
	v_and_b32_e32 v57, 0xffff0000, v68
	v_lshlrev_b32_e32 v58, 16, v69
	v_and_b32_e32 v59, 0xffff0000, v69
	v_lshlrev_b32_e32 v64, 16, v71
	v_mul_f32_e32 v47, v47, v65
	v_mul_f32_e32 v52, v52, v56
	v_mul_f32_e32 v53, v53, v57
	v_mul_f32_e32 v54, v54, v58
	v_mul_f32_e32 v55, v55, v59
	v_mul_f32_e32 v56, v44, v62
	v_mul_f32_e32 v57, v45, v63
	v_mul_f32_e32 v58, v46, v64
	v_cvt_pk_bf16_f32 v44, v52, v53
	v_cvt_pk_bf16_f32 v45, v54, v55
	v_cvt_pk_bf16_f32 v47, v58, v47
	v_cvt_pk_bf16_f32 v46, v56, v57
	global_store_dwordx4 v[60:61], v[44:47], off offset:256
	v_and_b32_e32 v53, 0xffff0000, v73
	v_and_b32_e32 v57, 0xffff0000, v75
	v_lshlrev_b64 v[44:45], 12, v[98:99]
	v_and_b32_e32 v47, 0xffff0000, v72
	v_lshlrev_b32_e32 v46, 16, v72
	v_lshlrev_b32_e32 v52, 16, v73
	v_lshlrev_b32_e32 v54, 16, v74
	v_and_b32_e32 v55, 0xffff0000, v74
	v_lshlrev_b32_e32 v56, 16, v75
	v_mul_f32_e32 v47, v49, v47
	v_mul_f32_e32 v49, v51, v53
	v_mul_f32_e32 v43, v43, v57
	v_lshl_add_u64 v[44:45], s[44:45], 0, v[44:45]
	v_mul_f32_e32 v46, v48, v46
	v_mul_f32_e32 v48, v50, v52
	v_mul_f32_e32 v50, v40, v54
	v_mul_f32_e32 v51, v41, v55
	v_mul_f32_e32 v52, v42, v56
	v_cvt_pk_bf16_f32 v40, v46, v47
	v_cvt_pk_bf16_f32 v41, v48, v49
	v_cvt_pk_bf16_f32 v42, v50, v51
	v_cvt_pk_bf16_f32 v43, v52, v43
	v_lshl_add_u64 v[44:45], v[44:45], 0, v[140:141]
	v_and_b32_e32 v49, 0xffff0000, v79
	global_store_dwordx4 v[44:45], v[40:43], off
	v_lshlrev_b32_e32 v46, 16, v78
	v_and_b32_e32 v47, 0xffff0000, v78
	v_lshlrev_b32_e32 v40, 16, v76
	v_and_b32_e32 v41, 0xffff0000, v76
	v_lshlrev_b32_e32 v42, 16, v77
	v_and_b32_e32 v43, 0xffff0000, v77
	v_lshlrev_b32_e32 v48, 16, v79
	v_mul_f32_e32 v31, v31, v49
	v_mul_f32_e32 v36, v36, v40
	v_mul_f32_e32 v37, v37, v41
	v_mul_f32_e32 v38, v38, v42
	v_mul_f32_e32 v39, v39, v43
	v_mul_f32_e32 v40, v28, v46
	v_mul_f32_e32 v41, v29, v47
	v_mul_f32_e32 v42, v30, v48
	v_cvt_pk_bf16_f32 v28, v36, v37
	v_cvt_pk_bf16_f32 v29, v38, v39
	v_cvt_pk_bf16_f32 v31, v42, v31
	v_cvt_pk_bf16_f32 v30, v40, v41
	global_store_dwordx4 v[44:45], v[28:31], off offset:256
	v_and_b32_e32 v37, 0xffff0000, v81
	v_and_b32_e32 v41, 0xffff0000, v83
	v_lshlrev_b64 v[28:29], 12, v[100:101]
	v_and_b32_e32 v31, 0xffff0000, v80
	v_lshlrev_b32_e32 v30, 16, v80
	v_lshlrev_b32_e32 v36, 16, v81
	v_lshlrev_b32_e32 v38, 16, v82
	v_and_b32_e32 v39, 0xffff0000, v82
	v_lshlrev_b32_e32 v40, 16, v83
	v_mul_f32_e32 v31, v33, v31
	v_mul_f32_e32 v33, v35, v37
	v_mul_f32_e32 v27, v27, v41
	v_lshl_add_u64 v[28:29], s[44:45], 0, v[28:29]
	v_mul_f32_e32 v30, v32, v30
	v_mul_f32_e32 v32, v34, v36
	v_mul_f32_e32 v34, v24, v38
	v_mul_f32_e32 v35, v25, v39
	v_mul_f32_e32 v36, v26, v40
	v_cvt_pk_bf16_f32 v24, v30, v31
	v_cvt_pk_bf16_f32 v25, v32, v33
	v_cvt_pk_bf16_f32 v26, v34, v35
	v_cvt_pk_bf16_f32 v27, v36, v27
	v_lshl_add_u64 v[28:29], v[28:29], 0, v[140:141]
	v_and_b32_e32 v33, 0xffff0000, v87
	global_store_dwordx4 v[28:29], v[24:27], off
	v_lshlrev_b32_e32 v30, 16, v86
	v_and_b32_e32 v31, 0xffff0000, v86
	v_lshlrev_b32_e32 v24, 16, v84
	v_and_b32_e32 v25, 0xffff0000, v84
	v_lshlrev_b32_e32 v26, 16, v85
	v_and_b32_e32 v27, 0xffff0000, v85
	v_lshlrev_b32_e32 v32, 16, v87
	v_mul_f32_e32 v15, v15, v33
	v_mul_f32_e32 v20, v20, v24
	v_mul_f32_e32 v21, v21, v25
	v_mul_f32_e32 v22, v22, v26
	v_mul_f32_e32 v23, v23, v27
	v_mul_f32_e32 v24, v12, v30
	v_mul_f32_e32 v25, v13, v31
	v_mul_f32_e32 v26, v14, v32
	v_cvt_pk_bf16_f32 v12, v20, v21
	v_cvt_pk_bf16_f32 v13, v22, v23
	v_cvt_pk_bf16_f32 v15, v26, v15
	v_cvt_pk_bf16_f32 v14, v24, v25
	global_store_dwordx4 v[28:29], v[12:15], off offset:256
	v_and_b32_e32 v21, 0xffff0000, v89
	v_and_b32_e32 v25, 0xffff0000, v91
	v_lshlrev_b64 v[12:13], 12, v[102:103]
	v_and_b32_e32 v15, 0xffff0000, v88
	v_lshlrev_b32_e32 v14, 16, v88
	v_lshlrev_b32_e32 v20, 16, v89
	v_lshlrev_b32_e32 v22, 16, v90
	v_and_b32_e32 v23, 0xffff0000, v90
	v_lshlrev_b32_e32 v24, 16, v91
	v_mul_f32_e32 v15, v17, v15
	v_mul_f32_e32 v17, v19, v21
	v_mul_f32_e32 v11, v11, v25
	v_lshl_add_u64 v[12:13], s[44:45], 0, v[12:13]
	v_mul_f32_e32 v14, v16, v14
	v_mul_f32_e32 v16, v18, v20
	v_mul_f32_e32 v18, v8, v22
	v_mul_f32_e32 v19, v9, v23
	v_mul_f32_e32 v20, v10, v24
	v_cvt_pk_bf16_f32 v8, v14, v15
	v_cvt_pk_bf16_f32 v9, v16, v17
	v_cvt_pk_bf16_f32 v10, v18, v19
	v_cvt_pk_bf16_f32 v11, v20, v11
	v_lshl_add_u64 v[12:13], v[12:13], 0, v[140:141]
	v_and_b32_e32 v17, 0xffff0000, v95
	global_store_dwordx4 v[12:13], v[8:11], off
	v_lshlrev_b32_e32 v14, 16, v94
	v_and_b32_e32 v15, 0xffff0000, v94
	v_lshlrev_b32_e32 v8, 16, v92
	v_and_b32_e32 v9, 0xffff0000, v92
	v_lshlrev_b32_e32 v10, 16, v93
	v_and_b32_e32 v11, 0xffff0000, v93
	v_lshlrev_b32_e32 v16, 16, v95
	v_mul_f32_e32 v3, v3, v17
	v_mul_f32_e32 v4, v4, v8
	v_mul_f32_e32 v5, v5, v9
	v_mul_f32_e32 v6, v6, v10
	v_mul_f32_e32 v7, v7, v11
	v_mul_f32_e32 v8, v0, v14
	v_mul_f32_e32 v9, v1, v15
	v_mul_f32_e32 v10, v2, v16
	v_cvt_pk_bf16_f32 v0, v4, v5
	v_cvt_pk_bf16_f32 v1, v6, v7
	v_cvt_pk_bf16_f32 v2, v8, v9
	v_cvt_pk_bf16_f32 v3, v10, v3
	global_store_dwordx4 v[12:13], v[0:3], off offset:256
	s_branch .LBB0_941
	s_waitcnt vmcnt(0)
	buffer_wbl2 sc1
	s_waitcnt vmcnt(0) lgkmcnt(0)
	s_waitcnt vmcnt(0)
	s_and_saveexec_b64 s[0:1], s[6:7]
	s_cbranch_execz .LBB0_940
	s_mov_b64 s[52:53], exec
	v_mbcnt_lo_u32_b32 v0, s52, 0
	v_mbcnt_hi_u32_b32 v0, s53, v0
	v_cmp_eq_u32_e32 vcc, 0, v0
	s_and_b64 s[42:43], exec, vcc
	s_mov_b64 exec, s[42:43]
	s_cbranch_execz .LBB0_940
	s_lshl_b32 s8, s70, 6
	s_lshl_b64 s[42:43], s[8:9], 2
	v_readlane_b32 s56, v255, 1
	v_readlane_b32 s57, v255, 2
	s_add_u32 s8, s56, s42
	s_addc_u32 s33, s57, s43
	s_add_u32 s42, s8, 0xfffc4e00
	s_addc_u32 s43, s33, -1
	s_bcnt1_i32_b64 s8, s[52:53]
	v_mov_b32_e32 v0, s8
	global_atomic_add v131, v0, s[42:43]
	s_branch .LBB0_940

; template <class Epi, class S_t>
; __device__ __forceinline__ void gemm_phase(LAS unsigned char* lds, int lda, int ldb, const S_t& S, const Epi& E) {
;     ...
;     for (;;) {
;         const bool has_next = S.next(ui + 1, nxt);
;         const char* nA = has_next ? nxt.A : cA; const char* nB = has_next ? nxt.B : cB;
;         const int nt = cur.nt;
;         for (int t = 0; t < nt; t += 2) {
;             const bool last = (t == nt - 2);
;             const char* a1 = cA + (size_t)(t + 1) * kstep;
;             const char* a2 = last ? nA : cA + (size_t)(t + 2) * kstep; const char* b2 = last ? nB : cB + (size_t)(t + 2) * kstep;
;             const char* a3 = a2 + kstep; const char* b3 = b2 + kstep;
;     ...
; #pragma unroll
;         for (int a = 0; a < 2; ++a)
; #pragma unroll
;             for (int b = 0; b < 2; ++b)
; #pragma unroll
;                 for (int m = 0; m < 4; ++m)
; #pragma unroll
;                     for (int n = 0; n < 2; ++n) acc[a][b][m][n] = (f32x4){0.f, 0.f, 0.f, 0.f};
;         cur = nxt; cA = nA; cB = nB; ++ui;
.LBB0_965:
	s_add_u32 s56, s56, 0x80080
	s_addc_u32 s57, s57, 0
	s_add_u32 s0, s58, 0x100
	s_addc_u32 s1, s59, 0
	s_mov_b32 s43, -2
	v_mov_b64_e32 v[0:1], 0
	v_mov_b64_e32 v[2:3], 0
	v_mov_b64_e32 v[4:5], 0
	v_mov_b64_e32 v[6:7], 0
	v_mov_b64_e32 v[8:9], 0
	v_mov_b64_e32 v[10:11], 0
	v_mov_b64_e32 v[12:13], 0
	v_mov_b64_e32 v[14:15], 0
	v_mov_b64_e32 v[16:17], 0
	v_mov_b64_e32 v[18:19], 0
	v_mov_b64_e32 v[20:21], 0
	v_mov_b64_e32 v[22:23], 0
	v_mov_b64_e32 v[24:25], 0
	v_mov_b64_e32 v[26:27], 0
	v_mov_b64_e32 v[28:29], 0
	v_mov_b64_e32 v[30:31], 0
	v_mov_b64_e32 v[32:33], 0
	v_mov_b64_e32 v[34:35], 0
	v_mov_b64_e32 v[36:37], 0
	v_mov_b64_e32 v[38:39], 0
	v_mov_b64_e32 v[40:41], 0
	v_mov_b64_e32 v[42:43], 0
	v_mov_b64_e32 v[44:45], 0
	v_mov_b64_e32 v[46:47], 0
	v_mov_b64_e32 v[48:49], 0
	v_mov_b64_e32 v[50:51], 0
	v_mov_b64_e32 v[52:53], 0
	v_mov_b64_e32 v[54:55], 0
	v_mov_b64_e32 v[56:57], 0
	v_mov_b64_e32 v[58:59], 0
	v_mov_b64_e32 v[60:61], 0
	v_mov_b64_e32 v[62:63], 0
	v_mov_b64_e32 v[64:65], 0
	v_mov_b64_e32 v[66:67], 0
	v_mov_b64_e32 v[68:69], 0
	v_mov_b64_e32 v[70:71], 0
	v_mov_b64_e32 v[72:73], 0
	v_mov_b64_e32 v[74:75], 0
	v_mov_b64_e32 v[76:77], 0
	v_mov_b64_e32 v[78:79], 0
	v_mov_b64_e32 v[80:81], 0
	v_mov_b64_e32 v[82:83], 0
	v_mov_b64_e32 v[84:85], 0
	v_mov_b64_e32 v[86:87], 0
	v_mov_b64_e32 v[88:89], 0
	v_mov_b64_e32 v[90:91], 0
	v_mov_b64_e32 v[92:93], 0
	v_mov_b64_e32 v[94:95], 0
	v_mov_b64_e32 v[96:97], 0
	v_mov_b64_e32 v[98:99], 0
	v_mov_b64_e32 v[100:101], 0
	v_mov_b64_e32 v[102:103], 0
	v_mov_b64_e32 v[104:105], 0
	v_mov_b64_e32 v[106:107], 0
	v_mov_b64_e32 v[108:109], 0
	v_mov_b64_e32 v[110:111], 0
	v_mov_b64_e32 v[112:113], 0
	v_mov_b64_e32 v[114:115], 0
	v_mov_b64_e32 v[116:117], 0
	v_mov_b64_e32 v[118:119], 0
	v_mov_b64_e32 v[120:121], 0
	v_mov_b64_e32 v[122:123], 0
	v_mov_b64_e32 v[124:125], 0
	v_mov_b64_e32 v[126:127], 0
	s_branch .LBB0_966

; #define PG8_STAGE(bufoff, gbase, voff) do { _Pragma("unroll") for (int _i = 0; _i < 2; ++_i) \
;         __builtin_amdgcn_global_load_lds((const unsigned*)((const char*)(gbase) + (voff)[_i]), (LAS unsigned*)(lds + (bufoff) + ldsw + _i * 8192), 16, 0, 0); } while (0)
; #define PG8_LDA(dst, b, h) do { _Pragma("unroll") for (int m = 0; m < 4; ++m) _Pragma("unroll") for (int k = 0; k < 2; ++k) dst[m][k] = *(const LAS bf16x8*)(lds + PG8_SA(b, h) + aoff + m * 2048 + k * 1024); } while (0)
; #define PG8_LDB(dst, b, h) do { _Pragma("unroll") for (int n = 0; n < 2; ++n) _Pragma("unroll") for (int k = 0; k < 2; ++k) dst[n][k] = *(const LAS bf16x8*)(lds + PG8_SB(b, h) + boff + n * 2048 + k * 1024); } while (0)
; #define PG8_MMA(ai, bj, At, Bt) do { __builtin_amdgcn_s_setprio(1); _Pragma("unroll") for (int m = 0; m < 4; ++m) _Pragma("unroll") for (int n = 0; n < 2; ++n) _Pragma("unroll") for (int k = 0; k < 2; ++k) \
;         acc[ai][bj][m][n] = __builtin_amdgcn_mfma_f32_16x16x32_bf16(Bt[n][k], At[m][k], acc[ai][bj][m][n], 0, 0, 0); __builtin_amdgcn_s_setprio(0); } while (0)
; #define PG8_WAIT_V(n) asm volatile("s_waitcnt vmcnt(" #n ")" ::: "memory")
; #define PG8_WAIT_L(n) asm volatile("s_waitcnt lgkmcnt(" #n ")" ::: "memory")
; #define PG8_BAR __builtin_amdgcn_s_barrier()
; #define PG8_SCHED __builtin_amdgcn_sched_barrier(0)
; template <class Epi, class S_t>
; __device__ __forceinline__ void gemm_phase(LAS unsigned char* lds, int lda, int ldb, const S_t& S, const Epi& E) {
;     ...
;             PG8_LDB(B0, 0, 0); PG8_SCHED; PG8_LDA(At, 0, 0); PG8_STAGE(PG8_SA(1, 1), a1 + hstepA, voffA);
;             PG8_WAIT_L(8); PG8_BAR; PG8_WAIT_L(0); PG8_MMA(0, 0, At, B0); PG8_BAR; PG8_SCHED;
;             PG8_LDB(B1, 0, 1); PG8_STAGE(PG8_SB(0, 0), b2, voffB);
;             PG8_BAR; PG8_WAIT_L(0); PG8_MMA(0, 1, At, B1); PG8_BAR;
;             PG8_LDA(At, 0, 1); PG8_STAGE(PG8_SA(0, 0), a2, voffA);
;             PG8_BAR; PG8_WAIT_L(0); PG8_MMA(1, 0, At, B0); PG8_BAR; PG8_SCHED;
;             PG8_STAGE(PG8_SB(0, 1), b2 + hstepB, voffB);
;             PG8_WAIT_V(6); PG8_BAR; PG8_MMA(1, 1, At, B1); PG8_BAR;
.LBB0_966:
	ds_read_b128 v[128:131], v169
	ds_read_b128 v[132:135], v169 offset:1024
	ds_read_b128 v[136:139], v169 offset:2048
	ds_read_b128 v[140:143], v169 offset:3072
	s_add_u32 s33, s56, 0xfff80080
	s_addc_u32 s58, s57, -1
	s_cmp_eq_u32 s43, 28
	s_cselect_b32 s61, s55, s58
	s_cselect_b32 s60, s54, s33
	s_cselect_b32 s59, s49, s1
	s_cselect_b32 s58, s48, s0
	s_add_i32 m0, s16, 0xc000
	ds_read_b128 v[156:159], v170
	ds_read_b128 v[160:163], v170 offset:1024
	ds_read_b128 v[172:175], v170 offset:2048
	ds_read_b128 v[176:179], v170 offset:3072
	ds_read_b128 v[180:183], v170 offset:4096
	ds_read_b128 v[186:189], v170 offset:5120
	ds_read_b128 v[190:193], v170 offset:6144
	ds_read_b128 v[194:197], v170 offset:7168
	global_load_lds_dwordx4 v152, s[56:57]
	s_add_i32 m0, s16, 0xe000
	s_nop 0
	global_load_lds_dwordx4 v154, s[56:57]
	s_waitcnt lgkmcnt(8)
	s_barrier
	s_waitcnt lgkmcnt(0)
	s_setprio 1
	v_mfma_f32_16x16x32_bf16 v[124:127], v[128:131], v[156:159], v[124:127]
	v_mfma_f32_16x16x32_bf16 v[120:123], v[136:139], v[156:159], v[120:123]
	v_mfma_f32_16x16x32_bf16 v[108:111], v[128:131], v[172:175], v[108:111]
	v_mfma_f32_16x16x32_bf16 v[104:107], v[136:139], v[172:175], v[104:107]
	v_mfma_f32_16x16x32_bf16 v[92:95], v[128:131], v[180:183], v[92:95]
	v_mfma_f32_16x16x32_bf16 v[88:91], v[136:139], v[180:183], v[88:91]
	v_mfma_f32_16x16x32_bf16 v[76:79], v[128:131], v[190:193], v[76:79]
	v_mfma_f32_16x16x32_bf16 v[72:75], v[136:139], v[190:193], v[72:75]
	v_mfma_f32_16x16x32_bf16 v[124:127], v[132:135], v[160:163], v[124:127]
	v_mfma_f32_16x16x32_bf16 v[120:123], v[140:143], v[160:163], v[120:123]
	v_mfma_f32_16x16x32_bf16 v[108:111], v[132:135], v[176:179], v[108:111]
	v_mfma_f32_16x16x32_bf16 v[104:107], v[140:143], v[176:179], v[104:107]
	v_mfma_f32_16x16x32_bf16 v[92:95], v[132:135], v[186:189], v[92:95]
	v_mfma_f32_16x16x32_bf16 v[88:91], v[140:143], v[186:189], v[88:91]
	v_mfma_f32_16x16x32_bf16 v[76:79], v[132:135], v[194:197], v[76:79]
	v_mfma_f32_16x16x32_bf16 v[72:75], v[140:143], v[194:197], v[72:75]
	s_setprio 0
	s_barrier
	s_add_i32 s33, s88, s5
	s_add_u32 s98, s58, s8
	s_addc_u32 s99, s59, s9
	s_mov_b32 m0, s33
	ds_read_b128 v[198:201], v171
	ds_read_b128 v[202:205], v171 offset:1024
	ds_read_b128 v[206:209], v171 offset:2048
	ds_read_b128 v[222:225], v171 offset:3072
	global_load_lds_dwordx4 v146, s[58:59]
	s_add_i32 m0, s33, 0x2000
	s_nop 0
	global_load_lds_dwordx4 v150, s[58:59]
	s_barrier
	s_waitcnt lgkmcnt(0)
	s_setprio 1
	v_mfma_f32_16x16x32_bf16 v[116:119], v[198:201], v[156:159], v[116:119]
	v_mfma_f32_16x16x32_bf16 v[112:115], v[206:209], v[156:159], v[112:115]
	v_mfma_f32_16x16x32_bf16 v[100:103], v[198:201], v[172:175], v[100:103]
	v_mfma_f32_16x16x32_bf16 v[96:99], v[206:209], v[172:175], v[96:99]
	v_mfma_f32_16x16x32_bf16 v[84:87], v[198:201], v[180:183], v[84:87]
	v_mfma_f32_16x16x32_bf16 v[80:83], v[206:209], v[180:183], v[80:83]
	v_mfma_f32_16x16x32_bf16 v[68:71], v[198:201], v[190:193], v[68:71]
	v_mfma_f32_16x16x32_bf16 v[64:67], v[206:209], v[190:193], v[64:67]
	v_mfma_f32_16x16x32_bf16 v[116:119], v[202:205], v[160:163], v[116:119]
	v_mfma_f32_16x16x32_bf16 v[112:115], v[222:225], v[160:163], v[112:115]
	v_mfma_f32_16x16x32_bf16 v[100:103], v[202:205], v[176:179], v[100:103]
	v_mfma_f32_16x16x32_bf16 v[96:99], v[222:225], v[176:179], v[96:99]
	v_mfma_f32_16x16x32_bf16 v[84:87], v[202:205], v[186:189], v[84:87]
	v_mfma_f32_16x16x32_bf16 v[80:83], v[222:225], v[186:189], v[80:83]
	v_mfma_f32_16x16x32_bf16 v[68:71], v[202:205], v[194:197], v[68:71]
	v_mfma_f32_16x16x32_bf16 v[64:67], v[222:225], v[194:197], v[64:67]
	s_setprio 0
	s_mov_b32 m0, s16
	s_add_u32 s100, s60, s8
	s_addc_u32 s101, s61, s9
	s_barrier
	ds_read_b128 v[156:159], v170 offset:16384
	ds_read_b128 v[160:163], v170 offset:17408
	ds_read_b128 v[172:175], v170 offset:18432
	ds_read_b128 v[176:179], v170 offset:19456
	ds_read_b128 v[180:183], v170 offset:20480
	ds_read_b128 v[186:189], v170 offset:21504
	ds_read_b128 v[190:193], v170 offset:22528
	ds_read_b128 v[194:197], v170 offset:23552
	global_load_lds_dwordx4 v144, s[60:61]
	s_mov_b32 m0, s17
	s_nop 0
	global_load_lds_dwordx4 v148, s[60:61]
	s_barrier
	s_waitcnt lgkmcnt(0)
	s_setprio 1
	v_mfma_f32_16x16x32_bf16 v[60:63], v[128:131], v[156:159], v[60:63]
	v_mfma_f32_16x16x32_bf16 v[56:59], v[136:139], v[156:159], v[56:59]
	v_mfma_f32_16x16x32_bf16 v[44:47], v[128:131], v[172:175], v[44:47]
	v_mfma_f32_16x16x32_bf16 v[40:43], v[136:139], v[172:175], v[40:43]
	v_mfma_f32_16x16x32_bf16 v[28:31], v[128:131], v[180:183], v[28:31]
	v_mfma_f32_16x16x32_bf16 v[24:27], v[136:139], v[180:183], v[24:27]
	v_mfma_f32_16x16x32_bf16 v[12:15], v[128:131], v[190:193], v[12:15]
	v_mfma_f32_16x16x32_bf16 v[8:11], v[136:139], v[190:193], v[8:11]
	v_mfma_f32_16x16x32_bf16 v[60:63], v[132:135], v[160:163], v[60:63]
	v_mfma_f32_16x16x32_bf16 v[56:59], v[140:143], v[160:163], v[56:59]
	v_mfma_f32_16x16x32_bf16 v[44:47], v[132:135], v[176:179], v[44:47]
	v_mfma_f32_16x16x32_bf16 v[40:43], v[140:143], v[176:179], v[40:43]
	v_mfma_f32_16x16x32_bf16 v[28:31], v[132:135], v[186:189], v[28:31]
	v_mfma_f32_16x16x32_bf16 v[24:27], v[140:143], v[186:189], v[24:27]
	v_mfma_f32_16x16x32_bf16 v[12:15], v[132:135], v[194:197], v[12:15]
	v_mfma_f32_16x16x32_bf16 v[8:11], v[140:143], v[194:197], v[8:11]
	s_setprio 0
	s_barrier
	s_add_u32 s64, s58, 0x80000
	s_addc_u32 s65, s59, 0
	s_add_i32 s33, s89, s5
	s_mov_b32 m0, s33
	s_nop 0
	global_load_lds_dwordx4 v146, s[64:65]
	s_add_i32 m0, s33, 0x2000
	s_nop 0
	global_load_lds_dwordx4 v150, s[64:65]
	s_waitcnt vmcnt(6)
	s_barrier
; #define PG8_STAGE(bufoff, gbase, voff) do { _Pragma("unroll") for (int _i = 0; _i < 2; ++_i) \
;         __builtin_amdgcn_global_load_lds((const unsigned*)((const char*)(gbase) + (voff)[_i]), (LAS unsigned*)(lds + (bufoff) + ldsw + _i * 8192), 16, 0, 0); } while (0)
; #define PG8_LDA(dst, b, h) do { _Pragma("unroll") for (int m = 0; m < 4; ++m) _Pragma("unroll") for (int k = 0; k < 2; ++k) dst[m][k] = *(const LAS bf16x8*)(lds + PG8_SA(b, h) + aoff + m * 2048 + k * 1024); } while (0)
; #define PG8_LDB(dst, b, h) do { _Pragma("unroll") for (int n = 0; n < 2; ++n) _Pragma("unroll") for (int k = 0; k < 2; ++k) dst[n][k] = *(const LAS bf16x8*)(lds + PG8_SB(b, h) + boff + n * 2048 + k * 1024); } while (0)
; #define PG8_MMA(ai, bj, At, Bt) do { __builtin_amdgcn_s_setprio(1); _Pragma("unroll") for (int m = 0; m < 4; ++m) _Pragma("unroll") for (int n = 0; n < 2; ++n) _Pragma("unroll") for (int k = 0; k < 2; ++k) \
;         acc[ai][bj][m][n] = __builtin_amdgcn_mfma_f32_16x16x32_bf16(Bt[n][k], At[m][k], acc[ai][bj][m][n], 0, 0, 0); __builtin_amdgcn_s_setprio(0); } while (0)
; #define PG8_WAIT_V(n) asm volatile("s_waitcnt vmcnt(" #n ")" ::: "memory")
; #define PG8_WAIT_L(n) asm volatile("s_waitcnt lgkmcnt(" #n ")" ::: "memory")
; #define PG8_BAR __builtin_amdgcn_s_barrier()
; #define PG8_SCHED __builtin_amdgcn_sched_barrier(0)
; template <class Epi, class S_t>
; __device__ __forceinline__ void gemm_phase(LAS unsigned char* lds, int lda, int ldb, const S_t& S, const Epi& E) {
;     ...
;             PG8_WAIT_V(6); PG8_BAR; PG8_MMA(1, 1, At, B1); PG8_BAR;
;             PG8_LDB(B0, 1, 0); PG8_SCHED; PG8_LDA(At, 1, 0); PG8_STAGE(PG8_SA(0, 1), a2 + hstepA, voffA);
;             PG8_WAIT_L(8); PG8_BAR; PG8_WAIT_L(0); PG8_MMA(0, 0, At, B0); PG8_BAR; PG8_SCHED;
;             PG8_LDB(B1, 1, 1); PG8_STAGE(PG8_SB(1, 0), b3, voffB);
;             PG8_BAR; PG8_WAIT_L(0); PG8_MMA(0, 1, At, B1); PG8_BAR;
;             PG8_LDA(At, 1, 1); PG8_STAGE(PG8_SA(1, 0), a3, voffA);
;             PG8_BAR; PG8_WAIT_L(0); PG8_MMA(1, 0, At, B0); PG8_BAR; PG8_SCHED;
	s_setprio 1
	v_mfma_f32_16x16x32_bf16 v[52:55], v[198:201], v[156:159], v[52:55]
	v_mfma_f32_16x16x32_bf16 v[48:51], v[206:209], v[156:159], v[48:51]
	v_mfma_f32_16x16x32_bf16 v[36:39], v[198:201], v[172:175], v[36:39]
	v_mfma_f32_16x16x32_bf16 v[32:35], v[206:209], v[172:175], v[32:35]
	v_mfma_f32_16x16x32_bf16 v[20:23], v[198:201], v[180:183], v[20:23]
	v_mfma_f32_16x16x32_bf16 v[16:19], v[206:209], v[180:183], v[16:19]
	v_mfma_f32_16x16x32_bf16 v[4:7], v[198:201], v[190:193], v[4:7]
	v_mfma_f32_16x16x32_bf16 v[0:3], v[206:209], v[190:193], v[0:3]
	v_mfma_f32_16x16x32_bf16 v[52:55], v[202:205], v[160:163], v[52:55]
	v_mfma_f32_16x16x32_bf16 v[48:51], v[222:225], v[160:163], v[48:51]
	v_mfma_f32_16x16x32_bf16 v[36:39], v[202:205], v[176:179], v[36:39]
	v_mfma_f32_16x16x32_bf16 v[32:35], v[222:225], v[176:179], v[32:35]
	v_mfma_f32_16x16x32_bf16 v[20:23], v[202:205], v[186:189], v[20:23]
	v_mfma_f32_16x16x32_bf16 v[16:19], v[222:225], v[186:189], v[16:19]
	v_mfma_f32_16x16x32_bf16 v[4:7], v[202:205], v[194:197], v[4:7]
	v_mfma_f32_16x16x32_bf16 v[0:3], v[222:225], v[194:197], v[0:3]
	s_setprio 0
	v_add_u32_e32 v140, s90, v167
	s_barrier
	ds_read_b128 v[128:131], v140
	ds_read_b128 v[132:135], v140 offset:1024
	ds_read_b128 v[136:139], v140 offset:2048
	ds_read_b128 v[140:143], v140 offset:3072
	s_add_u32 s60, s60, 0x80000
	s_addc_u32 s61, s61, 0
	s_mov_b32 m0, s20
	ds_read_b128 v[156:159], v170 offset:32768
	ds_read_b128 v[160:163], v170 offset:33792
	ds_read_b128 v[172:175], v170 offset:34816
	ds_read_b128 v[176:179], v170 offset:35840
	ds_read_b128 v[180:183], v170 offset:36864
	ds_read_b128 v[186:189], v170 offset:37888
	ds_read_b128 v[190:193], v170 offset:38912
	ds_read_b128 v[194:197], v170 offset:39936
	global_load_lds_dwordx4 v144, s[60:61]
	s_mov_b32 m0, s21
	s_nop 0
	global_load_lds_dwordx4 v148, s[60:61]
	s_waitcnt lgkmcnt(8)
	s_barrier
	s_waitcnt lgkmcnt(0)
	s_setprio 1
	v_mfma_f32_16x16x32_bf16 v[124:127], v[128:131], v[156:159], v[124:127]
	v_mfma_f32_16x16x32_bf16 v[120:123], v[136:139], v[156:159], v[120:123]
	v_mfma_f32_16x16x32_bf16 v[108:111], v[128:131], v[172:175], v[108:111]
	v_mfma_f32_16x16x32_bf16 v[104:107], v[136:139], v[172:175], v[104:107]
	v_mfma_f32_16x16x32_bf16 v[92:95], v[128:131], v[180:183], v[92:95]
	v_mfma_f32_16x16x32_bf16 v[88:91], v[136:139], v[180:183], v[88:91]
	v_mfma_f32_16x16x32_bf16 v[76:79], v[128:131], v[190:193], v[76:79]
	v_mfma_f32_16x16x32_bf16 v[72:75], v[136:139], v[190:193], v[72:75]
	v_mfma_f32_16x16x32_bf16 v[124:127], v[132:135], v[160:163], v[124:127]
	v_mfma_f32_16x16x32_bf16 v[120:123], v[140:143], v[160:163], v[120:123]
	v_mfma_f32_16x16x32_bf16 v[108:111], v[132:135], v[176:179], v[108:111]
	v_mfma_f32_16x16x32_bf16 v[104:107], v[140:143], v[176:179], v[104:107]
	v_mfma_f32_16x16x32_bf16 v[92:95], v[132:135], v[186:189], v[92:95]
	v_mfma_f32_16x16x32_bf16 v[88:91], v[140:143], v[186:189], v[88:91]
	v_mfma_f32_16x16x32_bf16 v[76:79], v[132:135], v[194:197], v[76:79]
	v_mfma_f32_16x16x32_bf16 v[72:75], v[140:143], v[194:197], v[72:75]
	s_setprio 0
	s_barrier
	s_add_i32 s33, s90, s5
	v_add_u32_e32 v185, s91, v167
	s_mov_b32 m0, s33
	ds_read_b128 v[198:201], v185
	ds_read_b128 v[202:205], v185 offset:1024
	ds_read_b128 v[206:209], v185 offset:2048
	ds_read_b128 v[222:225], v185 offset:3072
	global_load_lds_dwordx4 v146, s[98:99]
	s_add_i32 m0, s33, 0x2000
	s_nop 0
	global_load_lds_dwordx4 v150, s[98:99]
	s_barrier
; #define PG8_STAGE(bufoff, gbase, voff) do { _Pragma("unroll") for (int _i = 0; _i < 2; ++_i) \
;         __builtin_amdgcn_global_load_lds((const unsigned*)((const char*)(gbase) + (voff)[_i]), (LAS unsigned*)(lds + (bufoff) + ldsw + _i * 8192), 16, 0, 0); } while (0)
; #define PG8_MMA(ai, bj, At, Bt) do { __builtin_amdgcn_s_setprio(1); _Pragma("unroll") for (int m = 0; m < 4; ++m) _Pragma("unroll") for (int n = 0; n < 2; ++n) _Pragma("unroll") for (int k = 0; k < 2; ++k) \
;         acc[ai][bj][m][n] = __builtin_amdgcn_mfma_f32_16x16x32_bf16(Bt[n][k], At[m][k], acc[ai][bj][m][n], 0, 0, 0); __builtin_amdgcn_s_setprio(0); } while (0)
; #define PG8_WAIT_V(n) asm volatile("s_waitcnt vmcnt(" #n ")" ::: "memory")
; #define PG8_WAIT_L(n) asm volatile("s_waitcnt lgkmcnt(" #n ")" ::: "memory")
; #define PG8_BAR __builtin_amdgcn_s_barrier()
; #define PG8_SCHED __builtin_amdgcn_sched_barrier(0)
; template <class Epi, class S_t>
; __device__ __forceinline__ void gemm_phase(LAS unsigned char* lds, int lda, int ldb, const S_t& S, const Epi& E) {
;     ...
;             PG8_BAR; PG8_WAIT_L(0); PG8_MMA(1, 0, At, B0); PG8_BAR; PG8_SCHED;
;             PG8_STAGE(PG8_SB(1, 1), b3 + hstepB, voffB);
;             PG8_WAIT_V(6); PG8_BAR; PG8_MMA(1, 1, At, B1); PG8_BAR;
;     __device__ __forceinline__ void operator()(const f32x4 (&acc)[2][2][4][2], const Unit& u, int wr, int wc, int fr, int fq) const {
;     ...
;         if (ADD && u.tag >= 2000) {
;             unsigned* f = flags + P7_FLAG(u.tag - 2000); unsigned sp = 0;
;             while ((unsigned)__builtin_amdgcn_readfirstlane(__hip_atomic_load(f, __ATOMIC_RELAXED, __HIP_MEMORY_SCOPE_AGENT)) < 8u) { __builtin_amdgcn_s_sleep(2); if (++sp > (1u << 20)) break; }
	s_waitcnt lgkmcnt(0)
	s_setprio 1
	v_mfma_f32_16x16x32_bf16 v[116:119], v[198:201], v[156:159], v[116:119]
	v_mfma_f32_16x16x32_bf16 v[112:115], v[206:209], v[156:159], v[112:115]
	v_mfma_f32_16x16x32_bf16 v[100:103], v[198:201], v[172:175], v[100:103]
	v_mfma_f32_16x16x32_bf16 v[96:99], v[206:209], v[172:175], v[96:99]
	v_mfma_f32_16x16x32_bf16 v[84:87], v[198:201], v[180:183], v[84:87]
	v_mfma_f32_16x16x32_bf16 v[80:83], v[206:209], v[180:183], v[80:83]
	v_mfma_f32_16x16x32_bf16 v[68:71], v[198:201], v[190:193], v[68:71]
	v_mfma_f32_16x16x32_bf16 v[64:67], v[206:209], v[190:193], v[64:67]
	v_mfma_f32_16x16x32_bf16 v[116:119], v[202:205], v[160:163], v[116:119]
	v_mfma_f32_16x16x32_bf16 v[112:115], v[222:225], v[160:163], v[112:115]
	v_mfma_f32_16x16x32_bf16 v[100:103], v[202:205], v[176:179], v[100:103]
	v_mfma_f32_16x16x32_bf16 v[96:99], v[222:225], v[176:179], v[96:99]
	v_mfma_f32_16x16x32_bf16 v[84:87], v[202:205], v[186:189], v[84:87]
	v_mfma_f32_16x16x32_bf16 v[80:83], v[222:225], v[186:189], v[80:83]
	v_mfma_f32_16x16x32_bf16 v[68:71], v[202:205], v[194:197], v[68:71]
	v_mfma_f32_16x16x32_bf16 v[64:67], v[222:225], v[194:197], v[64:67]
	s_setprio 0
	s_mov_b32 m0, s35
	s_barrier
	ds_read_b128 v[156:159], v170 offset:49152
	ds_read_b128 v[160:163], v170 offset:50176
	ds_read_b128 v[172:175], v170 offset:51200
	ds_read_b128 v[176:179], v170 offset:52224
	ds_read_b128 v[180:183], v170 offset:53248
	ds_read_b128 v[186:189], v170 offset:54272
	ds_read_b128 v[190:193], v170 offset:55296
	ds_read_b128 v[194:197], v170 offset:56320
	global_load_lds_dwordx4 v144, s[100:101]
	s_mov_b32 m0, s47
	s_nop 0
	global_load_lds_dwordx4 v148, s[100:101]
	s_barrier
	s_waitcnt lgkmcnt(0)
	s_setprio 1
	v_mfma_f32_16x16x32_bf16 v[60:63], v[128:131], v[156:159], v[60:63]
	v_mfma_f32_16x16x32_bf16 v[56:59], v[136:139], v[156:159], v[56:59]
	v_mfma_f32_16x16x32_bf16 v[44:47], v[128:131], v[172:175], v[44:47]
	v_mfma_f32_16x16x32_bf16 v[40:43], v[136:139], v[172:175], v[40:43]
	v_mfma_f32_16x16x32_bf16 v[28:31], v[128:131], v[180:183], v[28:31]
	v_mfma_f32_16x16x32_bf16 v[24:27], v[136:139], v[180:183], v[24:27]
	v_mfma_f32_16x16x32_bf16 v[12:15], v[128:131], v[190:193], v[12:15]
	v_mfma_f32_16x16x32_bf16 v[8:11], v[136:139], v[190:193], v[8:11]
	v_mfma_f32_16x16x32_bf16 v[60:63], v[132:135], v[160:163], v[60:63]
	v_mfma_f32_16x16x32_bf16 v[56:59], v[140:143], v[160:163], v[56:59]
	v_mfma_f32_16x16x32_bf16 v[44:47], v[132:135], v[176:179], v[44:47]
	v_mfma_f32_16x16x32_bf16 v[40:43], v[140:143], v[176:179], v[40:43]
	v_mfma_f32_16x16x32_bf16 v[28:31], v[132:135], v[186:189], v[28:31]
	v_mfma_f32_16x16x32_bf16 v[24:27], v[140:143], v[186:189], v[24:27]
	v_mfma_f32_16x16x32_bf16 v[12:15], v[132:135], v[194:197], v[12:15]
	v_mfma_f32_16x16x32_bf16 v[8:11], v[140:143], v[194:197], v[8:11]
	s_setprio 0
	s_barrier
	s_add_u32 s58, s58, 0x80080
	s_addc_u32 s59, s59, 0
	s_add_i32 s33, s91, s5
	s_mov_b32 m0, s33
	s_nop 0
	global_load_lds_dwordx4 v146, s[58:59]
	s_add_i32 m0, s33, 0x2000
	s_nop 0
	global_load_lds_dwordx4 v150, s[58:59]
	s_waitcnt vmcnt(6)
	s_barrier
	s_setprio 1
	v_mfma_f32_16x16x32_bf16 v[52:55], v[198:201], v[156:159], v[52:55]
	v_mfma_f32_16x16x32_bf16 v[48:51], v[206:209], v[156:159], v[48:51]
	v_mfma_f32_16x16x32_bf16 v[36:39], v[198:201], v[172:175], v[36:39]
	v_mfma_f32_16x16x32_bf16 v[32:35], v[206:209], v[172:175], v[32:35]
	v_mfma_f32_16x16x32_bf16 v[20:23], v[198:201], v[180:183], v[20:23]
	v_mfma_f32_16x16x32_bf16 v[16:19], v[206:209], v[180:183], v[16:19]
	v_mfma_f32_16x16x32_bf16 v[4:7], v[198:201], v[190:193], v[4:7]
	v_mfma_f32_16x16x32_bf16 v[0:3], v[206:209], v[190:193], v[0:3]
	v_mfma_f32_16x16x32_bf16 v[52:55], v[202:205], v[160:163], v[52:55]
	v_mfma_f32_16x16x32_bf16 v[48:51], v[222:225], v[160:163], v[48:51]
	v_mfma_f32_16x16x32_bf16 v[36:39], v[202:205], v[176:179], v[36:39]
	v_mfma_f32_16x16x32_bf16 v[32:35], v[222:225], v[176:179], v[32:35]
	v_mfma_f32_16x16x32_bf16 v[20:23], v[202:205], v[186:189], v[20:23]
	v_mfma_f32_16x16x32_bf16 v[16:19], v[222:225], v[186:189], v[16:19]
	v_mfma_f32_16x16x32_bf16 v[4:7], v[202:205], v[194:197], v[4:7]
	v_mfma_f32_16x16x32_bf16 v[0:3], v[222:225], v[194:197], v[0:3]
	s_setprio 0
	s_add_i32 s43, s43, 2
	s_add_u32 s56, s56, 0x100
	s_addc_u32 s57, s57, 0
	s_add_u32 s0, s0, 0x100
	s_addc_u32 s1, s1, 0
	s_cmp_gt_u32 s43, 29
	s_cbranch_scc0 .Lrot_966
	s_barrier
	s_sub_i32 s98, s2, 32
	s_cmp_lt_u32 s98, 32
	s_cbranch_scc0 .Lp7x_nowait
	v_readlane_b32 s100, v255, 1
	v_readlane_b32 s101, v255, 2
	s_lshl_b32 s98, s98, 6
	s_addk_i32 s98, 0x1c00
	s_add_u32 s100, s100, s98
	s_addc_u32 s101, s101, 0

; template <class Epi, class S_t>
; __device__ __forceinline__ void gemm_phase(LAS unsigned char* lds, int lda, int ldb, const S_t& S, const Epi& E) {
;     ...
;     for (;;) {
;         const bool has_next = S.next(ui + 1, nxt);
;         const char* nA = has_next ? nxt.A : cA; const char* nB = has_next ? nxt.B : cB;
;         const int nt = cur.nt;
;         for (int t = 0; t < nt; t += 2) {
;             const bool last = (t == nt - 2);
;             const char* a1 = cA + (size_t)(t + 1) * kstep;
;             const char* a2 = last ? nA : cA + (size_t)(t + 2) * kstep; const char* b2 = last ? nB : cB + (size_t)(t + 2) * kstep;
;             const char* a3 = a2 + kstep; const char* b3 = b2 + kstep;
;     ...
; #pragma unroll
;         for (int a = 0; a < 2; ++a)
; #pragma unroll
;             for (int b = 0; b < 2; ++b)
; #pragma unroll
;                 for (int m = 0; m < 4; ++m)
; #pragma unroll
;                     for (int n = 0; n < 2; ++n) acc[a][b][m][n] = (f32x4){0.f, 0.f, 0.f, 0.f};
;         cur = nxt; cA = nA; cB = nB; ++ui;
.LBB0_1050:
	s_add_i32 s0, s42, -2
	s_add_u32 s60, s60, 0x80080
	s_addc_u32 s61, s61, 0
	s_add_u32 s1, s62, 0x100
	s_addc_u32 s69, s63, 0
	s_mov_b32 s62, 0
	v_mov_b64_e32 v[0:1], 0
	v_mov_b64_e32 v[2:3], 0
	v_mov_b64_e32 v[4:5], 0
	v_mov_b64_e32 v[6:7], 0
	v_mov_b64_e32 v[8:9], 0
	v_mov_b64_e32 v[10:11], 0
	v_mov_b64_e32 v[12:13], 0
	v_mov_b64_e32 v[14:15], 0
	v_mov_b64_e32 v[16:17], 0
	v_mov_b64_e32 v[18:19], 0
	v_mov_b64_e32 v[20:21], 0
	v_mov_b64_e32 v[22:23], 0
	v_mov_b64_e32 v[24:25], 0
	v_mov_b64_e32 v[26:27], 0
	v_mov_b64_e32 v[28:29], 0
	v_mov_b64_e32 v[30:31], 0
	v_mov_b64_e32 v[32:33], 0
	v_mov_b64_e32 v[34:35], 0
	v_mov_b64_e32 v[36:37], 0
	v_mov_b64_e32 v[38:39], 0
	v_mov_b64_e32 v[40:41], 0
	v_mov_b64_e32 v[42:43], 0
	v_mov_b64_e32 v[44:45], 0
	v_mov_b64_e32 v[46:47], 0
	v_mov_b64_e32 v[48:49], 0
	v_mov_b64_e32 v[50:51], 0
	v_mov_b64_e32 v[52:53], 0
	v_mov_b64_e32 v[54:55], 0
	v_mov_b64_e32 v[56:57], 0
	v_mov_b64_e32 v[58:59], 0
	v_mov_b64_e32 v[60:61], 0
	v_mov_b64_e32 v[62:63], 0
	v_mov_b64_e32 v[64:65], 0
	v_mov_b64_e32 v[66:67], 0
	v_mov_b64_e32 v[68:69], 0
	v_mov_b64_e32 v[70:71], 0
	v_mov_b64_e32 v[72:73], 0
	v_mov_b64_e32 v[74:75], 0
	v_mov_b64_e32 v[76:77], 0
	v_mov_b64_e32 v[78:79], 0
	v_mov_b64_e32 v[80:81], 0
	v_mov_b64_e32 v[82:83], 0
	v_mov_b64_e32 v[84:85], 0
	v_mov_b64_e32 v[86:87], 0
	v_mov_b64_e32 v[88:89], 0
	v_mov_b64_e32 v[90:91], 0
	v_mov_b64_e32 v[92:93], 0
	v_mov_b64_e32 v[94:95], 0
	v_mov_b64_e32 v[96:97], 0
	v_mov_b64_e32 v[98:99], 0
	v_mov_b64_e32 v[100:101], 0
	v_mov_b64_e32 v[102:103], 0
	v_mov_b64_e32 v[104:105], 0
	v_mov_b64_e32 v[106:107], 0
	v_mov_b64_e32 v[108:109], 0
	v_mov_b64_e32 v[110:111], 0
	v_mov_b64_e32 v[112:113], 0
	v_mov_b64_e32 v[114:115], 0
	v_mov_b64_e32 v[116:117], 0
	v_mov_b64_e32 v[118:119], 0
	v_mov_b64_e32 v[120:121], 0
	v_mov_b64_e32 v[122:123], 0
	v_mov_b64_e32 v[124:125], 0
	v_mov_b64_e32 v[126:127], 0
	s_branch .LBB0_1051

; #define PG8_STAGE(bufoff, gbase, voff) do { _Pragma("unroll") for (int _i = 0; _i < 2; ++_i) \
;         __builtin_amdgcn_global_load_lds((const unsigned*)((const char*)(gbase) + (voff)[_i]), (LAS unsigned*)(lds + (bufoff) + ldsw + _i * 8192), 16, 0, 0); } while (0)
; #define PG8_LDA(dst, b, h) do { _Pragma("unroll") for (int m = 0; m < 4; ++m) _Pragma("unroll") for (int k = 0; k < 2; ++k) dst[m][k] = *(const LAS bf16x8*)(lds + PG8_SA(b, h) + aoff + m * 2048 + k * 1024); } while (0)
; #define PG8_LDB(dst, b, h) do { _Pragma("unroll") for (int n = 0; n < 2; ++n) _Pragma("unroll") for (int k = 0; k < 2; ++k) dst[n][k] = *(const LAS bf16x8*)(lds + PG8_SB(b, h) + boff + n * 2048 + k * 1024); } while (0)
; #define PG8_MMA(ai, bj, At, Bt) do { __builtin_amdgcn_s_setprio(1); _Pragma("unroll") for (int m = 0; m < 4; ++m) _Pragma("unroll") for (int n = 0; n < 2; ++n) _Pragma("unroll") for (int k = 0; k < 2; ++k) \
;         acc[ai][bj][m][n] = __builtin_amdgcn_mfma_f32_16x16x32_bf16(Bt[n][k], At[m][k], acc[ai][bj][m][n], 0, 0, 0); __builtin_amdgcn_s_setprio(0); } while (0)
; #define PG8_WAIT_V(n) asm volatile("s_waitcnt vmcnt(" #n ")" ::: "memory")
; #define PG8_WAIT_L(n) asm volatile("s_waitcnt lgkmcnt(" #n ")" ::: "memory")
; #define PG8_BAR __builtin_amdgcn_s_barrier()
; #define PG8_SCHED __builtin_amdgcn_sched_barrier(0)
; template <class Epi, class S_t>
; __device__ __forceinline__ void gemm_phase(LAS unsigned char* lds, int lda, int ldb, const S_t& S, const Epi& E) {
;     ...
;             PG8_LDB(B0, 0, 0); PG8_SCHED; PG8_LDA(At, 0, 0); PG8_STAGE(PG8_SA(1, 1), a1 + hstepA, voffA);
;             PG8_WAIT_L(8); PG8_BAR; PG8_WAIT_L(0); PG8_MMA(0, 0, At, B0); PG8_BAR; PG8_SCHED;
;             PG8_LDB(B1, 0, 1); PG8_STAGE(PG8_SB(0, 0), b2, voffB);
;             PG8_BAR; PG8_WAIT_L(0); PG8_MMA(0, 1, At, B1); PG8_BAR;
;             PG8_LDA(At, 0, 1); PG8_STAGE(PG8_SA(0, 0), a2, voffA);
;             PG8_BAR; PG8_WAIT_L(0); PG8_MMA(1, 0, At, B0); PG8_BAR; PG8_SCHED;
;             PG8_STAGE(PG8_SB(0, 1), b2 + hstepB, voffB);
;             PG8_WAIT_V(6); PG8_BAR; PG8_MMA(1, 1, At, B1); PG8_BAR;
.LBB0_1051:
	ds_read_b128 v[150:153], v146
	ds_read_b128 v[154:157], v146 offset:1024
	ds_read_b128 v[158:161], v146 offset:2048
	ds_read_b128 v[162:165], v146 offset:3072
	s_add_i32 s70, s62, 2
	s_add_u32 s33, s60, 0xfff80080
	s_addc_u32 s63, s61, -1
	s_cmp_eq_u32 s0, s62
	s_cselect_b32 s62, s56, s1
	s_cselect_b32 s67, s59, s63
	s_cselect_b32 s66, s58, s33
	s_cselect_b32 s63, s57, s69
	s_add_i32 m0, s16, 0xc000
	ds_read_b128 v[166:169], v147
	ds_read_b128 v[170:173], v147 offset:1024
	ds_read_b128 v[174:177], v147 offset:2048
	ds_read_b128 v[178:181], v147 offset:3072
	ds_read_b128 v[186:189], v147 offset:4096
	ds_read_b128 v[190:193], v147 offset:5120
	ds_read_b128 v[194:197], v147 offset:6144
	ds_read_b128 v[198:201], v147 offset:7168
	global_load_lds_dwordx4 v136, s[60:61]
	s_add_i32 m0, s16, 0xe000
	s_nop 0
	global_load_lds_dwordx4 v138, s[60:61]
	s_waitcnt lgkmcnt(8)
	s_barrier
	s_waitcnt lgkmcnt(0)
	s_setprio 1
	v_mfma_f32_16x16x32_bf16 v[124:127], v[150:153], v[166:169], v[124:127]
	v_mfma_f32_16x16x32_bf16 v[120:123], v[158:161], v[166:169], v[120:123]
	v_mfma_f32_16x16x32_bf16 v[112:115], v[150:153], v[174:177], v[112:115]
	v_mfma_f32_16x16x32_bf16 v[104:107], v[158:161], v[174:177], v[104:107]
	v_mfma_f32_16x16x32_bf16 v[96:99], v[150:153], v[186:189], v[96:99]
	v_mfma_f32_16x16x32_bf16 v[88:91], v[158:161], v[186:189], v[88:91]
	v_mfma_f32_16x16x32_bf16 v[80:83], v[150:153], v[194:197], v[80:83]
	v_mfma_f32_16x16x32_bf16 v[72:75], v[158:161], v[194:197], v[72:75]
	v_mfma_f32_16x16x32_bf16 v[124:127], v[154:157], v[170:173], v[124:127]
	v_mfma_f32_16x16x32_bf16 v[120:123], v[162:165], v[170:173], v[120:123]
	v_mfma_f32_16x16x32_bf16 v[112:115], v[154:157], v[178:181], v[112:115]
	v_mfma_f32_16x16x32_bf16 v[104:107], v[162:165], v[178:181], v[104:107]
	v_mfma_f32_16x16x32_bf16 v[96:99], v[154:157], v[190:193], v[96:99]
	v_mfma_f32_16x16x32_bf16 v[88:91], v[162:165], v[190:193], v[88:91]
	v_mfma_f32_16x16x32_bf16 v[80:83], v[154:157], v[198:201], v[80:83]
	v_mfma_f32_16x16x32_bf16 v[72:75], v[162:165], v[198:201], v[72:75]
	s_setprio 0
	s_barrier
	s_add_i32 s33, s88, s5
	s_add_u32 s98, s62, s12
	s_addc_u32 s99, s63, s13
	s_mov_b32 m0, s33
	ds_read_b128 v[202:205], v148
	ds_read_b128 v[206:209], v148 offset:1024
	ds_read_b128 v[222:225], v148 offset:2048
	ds_read_b128 v[226:229], v148 offset:3072
	global_load_lds_dwordx4 v130, s[62:63]
	s_add_i32 m0, s33, 0x2000
	s_nop 0
	global_load_lds_dwordx4 v134, s[62:63]
	s_barrier
	s_waitcnt lgkmcnt(0)
	s_setprio 1
	v_mfma_f32_16x16x32_bf16 v[116:119], v[202:205], v[166:169], v[116:119]
	v_mfma_f32_16x16x32_bf16 v[108:111], v[222:225], v[166:169], v[108:111]
	v_mfma_f32_16x16x32_bf16 v[100:103], v[202:205], v[174:177], v[100:103]
	v_mfma_f32_16x16x32_bf16 v[92:95], v[222:225], v[174:177], v[92:95]
	v_mfma_f32_16x16x32_bf16 v[84:87], v[202:205], v[186:189], v[84:87]
	v_mfma_f32_16x16x32_bf16 v[76:79], v[222:225], v[186:189], v[76:79]
	v_mfma_f32_16x16x32_bf16 v[68:71], v[202:205], v[194:197], v[68:71]
	v_mfma_f32_16x16x32_bf16 v[64:67], v[222:225], v[194:197], v[64:67]
	v_mfma_f32_16x16x32_bf16 v[116:119], v[206:209], v[170:173], v[116:119]
	v_mfma_f32_16x16x32_bf16 v[108:111], v[226:229], v[170:173], v[108:111]
	v_mfma_f32_16x16x32_bf16 v[100:103], v[206:209], v[178:181], v[100:103]
	v_mfma_f32_16x16x32_bf16 v[92:95], v[226:229], v[178:181], v[92:95]
	v_mfma_f32_16x16x32_bf16 v[84:87], v[206:209], v[190:193], v[84:87]
	v_mfma_f32_16x16x32_bf16 v[76:79], v[226:229], v[190:193], v[76:79]
	v_mfma_f32_16x16x32_bf16 v[68:71], v[206:209], v[198:201], v[68:71]
	v_mfma_f32_16x16x32_bf16 v[64:67], v[226:229], v[198:201], v[64:67]
	s_setprio 0
	s_mov_b32 m0, s16
	s_add_u32 s100, s66, s12
	s_addc_u32 s101, s67, s13
	s_barrier
	ds_read_b128 v[166:169], v147 offset:16384
	ds_read_b128 v[170:173], v147 offset:17408
	ds_read_b128 v[174:177], v147 offset:18432
	ds_read_b128 v[178:181], v147 offset:19456
	ds_read_b128 v[186:189], v147 offset:20480
	ds_read_b128 v[190:193], v147 offset:21504
	ds_read_b128 v[194:197], v147 offset:22528
	ds_read_b128 v[198:201], v147 offset:23552
	global_load_lds_dwordx4 v128, s[66:67]
	s_mov_b32 m0, s17
	s_nop 0
	global_load_lds_dwordx4 v132, s[66:67]
	s_barrier
	s_waitcnt lgkmcnt(0)
	s_setprio 1
	v_mfma_f32_16x16x32_bf16 v[60:63], v[150:153], v[166:169], v[60:63]
	v_mfma_f32_16x16x32_bf16 v[56:59], v[158:161], v[166:169], v[56:59]
	v_mfma_f32_16x16x32_bf16 v[52:55], v[150:153], v[174:177], v[52:55]
	v_mfma_f32_16x16x32_bf16 v[44:47], v[158:161], v[174:177], v[44:47]
	v_mfma_f32_16x16x32_bf16 v[36:39], v[150:153], v[186:189], v[36:39]
	v_mfma_f32_16x16x32_bf16 v[28:31], v[158:161], v[186:189], v[28:31]
	v_mfma_f32_16x16x32_bf16 v[20:23], v[150:153], v[194:197], v[20:23]
	v_mfma_f32_16x16x32_bf16 v[12:15], v[158:161], v[194:197], v[12:15]
	v_mfma_f32_16x16x32_bf16 v[60:63], v[154:157], v[170:173], v[60:63]
	v_mfma_f32_16x16x32_bf16 v[56:59], v[162:165], v[170:173], v[56:59]
	v_mfma_f32_16x16x32_bf16 v[52:55], v[154:157], v[178:181], v[52:55]
	v_mfma_f32_16x16x32_bf16 v[44:47], v[162:165], v[178:181], v[44:47]
	v_mfma_f32_16x16x32_bf16 v[36:39], v[154:157], v[190:193], v[36:39]
	v_mfma_f32_16x16x32_bf16 v[28:31], v[162:165], v[190:193], v[28:31]
	v_mfma_f32_16x16x32_bf16 v[20:23], v[154:157], v[198:201], v[20:23]
	v_mfma_f32_16x16x32_bf16 v[12:15], v[162:165], v[198:201], v[12:15]
	s_setprio 0
	s_barrier
	s_add_u32 s72, s62, 0x80000
	s_addc_u32 s73, s63, 0
	s_add_i32 s33, s89, s5
	s_mov_b32 m0, s33
	s_nop 0
	global_load_lds_dwordx4 v130, s[72:73]
	s_add_i32 m0, s33, 0x2000
	s_nop 0
	global_load_lds_dwordx4 v134, s[72:73]
	s_waitcnt vmcnt(6)
	s_barrier
; #define PG8_STAGE(bufoff, gbase, voff) do { _Pragma("unroll") for (int _i = 0; _i < 2; ++_i) \
;         __builtin_amdgcn_global_load_lds((const unsigned*)((const char*)(gbase) + (voff)[_i]), (LAS unsigned*)(lds + (bufoff) + ldsw + _i * 8192), 16, 0, 0); } while (0)
; #define PG8_LDA(dst, b, h) do { _Pragma("unroll") for (int m = 0; m < 4; ++m) _Pragma("unroll") for (int k = 0; k < 2; ++k) dst[m][k] = *(const LAS bf16x8*)(lds + PG8_SA(b, h) + aoff + m * 2048 + k * 1024); } while (0)
; #define PG8_LDB(dst, b, h) do { _Pragma("unroll") for (int n = 0; n < 2; ++n) _Pragma("unroll") for (int k = 0; k < 2; ++k) dst[n][k] = *(const LAS bf16x8*)(lds + PG8_SB(b, h) + boff + n * 2048 + k * 1024); } while (0)
; #define PG8_MMA(ai, bj, At, Bt) do { __builtin_amdgcn_s_setprio(1); _Pragma("unroll") for (int m = 0; m < 4; ++m) _Pragma("unroll") for (int n = 0; n < 2; ++n) _Pragma("unroll") for (int k = 0; k < 2; ++k) \
;         acc[ai][bj][m][n] = __builtin_amdgcn_mfma_f32_16x16x32_bf16(Bt[n][k], At[m][k], acc[ai][bj][m][n], 0, 0, 0); __builtin_amdgcn_s_setprio(0); } while (0)
; #define PG8_WAIT_V(n) asm volatile("s_waitcnt vmcnt(" #n ")" ::: "memory")
; #define PG8_WAIT_L(n) asm volatile("s_waitcnt lgkmcnt(" #n ")" ::: "memory")
; #define PG8_BAR __builtin_amdgcn_s_barrier()
; #define PG8_SCHED __builtin_amdgcn_sched_barrier(0)
; template <class Epi, class S_t>
; __device__ __forceinline__ void gemm_phase(LAS unsigned char* lds, int lda, int ldb, const S_t& S, const Epi& E) {
;     ...
;             PG8_WAIT_V(6); PG8_BAR; PG8_MMA(1, 1, At, B1); PG8_BAR;
;             PG8_LDB(B0, 1, 0); PG8_SCHED; PG8_LDA(At, 1, 0); PG8_STAGE(PG8_SA(0, 1), a2 + hstepA, voffA);
;             PG8_WAIT_L(8); PG8_BAR; PG8_WAIT_L(0); PG8_MMA(0, 0, At, B0); PG8_BAR; PG8_SCHED;
;             PG8_LDB(B1, 1, 1); PG8_STAGE(PG8_SB(1, 0), b3, voffB);
;             PG8_BAR; PG8_WAIT_L(0); PG8_MMA(0, 1, At, B1); PG8_BAR;
;             PG8_LDA(At, 1, 1); PG8_STAGE(PG8_SA(1, 0), a3, voffA);
;             PG8_BAR; PG8_WAIT_L(0); PG8_MMA(1, 0, At, B0); PG8_BAR; PG8_SCHED;
	s_setprio 1
	v_mfma_f32_16x16x32_bf16 v[48:51], v[202:205], v[166:169], v[48:51]
	v_mfma_f32_16x16x32_bf16 v[40:43], v[222:225], v[166:169], v[40:43]
	v_mfma_f32_16x16x32_bf16 v[32:35], v[202:205], v[174:177], v[32:35]
	v_mfma_f32_16x16x32_bf16 v[24:27], v[222:225], v[174:177], v[24:27]
	v_mfma_f32_16x16x32_bf16 v[16:19], v[202:205], v[186:189], v[16:19]
	v_mfma_f32_16x16x32_bf16 v[8:11], v[222:225], v[186:189], v[8:11]
	v_mfma_f32_16x16x32_bf16 v[4:7], v[202:205], v[194:197], v[4:7]
	v_mfma_f32_16x16x32_bf16 v[0:3], v[222:225], v[194:197], v[0:3]
	v_mfma_f32_16x16x32_bf16 v[48:51], v[206:209], v[170:173], v[48:51]
	v_mfma_f32_16x16x32_bf16 v[40:43], v[226:229], v[170:173], v[40:43]
	v_mfma_f32_16x16x32_bf16 v[32:35], v[206:209], v[178:181], v[32:35]
	v_mfma_f32_16x16x32_bf16 v[24:27], v[226:229], v[178:181], v[24:27]
	v_mfma_f32_16x16x32_bf16 v[16:19], v[206:209], v[190:193], v[16:19]
	v_mfma_f32_16x16x32_bf16 v[8:11], v[226:229], v[190:193], v[8:11]
	v_mfma_f32_16x16x32_bf16 v[4:7], v[206:209], v[198:201], v[4:7]
	v_mfma_f32_16x16x32_bf16 v[0:3], v[226:229], v[198:201], v[0:3]
	s_setprio 0
	v_add_u32_e32 v149, s90, v143
	s_barrier
	ds_read_b128 v[150:153], v149
	ds_read_b128 v[154:157], v149 offset:1024
	ds_read_b128 v[158:161], v149 offset:2048
	ds_read_b128 v[162:165], v149 offset:3072
	s_add_u32 s66, s66, 0x80000
	s_addc_u32 s67, s67, 0
	s_mov_b32 m0, s20
	ds_read_b128 v[166:169], v147 offset:32768
	ds_read_b128 v[170:173], v147 offset:33792
	ds_read_b128 v[174:177], v147 offset:34816
	ds_read_b128 v[178:181], v147 offset:35840
	ds_read_b128 v[186:189], v147 offset:36864
	ds_read_b128 v[190:193], v147 offset:37888
	ds_read_b128 v[194:197], v147 offset:38912
	ds_read_b128 v[198:201], v147 offset:39936
	global_load_lds_dwordx4 v128, s[66:67]
	s_mov_b32 m0, s21
	s_nop 0
	global_load_lds_dwordx4 v132, s[66:67]
	s_waitcnt lgkmcnt(8)
	s_barrier
	s_waitcnt lgkmcnt(0)
	s_setprio 1
	v_mfma_f32_16x16x32_bf16 v[124:127], v[150:153], v[166:169], v[124:127]
	v_mfma_f32_16x16x32_bf16 v[120:123], v[158:161], v[166:169], v[120:123]
	v_mfma_f32_16x16x32_bf16 v[112:115], v[150:153], v[174:177], v[112:115]
	v_mfma_f32_16x16x32_bf16 v[104:107], v[158:161], v[174:177], v[104:107]
	v_mfma_f32_16x16x32_bf16 v[96:99], v[150:153], v[186:189], v[96:99]
	v_mfma_f32_16x16x32_bf16 v[88:91], v[158:161], v[186:189], v[88:91]
	v_mfma_f32_16x16x32_bf16 v[80:83], v[150:153], v[194:197], v[80:83]
	v_mfma_f32_16x16x32_bf16 v[72:75], v[158:161], v[194:197], v[72:75]
	v_mfma_f32_16x16x32_bf16 v[124:127], v[154:157], v[170:173], v[124:127]
	v_mfma_f32_16x16x32_bf16 v[120:123], v[162:165], v[170:173], v[120:123]
	v_mfma_f32_16x16x32_bf16 v[112:115], v[154:157], v[178:181], v[112:115]
	v_mfma_f32_16x16x32_bf16 v[104:107], v[162:165], v[178:181], v[104:107]
	v_mfma_f32_16x16x32_bf16 v[96:99], v[154:157], v[190:193], v[96:99]
	v_mfma_f32_16x16x32_bf16 v[88:91], v[162:165], v[190:193], v[88:91]
	v_mfma_f32_16x16x32_bf16 v[80:83], v[154:157], v[198:201], v[80:83]
	v_mfma_f32_16x16x32_bf16 v[72:75], v[162:165], v[198:201], v[72:75]
	s_setprio 0
	s_barrier
	s_add_i32 s33, s90, s5
	v_add_u32_e32 v149, s91, v143
	s_mov_b32 m0, s33
	ds_read_b128 v[202:205], v149
	ds_read_b128 v[206:209], v149 offset:1024
	ds_read_b128 v[222:225], v149 offset:2048
	ds_read_b128 v[226:229], v149 offset:3072
	global_load_lds_dwordx4 v130, s[98:99]
	s_add_i32 m0, s33, 0x2000
	s_nop 0
	global_load_lds_dwordx4 v134, s[98:99]
	s_barrier
	s_waitcnt lgkmcnt(0)
	s_setprio 1
	v_mfma_f32_16x16x32_bf16 v[116:119], v[202:205], v[166:169], v[116:119]
	v_mfma_f32_16x16x32_bf16 v[108:111], v[222:225], v[166:169], v[108:111]
	v_mfma_f32_16x16x32_bf16 v[100:103], v[202:205], v[174:177], v[100:103]
	v_mfma_f32_16x16x32_bf16 v[92:95], v[222:225], v[174:177], v[92:95]
	v_mfma_f32_16x16x32_bf16 v[84:87], v[202:205], v[186:189], v[84:87]
	v_mfma_f32_16x16x32_bf16 v[76:79], v[222:225], v[186:189], v[76:79]
	v_mfma_f32_16x16x32_bf16 v[68:71], v[202:205], v[194:197], v[68:71]
	v_mfma_f32_16x16x32_bf16 v[64:67], v[222:225], v[194:197], v[64:67]
	v_mfma_f32_16x16x32_bf16 v[116:119], v[206:209], v[170:173], v[116:119]
	v_mfma_f32_16x16x32_bf16 v[108:111], v[226:229], v[170:173], v[108:111]
	v_mfma_f32_16x16x32_bf16 v[100:103], v[206:209], v[178:181], v[100:103]
	v_mfma_f32_16x16x32_bf16 v[92:95], v[226:229], v[178:181], v[92:95]
	v_mfma_f32_16x16x32_bf16 v[84:87], v[206:209], v[190:193], v[84:87]
	v_mfma_f32_16x16x32_bf16 v[76:79], v[226:229], v[190:193], v[76:79]
	v_mfma_f32_16x16x32_bf16 v[68:71], v[206:209], v[198:201], v[68:71]
	v_mfma_f32_16x16x32_bf16 v[64:67], v[226:229], v[198:201], v[64:67]
	s_setprio 0
	s_mov_b32 m0, s35
	s_barrier
	ds_read_b128 v[166:169], v147 offset:49152
	ds_read_b128 v[170:173], v147 offset:50176
	ds_read_b128 v[174:177], v147 offset:51200
	ds_read_b128 v[178:181], v147 offset:52224
	ds_read_b128 v[186:189], v147 offset:53248
	ds_read_b128 v[190:193], v147 offset:54272
	ds_read_b128 v[194:197], v147 offset:55296
	ds_read_b128 v[198:201], v147 offset:56320
	global_load_lds_dwordx4 v128, s[100:101]
	s_mov_b32 m0, s52
	s_nop 0
	global_load_lds_dwordx4 v132, s[100:101]
	s_barrier
; #define PG8_STAGE(bufoff, gbase, voff) do { _Pragma("unroll") for (int _i = 0; _i < 2; ++_i) \
;         __builtin_amdgcn_global_load_lds((const unsigned*)((const char*)(gbase) + (voff)[_i]), (LAS unsigned*)(lds + (bufoff) + ldsw + _i * 8192), 16, 0, 0); } while (0)
; #define PG8_MMA(ai, bj, At, Bt) do { __builtin_amdgcn_s_setprio(1); _Pragma("unroll") for (int m = 0; m < 4; ++m) _Pragma("unroll") for (int n = 0; n < 2; ++n) _Pragma("unroll") for (int k = 0; k < 2; ++k) \
;         acc[ai][bj][m][n] = __builtin_amdgcn_mfma_f32_16x16x32_bf16(Bt[n][k], At[m][k], acc[ai][bj][m][n], 0, 0, 0); __builtin_amdgcn_s_setprio(0); } while (0)
; #define PG8_WAIT_V(n) asm volatile("s_waitcnt vmcnt(" #n ")" ::: "memory")
; #define PG8_WAIT_L(n) asm volatile("s_waitcnt lgkmcnt(" #n ")" ::: "memory")
; #define PG8_BAR __builtin_amdgcn_s_barrier()
; #define PG8_SCHED __builtin_amdgcn_sched_barrier(0)
; template <class Epi, class S_t>
; __device__ __forceinline__ void gemm_phase(LAS unsigned char* lds, int lda, int ldb, const S_t& S, const Epi& E) {
;     ...
;             PG8_BAR; PG8_WAIT_L(0); PG8_MMA(1, 0, At, B0); PG8_BAR; PG8_SCHED;
;             PG8_STAGE(PG8_SB(1, 1), b3 + hstepB, voffB);
;             PG8_WAIT_V(6); PG8_BAR; PG8_MMA(1, 1, At, B1); PG8_BAR;
;     __device__ __forceinline__ void operator()(const f32x4 (&acc)[2][2][4][2], const Unit& u, int wr, int wc, int fr, int fq) const {
;     ...
;         } else {
;             const int row0 = (u.pm - 32) * BM + wr * 64 + fr;
;             float* Op = Os + (size_t)(u.tag - 1) * (1024ull * DM);
; #pragma unroll
;             for (int ai = 0; ai < 2; ++ai)
; #pragma unroll
;                 for (int m = 0; m < 4; ++m) { float* rowp = Op + (size_t)(row0 + ai * HALF + m * 16) * DM + col0;
; #pragma unroll
;                     for (int bj = 0; bj < 2; ++bj)
; #pragma unroll
;                         for (int n = 0; n < 2; ++n) *(f32x4*)(rowp + bj * HALF + 4 * n) = acc[ai][bj][m][n]; }
;         }
	s_waitcnt lgkmcnt(0)
	s_setprio 1
	v_mfma_f32_16x16x32_bf16 v[60:63], v[150:153], v[166:169], v[60:63]
	v_mfma_f32_16x16x32_bf16 v[56:59], v[158:161], v[166:169], v[56:59]
	v_mfma_f32_16x16x32_bf16 v[52:55], v[150:153], v[174:177], v[52:55]
	v_mfma_f32_16x16x32_bf16 v[44:47], v[158:161], v[174:177], v[44:47]
	v_mfma_f32_16x16x32_bf16 v[36:39], v[150:153], v[186:189], v[36:39]
	v_mfma_f32_16x16x32_bf16 v[28:31], v[158:161], v[186:189], v[28:31]
	v_mfma_f32_16x16x32_bf16 v[20:23], v[150:153], v[194:197], v[20:23]
	v_mfma_f32_16x16x32_bf16 v[12:15], v[158:161], v[194:197], v[12:15]
	v_mfma_f32_16x16x32_bf16 v[60:63], v[154:157], v[170:173], v[60:63]
	v_mfma_f32_16x16x32_bf16 v[56:59], v[162:165], v[170:173], v[56:59]
	v_mfma_f32_16x16x32_bf16 v[52:55], v[154:157], v[178:181], v[52:55]
	v_mfma_f32_16x16x32_bf16 v[44:47], v[162:165], v[178:181], v[44:47]
	v_mfma_f32_16x16x32_bf16 v[36:39], v[154:157], v[190:193], v[36:39]
	v_mfma_f32_16x16x32_bf16 v[28:31], v[162:165], v[190:193], v[28:31]
	v_mfma_f32_16x16x32_bf16 v[20:23], v[154:157], v[198:201], v[20:23]
	v_mfma_f32_16x16x32_bf16 v[12:15], v[162:165], v[198:201], v[12:15]
	s_setprio 0
	s_barrier
	s_add_u32 s62, s62, 0x80080
	s_addc_u32 s63, s63, 0
	s_add_i32 s33, s91, s5
	s_mov_b32 m0, s33
	s_nop 0
	global_load_lds_dwordx4 v130, s[62:63]
	s_add_i32 m0, s33, 0x2000
	s_nop 0
	global_load_lds_dwordx4 v134, s[62:63]
	s_waitcnt vmcnt(6)
	s_barrier
	s_setprio 1
	v_mfma_f32_16x16x32_bf16 v[48:51], v[202:205], v[166:169], v[48:51]
	v_mfma_f32_16x16x32_bf16 v[40:43], v[222:225], v[166:169], v[40:43]
	v_mfma_f32_16x16x32_bf16 v[32:35], v[202:205], v[174:177], v[32:35]
	v_mfma_f32_16x16x32_bf16 v[24:27], v[222:225], v[174:177], v[24:27]
	v_mfma_f32_16x16x32_bf16 v[16:19], v[202:205], v[186:189], v[16:19]
	v_mfma_f32_16x16x32_bf16 v[8:11], v[222:225], v[186:189], v[8:11]
	v_mfma_f32_16x16x32_bf16 v[4:7], v[202:205], v[194:197], v[4:7]
	v_mfma_f32_16x16x32_bf16 v[0:3], v[222:225], v[194:197], v[0:3]
	v_mfma_f32_16x16x32_bf16 v[48:51], v[206:209], v[170:173], v[48:51]
	v_mfma_f32_16x16x32_bf16 v[40:43], v[226:229], v[170:173], v[40:43]
	v_mfma_f32_16x16x32_bf16 v[32:35], v[206:209], v[178:181], v[32:35]
	v_mfma_f32_16x16x32_bf16 v[24:27], v[226:229], v[178:181], v[24:27]
	v_mfma_f32_16x16x32_bf16 v[16:19], v[206:209], v[190:193], v[16:19]
	v_mfma_f32_16x16x32_bf16 v[8:11], v[226:229], v[190:193], v[8:11]
	v_mfma_f32_16x16x32_bf16 v[4:7], v[206:209], v[198:201], v[4:7]
	v_mfma_f32_16x16x32_bf16 v[0:3], v[226:229], v[198:201], v[0:3]
	s_setprio 0
	s_add_u32 s60, s60, 0x100
	s_addc_u32 s61, s61, 0
	s_add_u32 s1, s1, 0x100
	s_addc_u32 s69, s69, 0
	s_cmp_ge_u32 s70, s42
	s_mov_b32 s62, s70
	s_cbranch_scc0 .Lrot_1051
	s_barrier
	v_lshl_or_b32 v140, s43, 8, v145
	s_lshl_b32 s33, s8, 8
	s_cmp_lg_u32 s68, 0
	v_ashrrev_i32_e32 v141, 31, v140
	s_cbranch_scc0 .LBB0_1054
	s_add_i32 s8, s68, -1
	s_lshl_b64 s[0:1], s[8:9], 23
	v_add_u32_e32 v150, s33, v144
	s_add_u32 s0, s10, s0
	v_or_b32_e32 v156, 16, v150
	s_addc_u32 s1, s11, s1
	v_ashrrev_i32_e32 v151, 31, v150
	v_ashrrev_i32_e32 v157, 31, v156
	v_lshl_add_u64 v[152:153], v[140:141], 2, s[0:1]
	v_lshlrev_b64 v[154:155], 13, v[150:151]
	v_lshlrev_b64 v[156:157], 13, v[156:157]
	v_lshl_add_u64 v[154:155], v[152:153], 0, v[154:155]
	v_lshl_add_u64 v[156:157], v[152:153], 0, v[156:157]
	global_store_dwordx4 v[154:155], v[124:127], off
	global_store_dwordx4 v[154:155], v[120:123], off offset:16
	global_store_dwordx4 v[154:155], v[116:119], off offset:512
	global_store_dwordx4 v[154:155], v[108:111], off offset:528
	global_store_dwordx4 v[156:157], v[112:115], off
	global_store_dwordx4 v[156:157], v[104:107], off offset:16
	global_store_dwordx4 v[156:157], v[100:103], off offset:512
	global_store_dwordx4 v[156:157], v[92:95], off offset:528
	v_or_b32_e32 v156, 32, v150
	v_or_b32_e32 v150, 48, v150
	v_ashrrev_i32_e32 v157, 31, v156
	v_ashrrev_i32_e32 v151, 31, v150
	v_lshlrev_b64 v[156:157], 13, v[156:157]
	v_lshlrev_b64 v[150:151], 13, v[150:151]
	v_lshl_add_u64 v[156:157], v[152:153], 0, v[156:157]
	v_lshl_add_u64 v[150:151], v[152:153], 0, v[150:151]
	s_mov_b64 s[0:1], 0x100000
	global_store_dwordx4 v[156:157], v[96:99], off
	global_store_dwordx4 v[156:157], v[88:91], off offset:16
	global_store_dwordx4 v[156:157], v[84:87], off offset:512
	global_store_dwordx4 v[156:157], v[76:79], off offset:528
	global_store_dwordx4 v[150:151], v[80:83], off
	global_store_dwordx4 v[150:151], v[72:75], off offset:16
	global_store_dwordx4 v[150:151], v[68:71], off offset:512
	global_store_dwordx4 v[150:151], v[64:67], off offset:528
	v_lshl_add_u64 v[150:151], v[154:155], 0, s[0:1]
	s_mov_b32 s0, 0x100000
	v_add_co_u32_e32 v152, vcc, s0, v154
	s_mov_b64 s[0:1], 0x120000
	s_nop 0
	v_addc_co_u32_e32 v153, vcc, 0, v155, vcc
	global_store_dwordx4 v[152:153], v[60:63], off
	global_store_dwordx4 v[150:151], v[56:59], off offset:16
	global_store_dwordx4 v[150:151], v[48:51], off offset:512
	global_store_dwordx4 v[150:151], v[40:43], off offset:528
	v_lshl_add_u64 v[150:151], v[154:155], 0, s[0:1]
	s_mov_b32 s0, 0x120000
	v_add_co_u32_e32 v152, vcc, s0, v154
	s_mov_b64 s[0:1], 0x140000
	s_nop 0
	v_addc_co_u32_e32 v153, vcc, 0, v155, vcc
	global_store_dwordx4 v[152:153], v[52:55], off
	global_store_dwordx4 v[150:151], v[44:47], off offset:16
	global_store_dwordx4 v[150:151], v[32:35], off offset:512
	global_store_dwordx4 v[150:151], v[24:27], off offset:528
	v_lshl_add_u64 v[150:151], v[154:155], 0, s[0:1]
	s_mov_b32 s0, 0x140000
	v_add_co_u32_e32 v152, vcc, s0, v154
	s_mov_b64 s[0:1], 0x160000
	s_nop 0
	v_addc_co_u32_e32 v153, vcc, 0, v155, vcc
	global_store_dwordx4 v[152:153], v[36:39], off
	global_store_dwordx4 v[150:151], v[28:31], off offset:16
	global_store_dwordx4 v[150:151], v[16:19], off offset:512
	global_store_dwordx4 v[150:151], v[8:11], off offset:528
	v_add_co_u32_e32 v152, vcc, 0x160000, v154
	v_lshl_add_u64 v[150:151], v[154:155], 0, s[0:1]
	s_nop 0
	v_addc_co_u32_e32 v153, vcc, 0, v155, vcc
	global_store_dwordx4 v[152:153], v[20:23], off
	global_store_dwordx4 v[150:151], v[12:15], off offset:16
	global_store_dwordx4 v[150:151], v[4:7], off offset:512
	global_store_dwordx4 v[150:151], v[0:3], off offset:528
	s_cbranch_execnz .LBB0_1047
	s_branch .LBB0_1046

; template <class Epi, class S_t>
; __device__ __forceinline__ void gemm_phase(LAS unsigned char* lds, int lda, int ldb, const S_t& S, const Epi& E) {
;     ...
; #pragma unroll
;         for (int a = 0; a < 2; ++a)
; #pragma unroll
;             for (int b = 0; b < 2; ++b)
; #pragma unroll
;                 for (int m = 0; m < 4; ++m)
; #pragma unroll
;                     for (int n = 0; n < 2; ++n) acc[a][b][m][n] = (f32x4){0.f, 0.f, 0.f, 0.f};
;         cur = nxt; cA = nA; cB = nB; ++ui;
;     __device__ __forceinline__ void operator()(const f32x4 (&acc)[2][2][4][2], const Unit& u, int wr, int wc, int fr, int fq) const {
;     ...
;         const int j0 = u.pn * HALF + wc * 32 + 8 * fq;
;         u32x2 res0[8];
; #pragma unroll
;         for (int n = 0; n < 2; ++n) {
;             asm volatile("" ::: "memory");
;             const int jc = j0 + 4 * n;
;             const f32x4 wg0 = *(const f32x4*)(wconv + jc), wg1 = *(const f32x4*)(wconv + 2 * DFF + jc), wg2 = *(const f32x4*)(wconv + 4 * DFF + jc), bg = *(const f32x4*)(bconv + jc);
;             const f32x4 wv0 = *(const f32x4*)(wconv + DFF + jc), wv1 = *(const f32x4*)(wconv + 3 * DFF + jc), wv2 = *(const f32x4*)(wconv + 5 * DFF + jc), bv = *(const f32x4*)(bconv + DFF + jc);
.LBB0_1199:
	v_readlane_b32 s100, v254, 41
	v_readlane_b32 s101, v254, 42
	v_readlane_b32 s98, v254, 43
	v_readlane_b32 s99, v254, 44
	v_and_b32_e32 v128, 63, v212
	v_lshrrev_b32_e32 v129, 3, v128
	v_and_b32_e32 v128, 7, v128
	v_and_b32_e32 v130, 0x60, v219
	v_lshl_or_b32 v130, s42, 7, v130
	v_lshlrev_b32_e32 v130, 2, v130
	v_lshl_add_u32 v130, v128, 4, v130
	v_cmp_gt_u32_e32 vcc, 6, v129
	v_subrev_u32_e32 v131, 6, v129
	v_mov_b32_e32 v132, s100
	v_mov_b32_e32 v133, s98
	v_mov_b32_e32 v134, s101
	v_mov_b32_e32 v135, s99
	v_cndmask_b32_e32 v131, v131, v129, vcc
	v_cndmask_b32_e32 v132, v133, v132, vcc
	v_cndmask_b32_e32 v134, v135, v134, vcc
	v_mul_u32_u24_e32 v131, 0x6000, v131
	v_add_u32_e32 v130, v130, v131
	v_add_co_u32_e32 v130, vcc, v132, v130
	v_addc_co_u32_e32 v131, vcc, 0, v134, vcc
	v_readfirstlane_b32 s98, v212
	s_lshr_b32 s98, s98, 6
	s_lshl_b32 s98, s98, 10
	s_add_i32 m0, s98, 0x20840
	s_nop 0
	global_load_lds_dwordx4 v[130:131], off
	s_add_u32 s74, s74, 0x80080
	s_addc_u32 s75, s75, 0
	s_add_u32 s0, s76, 0x100
	s_addc_u32 s1, s77, 0
	s_mov_b32 s5, -2
	v_mov_b64_e32 v[0:1], 0
	v_mov_b64_e32 v[2:3], 0
	v_mov_b64_e32 v[4:5], 0
	v_mov_b64_e32 v[6:7], 0
	v_mov_b64_e32 v[8:9], 0
	v_mov_b64_e32 v[10:11], 0
	v_mov_b64_e32 v[12:13], 0
	v_mov_b64_e32 v[14:15], 0
	v_mov_b64_e32 v[16:17], 0
	v_mov_b64_e32 v[18:19], 0
	v_mov_b64_e32 v[20:21], 0
	v_mov_b64_e32 v[22:23], 0
	v_mov_b64_e32 v[24:25], 0
	v_mov_b64_e32 v[26:27], 0
	v_mov_b64_e32 v[28:29], 0
	v_mov_b64_e32 v[30:31], 0
	v_mov_b64_e32 v[32:33], 0
	v_mov_b64_e32 v[34:35], 0
	v_mov_b64_e32 v[36:37], 0
	v_mov_b64_e32 v[38:39], 0
	v_mov_b64_e32 v[40:41], 0
	v_mov_b64_e32 v[42:43], 0
	v_mov_b64_e32 v[44:45], 0
	v_mov_b64_e32 v[46:47], 0
	v_mov_b64_e32 v[48:49], 0
	v_mov_b64_e32 v[50:51], 0
	v_mov_b64_e32 v[52:53], 0
	v_mov_b64_e32 v[54:55], 0
	v_mov_b64_e32 v[56:57], 0
	v_mov_b64_e32 v[58:59], 0
	v_mov_b64_e32 v[60:61], 0
	v_mov_b64_e32 v[62:63], 0
	v_mov_b64_e32 v[64:65], 0
	v_mov_b64_e32 v[66:67], 0
	v_mov_b64_e32 v[68:69], 0
	v_mov_b64_e32 v[70:71], 0
	v_mov_b64_e32 v[72:73], 0
	v_mov_b64_e32 v[74:75], 0
	v_mov_b64_e32 v[76:77], 0
	v_mov_b64_e32 v[78:79], 0
	v_mov_b64_e32 v[80:81], 0
	v_mov_b64_e32 v[82:83], 0
	v_mov_b64_e32 v[84:85], 0
	v_mov_b64_e32 v[86:87], 0
	v_mov_b64_e32 v[88:89], 0
	v_mov_b64_e32 v[90:91], 0
	v_mov_b64_e32 v[92:93], 0
	v_mov_b64_e32 v[94:95], 0
	v_mov_b64_e32 v[96:97], 0
	v_mov_b64_e32 v[98:99], 0
	v_mov_b64_e32 v[100:101], 0
	v_mov_b64_e32 v[102:103], 0
	v_mov_b64_e32 v[104:105], 0
	v_mov_b64_e32 v[106:107], 0
	v_mov_b64_e32 v[108:109], 0
	v_mov_b64_e32 v[110:111], 0
	v_mov_b64_e32 v[112:113], 0
	v_mov_b64_e32 v[114:115], 0
	v_mov_b64_e32 v[116:117], 0
	v_mov_b64_e32 v[118:119], 0
	v_mov_b64_e32 v[120:121], 0
	v_mov_b64_e32 v[122:123], 0
	v_mov_b64_e32 v[124:125], 0
	v_mov_b64_e32 v[126:127], 0
	s_branch .LBB0_1200

; #define PG8_STAGE(bufoff, gbase, voff) do { _Pragma("unroll") for (int _i = 0; _i < 2; ++_i) \
;         __builtin_amdgcn_global_load_lds((const unsigned*)((const char*)(gbase) + (voff)[_i]), (LAS unsigned*)(lds + (bufoff) + ldsw + _i * 8192), 16, 0, 0); } while (0)
; #define PG8_LDA(dst, b, h) do { _Pragma("unroll") for (int m = 0; m < 4; ++m) _Pragma("unroll") for (int k = 0; k < 2; ++k) dst[m][k] = *(const LAS bf16x8*)(lds + PG8_SA(b, h) + aoff + m * 2048 + k * 1024); } while (0)
; #define PG8_LDB(dst, b, h) do { _Pragma("unroll") for (int n = 0; n < 2; ++n) _Pragma("unroll") for (int k = 0; k < 2; ++k) dst[n][k] = *(const LAS bf16x8*)(lds + PG8_SB(b, h) + boff + n * 2048 + k * 1024); } while (0)
; #define PG8_MMA(ai, bj, At, Bt) do { __builtin_amdgcn_s_setprio(1); _Pragma("unroll") for (int m = 0; m < 4; ++m) _Pragma("unroll") for (int n = 0; n < 2; ++n) _Pragma("unroll") for (int k = 0; k < 2; ++k) \
;         acc[ai][bj][m][n] = __builtin_amdgcn_mfma_f32_16x16x32_bf16(Bt[n][k], At[m][k], acc[ai][bj][m][n], 0, 0, 0); __builtin_amdgcn_s_setprio(0); } while (0)
; #define PG8_WAIT_V(n) asm volatile("s_waitcnt vmcnt(" #n ")" ::: "memory")
; #define PG8_WAIT_L(n) asm volatile("s_waitcnt lgkmcnt(" #n ")" ::: "memory")
; #define PG8_BAR __builtin_amdgcn_s_barrier()
; #define PG8_SCHED __builtin_amdgcn_sched_barrier(0)
; template <class Epi, class S_t>
; __device__ __forceinline__ void gemm_phase(LAS unsigned char* lds, int lda, int ldb, const S_t& S, const Epi& E) {
;     ...
;             PG8_LDB(B0, 0, 0); PG8_SCHED; PG8_LDA(At, 0, 0); PG8_STAGE(PG8_SA(1, 1), a1 + hstepA, voffA);
;             PG8_WAIT_L(8); PG8_BAR; PG8_WAIT_L(0); PG8_MMA(0, 0, At, B0); PG8_BAR; PG8_SCHED;
;             PG8_LDB(B1, 0, 1); PG8_STAGE(PG8_SB(0, 0), b2, voffB);
;             PG8_BAR; PG8_WAIT_L(0); PG8_MMA(0, 1, At, B1); PG8_BAR;
;             PG8_LDA(At, 0, 1); PG8_STAGE(PG8_SA(0, 0), a2, voffA);
;             PG8_BAR; PG8_WAIT_L(0); PG8_MMA(1, 0, At, B0); PG8_BAR; PG8_SCHED;
;             PG8_STAGE(PG8_SB(0, 1), b2 + hstepB, voffB);
;             PG8_WAIT_V(6); PG8_BAR; PG8_MMA(1, 1, At, B1); PG8_BAR;
.LBB0_1200:
	ds_read_b128 v[128:131], v223
	ds_read_b128 v[132:135], v223 offset:1024
	ds_read_b128 v[136:139], v223 offset:2048
	ds_read_b128 v[140:143], v223 offset:3072
	s_add_u32 s33, s74, 0xfff80080
	s_addc_u32 s43, s75, -1
	s_cmp_eq_u32 s5, 28
	s_cselect_b32 s79, s69, s43
	s_cselect_b32 s78, s68, s33
	s_cselect_b32 s77, s71, s1
	s_cselect_b32 s76, s70, s0
	s_add_i32 m0, s7, 0xc000
	ds_read_b128 v[144:147], v246
	ds_read_b128 v[148:151], v246 offset:1024
	ds_read_b128 v[152:155], v246 offset:2048
	ds_read_b128 v[156:159], v246 offset:3072
	ds_read_b128 v[160:163], v246 offset:4096
	ds_read_b128 v[164:167], v246 offset:5120
	ds_read_b128 v[168:171], v246 offset:6144
	ds_read_b128 v[172:175], v246 offset:7168
	global_load_lds_dwordx4 v236, s[74:75]
	s_add_i32 m0, s7, 0xe000
	s_nop 0
	global_load_lds_dwordx4 v238, s[74:75]
	s_waitcnt lgkmcnt(8)
	s_barrier
	s_waitcnt lgkmcnt(0)
	s_setprio 1
	v_mfma_f32_16x16x32_bf16 v[124:127], v[128:131], v[144:147], v[124:127]
	v_mfma_f32_16x16x32_bf16 v[120:123], v[136:139], v[144:147], v[120:123]
	v_mfma_f32_16x16x32_bf16 v[116:119], v[128:131], v[152:155], v[116:119]
	v_mfma_f32_16x16x32_bf16 v[108:111], v[136:139], v[152:155], v[108:111]
	v_mfma_f32_16x16x32_bf16 v[100:103], v[128:131], v[160:163], v[100:103]
	v_mfma_f32_16x16x32_bf16 v[92:95], v[136:139], v[160:163], v[92:95]
	v_mfma_f32_16x16x32_bf16 v[84:87], v[128:131], v[168:171], v[84:87]
	v_mfma_f32_16x16x32_bf16 v[76:79], v[136:139], v[168:171], v[76:79]
	v_mfma_f32_16x16x32_bf16 v[124:127], v[132:135], v[148:151], v[124:127]
	v_mfma_f32_16x16x32_bf16 v[120:123], v[140:143], v[148:151], v[120:123]
	v_mfma_f32_16x16x32_bf16 v[116:119], v[132:135], v[156:159], v[116:119]
	v_mfma_f32_16x16x32_bf16 v[108:111], v[140:143], v[156:159], v[108:111]
	v_mfma_f32_16x16x32_bf16 v[100:103], v[132:135], v[164:167], v[100:103]
	v_mfma_f32_16x16x32_bf16 v[92:95], v[140:143], v[164:167], v[92:95]
	v_mfma_f32_16x16x32_bf16 v[84:87], v[132:135], v[172:175], v[84:87]
	v_mfma_f32_16x16x32_bf16 v[76:79], v[140:143], v[172:175], v[76:79]
	s_setprio 0
	s_barrier
	s_add_i32 s33, s88, s64
	s_add_u32 s98, s76, s38
	s_addc_u32 s99, s77, s39
	s_mov_b32 m0, s33
	ds_read_b128 v[176:179], v247
	ds_read_b128 v[180:183], v247 offset:1024
	ds_read_b128 v[184:187], v247 offset:2048
	ds_read_b128 v[188:191], v247 offset:3072
	global_load_lds_dwordx4 v228, s[76:77]
	s_add_i32 m0, s33, 0x2000
	s_nop 0
	global_load_lds_dwordx4 v224, s[76:77]
	s_barrier
	s_waitcnt lgkmcnt(0)
	s_setprio 1
	v_mfma_f32_16x16x32_bf16 v[112:115], v[176:179], v[144:147], v[112:115]
	v_mfma_f32_16x16x32_bf16 v[104:107], v[184:187], v[144:147], v[104:107]
	v_mfma_f32_16x16x32_bf16 v[96:99], v[176:179], v[152:155], v[96:99]
	v_mfma_f32_16x16x32_bf16 v[88:91], v[184:187], v[152:155], v[88:91]
	v_mfma_f32_16x16x32_bf16 v[80:83], v[176:179], v[160:163], v[80:83]
	v_mfma_f32_16x16x32_bf16 v[72:75], v[184:187], v[160:163], v[72:75]
	v_mfma_f32_16x16x32_bf16 v[68:71], v[176:179], v[168:171], v[68:71]
	v_mfma_f32_16x16x32_bf16 v[64:67], v[184:187], v[168:171], v[64:67]
	v_mfma_f32_16x16x32_bf16 v[112:115], v[180:183], v[148:151], v[112:115]
	v_mfma_f32_16x16x32_bf16 v[104:107], v[188:191], v[148:151], v[104:107]
	v_mfma_f32_16x16x32_bf16 v[96:99], v[180:183], v[156:159], v[96:99]
	v_mfma_f32_16x16x32_bf16 v[88:91], v[188:191], v[156:159], v[88:91]
	v_mfma_f32_16x16x32_bf16 v[80:83], v[180:183], v[164:167], v[80:83]
	v_mfma_f32_16x16x32_bf16 v[72:75], v[188:191], v[164:167], v[72:75]
	v_mfma_f32_16x16x32_bf16 v[68:71], v[180:183], v[172:175], v[68:71]
	v_mfma_f32_16x16x32_bf16 v[64:67], v[188:191], v[172:175], v[64:67]
	s_setprio 0
	s_mov_b32 m0, s7
	s_add_u32 s100, s78, s38
	s_addc_u32 s101, s79, s39
	s_barrier
	ds_read_b128 v[144:147], v246 offset:16384
	ds_read_b128 v[148:151], v246 offset:17408
	ds_read_b128 v[152:155], v246 offset:18432
	ds_read_b128 v[156:159], v246 offset:19456
	ds_read_b128 v[160:163], v246 offset:20480
	ds_read_b128 v[164:167], v246 offset:21504
	ds_read_b128 v[168:171], v246 offset:22528
	ds_read_b128 v[172:175], v246 offset:23552
	global_load_lds_dwordx4 v230, s[78:79]
	s_mov_b32 m0, s35
	s_nop 0
	global_load_lds_dwordx4 v226, s[78:79]
	s_barrier
	s_waitcnt lgkmcnt(0)
	s_setprio 1
	v_mfma_f32_16x16x32_bf16 v[60:63], v[128:131], v[144:147], v[60:63]
	v_mfma_f32_16x16x32_bf16 v[56:59], v[136:139], v[144:147], v[56:59]
	v_mfma_f32_16x16x32_bf16 v[52:55], v[128:131], v[152:155], v[52:55]
	v_mfma_f32_16x16x32_bf16 v[44:47], v[136:139], v[152:155], v[44:47]
	v_mfma_f32_16x16x32_bf16 v[36:39], v[128:131], v[160:163], v[36:39]
	v_mfma_f32_16x16x32_bf16 v[28:31], v[136:139], v[160:163], v[28:31]
	v_mfma_f32_16x16x32_bf16 v[20:23], v[128:131], v[168:171], v[20:23]
	v_mfma_f32_16x16x32_bf16 v[12:15], v[136:139], v[168:171], v[12:15]
	v_mfma_f32_16x16x32_bf16 v[60:63], v[132:135], v[148:151], v[60:63]
	v_mfma_f32_16x16x32_bf16 v[56:59], v[140:143], v[148:151], v[56:59]
	v_mfma_f32_16x16x32_bf16 v[52:55], v[132:135], v[156:159], v[52:55]
	v_mfma_f32_16x16x32_bf16 v[44:47], v[140:143], v[156:159], v[44:47]
	v_mfma_f32_16x16x32_bf16 v[36:39], v[132:135], v[164:167], v[36:39]
	v_mfma_f32_16x16x32_bf16 v[28:31], v[140:143], v[164:167], v[28:31]
	v_mfma_f32_16x16x32_bf16 v[20:23], v[132:135], v[172:175], v[20:23]
	v_mfma_f32_16x16x32_bf16 v[12:15], v[140:143], v[172:175], v[12:15]
	s_setprio 0
	s_barrier
	s_add_u32 s52, s76, 0x80000
	s_addc_u32 s53, s77, 0
	s_add_i32 s33, s89, s64
	s_mov_b32 m0, s33
	s_nop 0
	global_load_lds_dwordx4 v228, s[52:53]
	s_add_i32 m0, s33, 0x2000
	s_nop 0
	global_load_lds_dwordx4 v224, s[52:53]
	s_waitcnt vmcnt(6)
	s_barrier
; #define PG8_STAGE(bufoff, gbase, voff) do { _Pragma("unroll") for (int _i = 0; _i < 2; ++_i) \
;         __builtin_amdgcn_global_load_lds((const unsigned*)((const char*)(gbase) + (voff)[_i]), (LAS unsigned*)(lds + (bufoff) + ldsw + _i * 8192), 16, 0, 0); } while (0)
; #define PG8_LDA(dst, b, h) do { _Pragma("unroll") for (int m = 0; m < 4; ++m) _Pragma("unroll") for (int k = 0; k < 2; ++k) dst[m][k] = *(const LAS bf16x8*)(lds + PG8_SA(b, h) + aoff + m * 2048 + k * 1024); } while (0)
; #define PG8_LDB(dst, b, h) do { _Pragma("unroll") for (int n = 0; n < 2; ++n) _Pragma("unroll") for (int k = 0; k < 2; ++k) dst[n][k] = *(const LAS bf16x8*)(lds + PG8_SB(b, h) + boff + n * 2048 + k * 1024); } while (0)
; #define PG8_MMA(ai, bj, At, Bt) do { __builtin_amdgcn_s_setprio(1); _Pragma("unroll") for (int m = 0; m < 4; ++m) _Pragma("unroll") for (int n = 0; n < 2; ++n) _Pragma("unroll") for (int k = 0; k < 2; ++k) \
;         acc[ai][bj][m][n] = __builtin_amdgcn_mfma_f32_16x16x32_bf16(Bt[n][k], At[m][k], acc[ai][bj][m][n], 0, 0, 0); __builtin_amdgcn_s_setprio(0); } while (0)
; #define PG8_WAIT_V(n) asm volatile("s_waitcnt vmcnt(" #n ")" ::: "memory")
; #define PG8_WAIT_L(n) asm volatile("s_waitcnt lgkmcnt(" #n ")" ::: "memory")
; #define PG8_BAR __builtin_amdgcn_s_barrier()
; #define PG8_SCHED __builtin_amdgcn_sched_barrier(0)
; template <class Epi, class S_t>
; __device__ __forceinline__ void gemm_phase(LAS unsigned char* lds, int lda, int ldb, const S_t& S, const Epi& E) {
;     ...
;             PG8_WAIT_V(6); PG8_BAR; PG8_MMA(1, 1, At, B1); PG8_BAR;
;             PG8_LDB(B0, 1, 0); PG8_SCHED; PG8_LDA(At, 1, 0); PG8_STAGE(PG8_SA(0, 1), a2 + hstepA, voffA);
;             PG8_WAIT_L(8); PG8_BAR; PG8_WAIT_L(0); PG8_MMA(0, 0, At, B0); PG8_BAR; PG8_SCHED;
;             PG8_LDB(B1, 1, 1); PG8_STAGE(PG8_SB(1, 0), b3, voffB);
;             PG8_BAR; PG8_WAIT_L(0); PG8_MMA(0, 1, At, B1); PG8_BAR;
;             PG8_LDA(At, 1, 1); PG8_STAGE(PG8_SA(1, 0), a3, voffA);
;             PG8_BAR; PG8_WAIT_L(0); PG8_MMA(1, 0, At, B0); PG8_BAR; PG8_SCHED;
	s_setprio 1
	v_mfma_f32_16x16x32_bf16 v[48:51], v[176:179], v[144:147], v[48:51]
	v_mfma_f32_16x16x32_bf16 v[40:43], v[184:187], v[144:147], v[40:43]
	v_mfma_f32_16x16x32_bf16 v[32:35], v[176:179], v[152:155], v[32:35]
	v_mfma_f32_16x16x32_bf16 v[24:27], v[184:187], v[152:155], v[24:27]
	v_mfma_f32_16x16x32_bf16 v[16:19], v[176:179], v[160:163], v[16:19]
	v_mfma_f32_16x16x32_bf16 v[8:11], v[184:187], v[160:163], v[8:11]
	v_mfma_f32_16x16x32_bf16 v[4:7], v[176:179], v[168:171], v[4:7]
	v_mfma_f32_16x16x32_bf16 v[0:3], v[184:187], v[168:171], v[0:3]
	v_mfma_f32_16x16x32_bf16 v[48:51], v[180:183], v[148:151], v[48:51]
	v_mfma_f32_16x16x32_bf16 v[40:43], v[188:191], v[148:151], v[40:43]
	v_mfma_f32_16x16x32_bf16 v[32:35], v[180:183], v[156:159], v[32:35]
	v_mfma_f32_16x16x32_bf16 v[24:27], v[188:191], v[156:159], v[24:27]
	v_mfma_f32_16x16x32_bf16 v[16:19], v[180:183], v[164:167], v[16:19]
	v_mfma_f32_16x16x32_bf16 v[8:11], v[188:191], v[164:167], v[8:11]
	v_mfma_f32_16x16x32_bf16 v[4:7], v[180:183], v[172:175], v[4:7]
	v_mfma_f32_16x16x32_bf16 v[0:3], v[188:191], v[172:175], v[0:3]
	s_setprio 0
	v_add_u32_e32 v140, s90, v215
	s_barrier
	ds_read_b128 v[128:131], v140
	ds_read_b128 v[132:135], v140 offset:1024
	ds_read_b128 v[136:139], v140 offset:2048
	ds_read_b128 v[140:143], v140 offset:3072
	s_add_u32 s52, s78, 0x80000
	s_addc_u32 s53, s79, 0
	s_mov_b32 m0, s92
	ds_read_b128 v[144:147], v246 offset:32768
	ds_read_b128 v[148:151], v246 offset:33792
	ds_read_b128 v[152:155], v246 offset:34816
	ds_read_b128 v[156:159], v246 offset:35840
	ds_read_b128 v[160:163], v246 offset:36864
	ds_read_b128 v[164:167], v246 offset:37888
	ds_read_b128 v[168:171], v246 offset:38912
	ds_read_b128 v[172:175], v246 offset:39936
	global_load_lds_dwordx4 v230, s[52:53]
	s_mov_b32 m0, s50
	s_nop 0
	global_load_lds_dwordx4 v226, s[52:53]
	s_waitcnt lgkmcnt(8)
	s_barrier
	s_waitcnt lgkmcnt(0)
	s_setprio 1
	v_mfma_f32_16x16x32_bf16 v[124:127], v[128:131], v[144:147], v[124:127]
	v_mfma_f32_16x16x32_bf16 v[120:123], v[136:139], v[144:147], v[120:123]
	v_mfma_f32_16x16x32_bf16 v[116:119], v[128:131], v[152:155], v[116:119]
	v_mfma_f32_16x16x32_bf16 v[108:111], v[136:139], v[152:155], v[108:111]
	v_mfma_f32_16x16x32_bf16 v[100:103], v[128:131], v[160:163], v[100:103]
	v_mfma_f32_16x16x32_bf16 v[92:95], v[136:139], v[160:163], v[92:95]
	v_mfma_f32_16x16x32_bf16 v[84:87], v[128:131], v[168:171], v[84:87]
	v_mfma_f32_16x16x32_bf16 v[76:79], v[136:139], v[168:171], v[76:79]
	v_mfma_f32_16x16x32_bf16 v[124:127], v[132:135], v[148:151], v[124:127]
	v_mfma_f32_16x16x32_bf16 v[120:123], v[140:143], v[148:151], v[120:123]
	v_mfma_f32_16x16x32_bf16 v[116:119], v[132:135], v[156:159], v[116:119]
	v_mfma_f32_16x16x32_bf16 v[108:111], v[140:143], v[156:159], v[108:111]
	v_mfma_f32_16x16x32_bf16 v[100:103], v[132:135], v[164:167], v[100:103]
	v_mfma_f32_16x16x32_bf16 v[92:95], v[140:143], v[164:167], v[92:95]
	v_mfma_f32_16x16x32_bf16 v[84:87], v[132:135], v[172:175], v[84:87]
	v_mfma_f32_16x16x32_bf16 v[76:79], v[140:143], v[172:175], v[76:79]
	s_setprio 0
	s_barrier
	s_add_i32 s33, s90, s64
	v_add_u32_e32 v188, s91, v215
	s_mov_b32 m0, s33
	ds_read_b128 v[176:179], v188
	ds_read_b128 v[180:183], v188 offset:1024
	ds_read_b128 v[184:187], v188 offset:2048
	ds_read_b128 v[188:191], v188 offset:3072
	global_load_lds_dwordx4 v228, s[98:99]
	s_add_i32 m0, s33, 0x2000
	s_nop 0
	global_load_lds_dwordx4 v224, s[98:99]
	s_barrier
	s_waitcnt lgkmcnt(0)
	s_setprio 1
	v_mfma_f32_16x16x32_bf16 v[112:115], v[176:179], v[144:147], v[112:115]
	v_mfma_f32_16x16x32_bf16 v[104:107], v[184:187], v[144:147], v[104:107]
	v_mfma_f32_16x16x32_bf16 v[96:99], v[176:179], v[152:155], v[96:99]
	v_mfma_f32_16x16x32_bf16 v[88:91], v[184:187], v[152:155], v[88:91]
	v_mfma_f32_16x16x32_bf16 v[80:83], v[176:179], v[160:163], v[80:83]
	v_mfma_f32_16x16x32_bf16 v[72:75], v[184:187], v[160:163], v[72:75]
	v_mfma_f32_16x16x32_bf16 v[68:71], v[176:179], v[168:171], v[68:71]
	v_mfma_f32_16x16x32_bf16 v[64:67], v[184:187], v[168:171], v[64:67]
	v_mfma_f32_16x16x32_bf16 v[112:115], v[180:183], v[148:151], v[112:115]
	v_mfma_f32_16x16x32_bf16 v[104:107], v[188:191], v[148:151], v[104:107]
	v_mfma_f32_16x16x32_bf16 v[96:99], v[180:183], v[156:159], v[96:99]
	v_mfma_f32_16x16x32_bf16 v[88:91], v[188:191], v[156:159], v[88:91]
	v_mfma_f32_16x16x32_bf16 v[80:83], v[180:183], v[164:167], v[80:83]
	v_mfma_f32_16x16x32_bf16 v[72:75], v[188:191], v[164:167], v[72:75]
	v_mfma_f32_16x16x32_bf16 v[68:71], v[180:183], v[172:175], v[68:71]
	v_mfma_f32_16x16x32_bf16 v[64:67], v[188:191], v[172:175], v[64:67]
	s_setprio 0
	s_mov_b32 m0, s96
	s_barrier
	ds_read_b128 v[144:147], v246 offset:49152
	ds_read_b128 v[148:151], v246 offset:50176
	ds_read_b128 v[152:155], v246 offset:51200
	ds_read_b128 v[156:159], v246 offset:52224
	ds_read_b128 v[160:163], v246 offset:53248
	ds_read_b128 v[164:167], v246 offset:54272
	ds_read_b128 v[168:171], v246 offset:55296
	ds_read_b128 v[172:175], v246 offset:56320
	global_load_lds_dwordx4 v230, s[100:101]
	s_mov_b32 m0, s97
	s_nop 0
	global_load_lds_dwordx4 v226, s[100:101]
	s_barrier
; #define PG8_WAIT_V(n) asm volatile("s_waitcnt vmcnt(" #n ")" ::: "memory")
; #define PG8_BAR __builtin_amdgcn_s_barrier()
; template <class Epi, class S_t>
; __device__ __forceinline__ void gemm_phase(LAS unsigned char* lds, int lda, int ldb, const S_t& S, const Epi& E) {
;     ...
;             PG8_BAR; PG8_WAIT_L(0); PG8_MMA(1, 0, At, B0); PG8_BAR; PG8_SCHED;
;             PG8_STAGE(PG8_SB(1, 1), b3 + hstepB, voffB);
;             PG8_WAIT_V(6); PG8_BAR; PG8_MMA(1, 1, At, B1); PG8_BAR;
;     __device__ __forceinline__ void operator()(const f32x4 (&acc)[2][2][4][2], const Unit& u, int wr, int wc, int fr, int fq) const {
;     ...
;         const int j0 = u.pn * HALF + wc * 32 + 8 * fq;
;         u32x2 res0[8];
; #pragma unroll
;         for (int n = 0; n < 2; ++n) {
;             asm volatile("" ::: "memory");
;             const int jc = j0 + 4 * n;
;             const f32x4 wg0 = *(const f32x4*)(wconv + jc), wg1 = *(const f32x4*)(wconv + 2 * DFF + jc), wg2 = *(const f32x4*)(wconv + 4 * DFF + jc), bg = *(const f32x4*)(bconv + jc);
;             const f32x4 wv0 = *(const f32x4*)(wconv + DFF + jc), wv1 = *(const f32x4*)(wconv + 3 * DFF + jc), wv2 = *(const f32x4*)(wconv + 5 * DFF + jc), bv = *(const f32x4*)(bconv + DFF + jc);
; #pragma unroll
;             for (int ai = 0; ai < 2; ++ai)
; #pragma unroll
;                 for (int m = 0; m < 4; ++m) { const int row = row0 + ai * HALF + m * 16;
;                     const f32x4 g0 = acc[ai][0][m][n], v0 = acc[ai][1][m][n];
;                     f32x4 gp = (f32x4){0.f, 0.f, 0.f, 0.f}, vp = gp;
;                     if (m > 0) { gp = acc[ai][0][m > 0 ? m - 1 : 0][n]; vp = acc[ai][1][m > 0 ? m - 1 : 0][n]; }
;                     f32x4 f;
; #pragma unroll
;                     for (int j = 0; j < 4; ++j) {
;                         const float g1 = dpp_shr1(dpp_ror1(gp[j]), g0[j]), g2 = dpp_shr2(dpp_ror2(gp[j]), g0[j]);
;                         const float v1 = dpp_shr1(dpp_ror1(vp[j]), v0[j]), v2 = dpp_shr2(dpp_ror2(vp[j]), v0[j]);
;                         const float cg_ = bg[j] + g2 * wg0[j] + g1 * wg1[j] + g0[j] * wg2[j];
;                         const float cv_ = bv[j] + v2 * wv0[j] + v1 * wv1[j] + v0[j] * wv2[j];
;                         f[j] = gelu_tanh(cg_) * cv_; }
;                     u32x2 w; w.x = pk2(f[0], f[1]); w.y = pk2(f[2], f[3]);
;                     if (n == 0) res0[ai * 4 + m] = w;
	s_waitcnt lgkmcnt(0)
	s_setprio 1
	v_mfma_f32_16x16x32_bf16 v[60:63], v[128:131], v[144:147], v[60:63]
	v_mfma_f32_16x16x32_bf16 v[56:59], v[136:139], v[144:147], v[56:59]
	v_mfma_f32_16x16x32_bf16 v[52:55], v[128:131], v[152:155], v[52:55]
	v_mfma_f32_16x16x32_bf16 v[44:47], v[136:139], v[152:155], v[44:47]
	v_mfma_f32_16x16x32_bf16 v[36:39], v[128:131], v[160:163], v[36:39]
	v_mfma_f32_16x16x32_bf16 v[28:31], v[136:139], v[160:163], v[28:31]
	v_mfma_f32_16x16x32_bf16 v[20:23], v[128:131], v[168:171], v[20:23]
	v_mfma_f32_16x16x32_bf16 v[12:15], v[136:139], v[168:171], v[12:15]
	v_mfma_f32_16x16x32_bf16 v[60:63], v[132:135], v[148:151], v[60:63]
	v_mfma_f32_16x16x32_bf16 v[56:59], v[140:143], v[148:151], v[56:59]
	v_mfma_f32_16x16x32_bf16 v[52:55], v[132:135], v[156:159], v[52:55]
	v_mfma_f32_16x16x32_bf16 v[44:47], v[140:143], v[156:159], v[44:47]
	v_mfma_f32_16x16x32_bf16 v[36:39], v[132:135], v[164:167], v[36:39]
	v_mfma_f32_16x16x32_bf16 v[28:31], v[140:143], v[164:167], v[28:31]
	v_mfma_f32_16x16x32_bf16 v[20:23], v[132:135], v[172:175], v[20:23]
	v_mfma_f32_16x16x32_bf16 v[12:15], v[140:143], v[172:175], v[12:15]
	s_setprio 0
	s_barrier
	s_add_u32 s52, s76, 0x80080
	s_addc_u32 s53, s77, 0
	s_add_i32 s33, s91, s64
	s_mov_b32 m0, s33
	s_nop 0
	global_load_lds_dwordx4 v228, s[52:53]
	s_add_i32 m0, s33, 0x2000
	s_nop 0
	global_load_lds_dwordx4 v224, s[52:53]
	s_waitcnt vmcnt(6)
	s_barrier
	s_setprio 1
	v_mfma_f32_16x16x32_bf16 v[48:51], v[176:179], v[144:147], v[48:51]
	v_mfma_f32_16x16x32_bf16 v[40:43], v[184:187], v[144:147], v[40:43]
	v_mfma_f32_16x16x32_bf16 v[32:35], v[176:179], v[152:155], v[32:35]
	v_mfma_f32_16x16x32_bf16 v[24:27], v[184:187], v[152:155], v[24:27]
	v_mfma_f32_16x16x32_bf16 v[16:19], v[176:179], v[160:163], v[16:19]
	v_mfma_f32_16x16x32_bf16 v[8:11], v[184:187], v[160:163], v[8:11]
	v_mfma_f32_16x16x32_bf16 v[4:7], v[176:179], v[168:171], v[4:7]
	v_mfma_f32_16x16x32_bf16 v[0:3], v[184:187], v[168:171], v[0:3]
	v_mfma_f32_16x16x32_bf16 v[48:51], v[180:183], v[148:151], v[48:51]
	v_mfma_f32_16x16x32_bf16 v[40:43], v[188:191], v[148:151], v[40:43]
	v_mfma_f32_16x16x32_bf16 v[32:35], v[180:183], v[156:159], v[32:35]
	v_mfma_f32_16x16x32_bf16 v[24:27], v[188:191], v[156:159], v[24:27]
	v_mfma_f32_16x16x32_bf16 v[16:19], v[180:183], v[164:167], v[16:19]
	v_mfma_f32_16x16x32_bf16 v[8:11], v[188:191], v[164:167], v[8:11]
	v_mfma_f32_16x16x32_bf16 v[4:7], v[180:183], v[172:175], v[4:7]
	v_mfma_f32_16x16x32_bf16 v[0:3], v[188:191], v[172:175], v[0:3]
	s_setprio 0
	s_add_i32 s5, s5, 2
	s_add_u32 s74, s74, 0x100
	s_addc_u32 s75, s75, 0
	s_add_u32 s0, s0, 0x100
	s_addc_u32 s1, s1, 0
	s_cmp_gt_u32 s5, 29
	s_cbranch_scc0 .Lrot_1200
	s_barrier
	s_lshl_b32 s5, s72, 8
	s_add_i32 s5, s5, s95
	v_or_b32_e32 v248, s5, v232
	s_cmp_lt_i32 s72, 32
	v_lshl_or_b32 v240, s42, 8, v219
	s_cbranch_scc0 .LBB0_1215
	v_lshl_or_b32 v130, s42, 7, v219
	v_readlane_b32 s16, v254, 33
	v_readlane_b32 s17, v254, 34
	v_readlane_b32 s18, v254, 35
	v_readlane_b32 s19, v254, 36
	v_readlane_b32 s20, v254, 37
	v_readlane_b32 s21, v254, 38
	v_readlane_b32 s22, v254, 39
	v_readlane_b32 s23, v254, 40
	v_readlane_b32 s24, v254, 41
	v_readlane_b32 s25, v254, 42
	v_readlane_b32 s26, v254, 43
	v_readlane_b32 s27, v254, 44
	v_readlane_b32 s28, v254, 45
	v_readlane_b32 s29, v254, 46
	v_readlane_b32 s30, v254, 47
	v_readlane_b32 s31, v254, 48
	v_ashrrev_i32_e32 v131, 31, v130
	s_ashr_i32 s72, s5, 6
	v_lshlrev_b64 v[128:129], 2, v[130:131]
	s_lshl_b32 s72, s72, 2
	s_add_i32 s73, s72, 8
	v_readfirstlane_b32 s98, v212
	v_and_b32_e32 v249, 48, v212
	s_lshr_b32 s98, s98, 6
	s_lshl_b32 s98, s98, 10
	s_add_i32 s98, s98, 0x20840
	v_lshl_add_u32 v249, v249, 1, s98
	ds_read_b128 v[146:149], v249 offset:768
	ds_read_b128 v[178:181], v249 offset:784
	ds_read_b128 v[158:161], v249 offset:512
	ds_read_b128 v[190:193], v249 offset:528
	ds_read_b128 v[162:165], v249 offset:896
	ds_read_b128 v[194:197], v249 offset:912
	ds_read_b128 v[174:177], v249 offset:640
	ds_read_b128 v[206:209], v249 offset:656
	ds_read_b128 v[154:157], v249 offset:256
	ds_read_b128 v[186:189], v249 offset:272
	ds_read_b128 v[170:173], v249 offset:384
	ds_read_b128 v[202:205], v249 offset:400
	ds_read_b128 v[150:153], v249 offset:0
	ds_read_b128 v[182:185], v249 offset:16
	ds_read_b128 v[166:169], v249 offset:128
	ds_read_b128 v[198:201], v249 offset:144
	v_lshl_add_u64 v[242:243], v[130:131], 1, s[40:41]
	v_ashrrev_i32_e32 v241, 31, v240
	s_mov_b32 s98, 0xbdd2d3e8
	s_mov_b32 s99, 0xbdd2d3e8
	s_mov_b32 s100, 1.0
	s_mov_b32 s101, 1.0
	v_mov_b32_e32 v244, 0xc0135761
	v_mov_b32_e32 v245, 0xc0135761
	s_and_saveexec_b64 s[42:43], s[10:11]
	v_or_b32_e32 v144, s72, v232
	v_mov_b64_e32 v[128:129], s[80:81]
	v_mad_u64_u32 v[128:129], vcc, v144, s83, v[128:129]
	v_lshl_add_u64 v[128:129], v[240:241], 1, v[128:129]
	v_cvt_pk_bf16_f32 v132, v124, v125
	v_cvt_pk_bf16_f32 v133, v126, v127
	v_cvt_pk_bf16_f32 v134, v120, v121
	v_cvt_pk_bf16_f32 v135, v122, v123
	v_cvt_pk_bf16_f32 v136, v112, v113
	v_cvt_pk_bf16_f32 v137, v114, v115
	v_cvt_pk_bf16_f32 v138, v104, v105
	v_cvt_pk_bf16_f32 v139, v106, v107
	global_store_dwordx4 v[128:129], v[132:135], off
	global_store_dwordx4 v[128:129], v[136:139], off offset:256
	v_or_b32_e32 v144, s73, v232
	v_mov_b64_e32 v[130:131], s[80:81]
	v_mad_u64_u32 v[130:131], vcc, v144, s83, v[130:131]
	v_lshl_add_u64 v[130:131], v[240:241], 1, v[130:131]
	v_cvt_pk_bf16_f32 v140, v60, v61
	v_cvt_pk_bf16_f32 v141, v62, v63
	v_cvt_pk_bf16_f32 v142, v56, v57
	v_cvt_pk_bf16_f32 v143, v58, v59
	v_cvt_pk_bf16_f32 v250, v48, v49
	v_cvt_pk_bf16_f32 v251, v50, v51
	v_cvt_pk_bf16_f32 v252, v40, v41
	v_cvt_pk_bf16_f32 v253, v42, v43
	global_store_dwordx4 v[130:131], v[140:143], off
	global_store_dwordx4 v[130:131], v[250:253], off offset:256
	s_or_b64 exec, exec, s[42:43]
	s_and_saveexec_b64 s[42:43], s[12:13]
	v_add_u32_e32 v144, s72, v234
	v_mov_b64_e32 v[128:129], s[80:81]
	v_mad_u64_u32 v[128:129], vcc, v144, s83, v[128:129]
	v_lshl_add_u64 v[128:129], v[240:241], 1, v[128:129]
	v_cvt_pk_bf16_f32 v132, v84, v85
	v_cvt_pk_bf16_f32 v133, v86, v87
	v_cvt_pk_bf16_f32 v134, v76, v77
	v_cvt_pk_bf16_f32 v135, v78, v79
	v_cvt_pk_bf16_f32 v136, v68, v69
	v_cvt_pk_bf16_f32 v137, v70, v71
	v_cvt_pk_bf16_f32 v138, v64, v65
	v_cvt_pk_bf16_f32 v139, v66, v67
	global_store_dwordx4 v[128:129], v[132:135], off
	global_store_dwordx4 v[128:129], v[136:139], off offset:256
	s_or_b64 exec, exec, s[42:43]
	s_waitcnt lgkmcnt(0)
; __device__ __forceinline__ unsigned pk2(float lo, float hi) { unsigned r; asm("v_cvt_pk_bf16_f32 %0, %1, %2" : "=v"(r) : "v"(lo), "v"(hi)); return r; }
; __device__ __forceinline__ float gelu_tanh(float x) { const float y = 1.5957691216f * (x + 0.044715f * x * x * x); return x * __builtin_amdgcn_rcpf(1.0f + __expf(-y)); }
; __device__ __forceinline__ float dpp_shr1(float old, float src) { return __int_as_float(__builtin_amdgcn_update_dpp(__float_as_int(old), __float_as_int(src), 0x111, 0xf, 0xf, false)); }
; __device__ __forceinline__ float dpp_shr2(float old, float src) { return __int_as_float(__builtin_amdgcn_update_dpp(__float_as_int(old), __float_as_int(src), 0x112, 0xf, 0xf, false)); }
; __device__ __forceinline__ float dpp_ror1(float src) { return __int_as_float(__builtin_amdgcn_update_dpp(0, __float_as_int(src), 0x121, 0xf, 0xf, false)); }
;     __device__ __forceinline__ void operator()(const f32x4 (&acc)[2][2][4][2], const Unit& u, int wr, int wc, int fr, int fq) const {
;     ...
; #pragma unroll
;                 for (int m = 0; m < 4; ++m) { const int row = row0 + ai * HALF + m * 16;
;                     const f32x4 g0 = acc[ai][0][m][n], v0 = acc[ai][1][m][n];
;                     f32x4 gp = (f32x4){0.f, 0.f, 0.f, 0.f}, vp = gp;
;                     if (m > 0) { gp = acc[ai][0][m > 0 ? m - 1 : 0][n]; vp = acc[ai][1][m > 0 ? m - 1 : 0][n]; }
;                     f32x4 f;
; #pragma unroll
;                     for (int j = 0; j < 4; ++j) {
;                         const float g1 = dpp_shr1(dpp_ror1(gp[j]), g0[j]), g2 = dpp_shr2(dpp_ror2(gp[j]), g0[j]);
;                         const float v1 = dpp_shr1(dpp_ror1(vp[j]), v0[j]), v2 = dpp_shr2(dpp_ror2(vp[j]), v0[j]);
;                         const float cg_ = bg[j] + g2 * wg0[j] + g1 * wg1[j] + g0[j] * wg2[j];
;                         const float cv_ = bv[j] + v2 * wv0[j] + v1 * wv1[j] + v0[j] * wv2[j];
;                         f[j] = gelu_tanh(cg_) * cv_; }
;                     u32x2 w; w.x = pk2(f[0], f[1]); w.y = pk2(f[2], f[3]);
;                     if (n == 0) res0[ai * 4 + m] = w;
;                     else if (m > 0 || fr >= 2) { u32x4 w4; w4.x = res0[ai * 4 + m].x; w4.y = res0[ai * 4 + m].y; w4.z = w.x; w4.w = w.y; *(u32x4*)(F + (size_t)row * DFF + j0) = w4; }
	s_nop 4
	v_pk_fma_f32 v[132:133], v[124:125], v[158:159], v[146:147]
	v_pk_fma_f32 v[136:137], v[112:113], v[174:175], v[162:163]
	v_pk_fma_f32 v[134:135], v[126:127], v[160:161], v[148:149]
	v_pk_fma_f32 v[138:139], v[114:115], v[176:177], v[164:165]
	v_fmac_f32_dpp v132, v124, v154 row_shr:1 row_mask:0xf bank_mask:0xf
	v_fmac_f32_dpp v133, v125, v155 row_shr:1 row_mask:0xf bank_mask:0xf
	v_fmac_f32_dpp v134, v126, v156 row_shr:1 row_mask:0xf bank_mask:0xf
	v_fmac_f32_dpp v135, v127, v157 row_shr:1 row_mask:0xf bank_mask:0xf
	v_fmac_f32_dpp v136, v112, v170 row_shr:1 row_mask:0xf bank_mask:0xf
	v_fmac_f32_dpp v137, v113, v171 row_shr:1 row_mask:0xf bank_mask:0xf
	v_fmac_f32_dpp v138, v114, v172 row_shr:1 row_mask:0xf bank_mask:0xf
	v_fmac_f32_dpp v139, v115, v173 row_shr:1 row_mask:0xf bank_mask:0xf
	v_fmac_f32_dpp v132, v124, v150 row_shr:2 row_mask:0xf bank_mask:0xf
	v_fmac_f32_dpp v133, v125, v151 row_shr:2 row_mask:0xf bank_mask:0xf
	v_fmac_f32_dpp v134, v126, v152 row_shr:2 row_mask:0xf bank_mask:0xf
	v_fmac_f32_dpp v135, v127, v153 row_shr:2 row_mask:0xf bank_mask:0xf
	v_fmac_f32_dpp v136, v112, v166 row_shr:2 row_mask:0xf bank_mask:0xf
	v_fmac_f32_dpp v137, v113, v167 row_shr:2 row_mask:0xf bank_mask:0xf
	v_fmac_f32_dpp v138, v114, v168 row_shr:2 row_mask:0xf bank_mask:0xf
	v_fmac_f32_dpp v139, v115, v169 row_shr:2 row_mask:0xf bank_mask:0xf
	v_pk_mul_f32 v[140:141], v[132:133], v[132:133]
	v_pk_mul_f32 v[142:143], v[134:135], v[134:135]
	v_pk_fma_f32 v[140:141], v[140:141], s[98:99], v[244:245]
	v_pk_fma_f32 v[142:143], v[142:143], s[98:99], v[244:245]
	v_pk_mul_f32 v[140:141], v[132:133], v[140:141]
	v_pk_mul_f32 v[142:143], v[134:135], v[142:143]
	v_exp_f32_e32 v140, v140
	v_exp_f32_e32 v141, v141
	v_exp_f32_e32 v142, v142
	v_exp_f32_e32 v143, v143
	v_pk_add_f32 v[140:141], v[140:141], s[100:101]
	v_pk_add_f32 v[142:143], v[142:143], s[100:101]
	v_rcp_f32_e32 v140, v140
	v_rcp_f32_e32 v141, v141
	v_rcp_f32_e32 v142, v142
	v_rcp_f32_e32 v143, v143
	v_pk_mul_f32 v[140:141], v[132:133], v[140:141]
	v_pk_mul_f32 v[142:143], v[134:135], v[142:143]
	v_pk_mul_f32 v[140:141], v[140:141], v[136:137]
	v_pk_mul_f32 v[142:143], v[142:143], v[138:139]
	v_cvt_pk_bf16_f32 v128, v140, v141
	v_cvt_pk_bf16_f32 v129, v142, v143
	v_pk_fma_f32 v[132:133], v[120:121], v[190:191], v[178:179]
	v_pk_fma_f32 v[136:137], v[104:105], v[206:207], v[194:195]
	v_pk_fma_f32 v[134:135], v[122:123], v[192:193], v[180:181]
	v_pk_fma_f32 v[138:139], v[106:107], v[208:209], v[196:197]
	v_fmac_f32_dpp v132, v120, v186 row_shr:1 row_mask:0xf bank_mask:0xf
	v_fmac_f32_dpp v133, v121, v187 row_shr:1 row_mask:0xf bank_mask:0xf
	v_fmac_f32_dpp v134, v122, v188 row_shr:1 row_mask:0xf bank_mask:0xf
	v_fmac_f32_dpp v135, v123, v189 row_shr:1 row_mask:0xf bank_mask:0xf
	v_fmac_f32_dpp v136, v104, v202 row_shr:1 row_mask:0xf bank_mask:0xf
	v_fmac_f32_dpp v137, v105, v203 row_shr:1 row_mask:0xf bank_mask:0xf
	v_fmac_f32_dpp v138, v106, v204 row_shr:1 row_mask:0xf bank_mask:0xf
	v_fmac_f32_dpp v139, v107, v205 row_shr:1 row_mask:0xf bank_mask:0xf
	v_fmac_f32_dpp v132, v120, v182 row_shr:2 row_mask:0xf bank_mask:0xf
	v_fmac_f32_dpp v133, v121, v183 row_shr:2 row_mask:0xf bank_mask:0xf
	v_fmac_f32_dpp v134, v122, v184 row_shr:2 row_mask:0xf bank_mask:0xf
	v_fmac_f32_dpp v135, v123, v185 row_shr:2 row_mask:0xf bank_mask:0xf
	v_fmac_f32_dpp v136, v104, v198 row_shr:2 row_mask:0xf bank_mask:0xf
	v_fmac_f32_dpp v137, v105, v199 row_shr:2 row_mask:0xf bank_mask:0xf
	v_fmac_f32_dpp v138, v106, v200 row_shr:2 row_mask:0xf bank_mask:0xf
	v_fmac_f32_dpp v139, v107, v201 row_shr:2 row_mask:0xf bank_mask:0xf
	v_pk_mul_f32 v[140:141], v[132:133], v[132:133]
	v_pk_mul_f32 v[142:143], v[134:135], v[134:135]
	v_pk_fma_f32 v[140:141], v[140:141], s[98:99], v[244:245]
	v_pk_fma_f32 v[142:143], v[142:143], s[98:99], v[244:245]
	v_pk_mul_f32 v[140:141], v[132:133], v[140:141]
	v_pk_mul_f32 v[142:143], v[134:135], v[142:143]
	v_exp_f32_e32 v140, v140
	v_exp_f32_e32 v141, v141
	v_exp_f32_e32 v142, v142
	v_exp_f32_e32 v143, v143
	v_pk_add_f32 v[140:141], v[140:141], s[100:101]
	v_pk_add_f32 v[142:143], v[142:143], s[100:101]
	v_rcp_f32_e32 v140, v140
	v_rcp_f32_e32 v141, v141
	v_rcp_f32_e32 v142, v142
	v_rcp_f32_e32 v143, v143
	v_pk_mul_f32 v[140:141], v[132:133], v[140:141]
	v_pk_mul_f32 v[142:143], v[134:135], v[142:143]
	v_pk_mul_f32 v[140:141], v[140:141], v[136:137]
	v_pk_mul_f32 v[142:143], v[142:143], v[138:139]
	v_cvt_pk_bf16_f32 v130, v140, v141
	v_cvt_pk_bf16_f32 v131, v142, v143
	s_and_saveexec_b64 s[42:43], s[8:9]
	v_mad_u64_u32 v[144:145], vcc, v248, s4, v[242:243]
	global_store_dwordx4 v[144:145], v[128:131], off nt
	s_or_b64 exec, exec, s[42:43]
	s_nop 4
	v_pk_fma_f32 v[132:133], v[116:117], v[158:159], v[146:147]
	v_pk_fma_f32 v[136:137], v[96:97], v[174:175], v[162:163]
	v_pk_fma_f32 v[134:135], v[118:119], v[160:161], v[148:149]
	v_pk_fma_f32 v[138:139], v[98:99], v[176:177], v[164:165]
	v_fmac_f32_dpp v132, v116, v154 row_shr:1 row_mask:0xf bank_mask:0xf
	v_fmac_f32_dpp v133, v117, v155 row_shr:1 row_mask:0xf bank_mask:0xf
	v_fmac_f32_dpp v134, v118, v156 row_shr:1 row_mask:0xf bank_mask:0xf
	v_fmac_f32_dpp v135, v119, v157 row_shr:1 row_mask:0xf bank_mask:0xf
	v_fmac_f32_dpp v136, v96, v170 row_shr:1 row_mask:0xf bank_mask:0xf
	v_fmac_f32_dpp v137, v97, v171 row_shr:1 row_mask:0xf bank_mask:0xf
	v_fmac_f32_dpp v138, v98, v172 row_shr:1 row_mask:0xf bank_mask:0xf
	v_fmac_f32_dpp v139, v99, v173 row_shr:1 row_mask:0xf bank_mask:0xf
	v_fmac_f32_dpp v132, v124, v154 row_shl:15 row_mask:0xf bank_mask:0xf
	v_fmac_f32_dpp v133, v125, v155 row_shl:15 row_mask:0xf bank_mask:0xf
; __device__ __forceinline__ unsigned pk2(float lo, float hi) { unsigned r; asm("v_cvt_pk_bf16_f32 %0, %1, %2" : "=v"(r) : "v"(lo), "v"(hi)); return r; }
; __device__ __forceinline__ float gelu_tanh(float x) { const float y = 1.5957691216f * (x + 0.044715f * x * x * x); return x * __builtin_amdgcn_rcpf(1.0f + __expf(-y)); }
; __device__ __forceinline__ float dpp_shr1(float old, float src) { return __int_as_float(__builtin_amdgcn_update_dpp(__float_as_int(old), __float_as_int(src), 0x111, 0xf, 0xf, false)); }
; __device__ __forceinline__ float dpp_shr2(float old, float src) { return __int_as_float(__builtin_amdgcn_update_dpp(__float_as_int(old), __float_as_int(src), 0x112, 0xf, 0xf, false)); }
; __device__ __forceinline__ float dpp_ror1(float src) { return __int_as_float(__builtin_amdgcn_update_dpp(0, __float_as_int(src), 0x121, 0xf, 0xf, false)); }
;     __device__ __forceinline__ void operator()(const f32x4 (&acc)[2][2][4][2], const Unit& u, int wr, int wc, int fr, int fq) const {
;     ...
; #pragma unroll
;                 for (int m = 0; m < 4; ++m) { const int row = row0 + ai * HALF + m * 16;
;                     const f32x4 g0 = acc[ai][0][m][n], v0 = acc[ai][1][m][n];
;                     f32x4 gp = (f32x4){0.f, 0.f, 0.f, 0.f}, vp = gp;
;                     if (m > 0) { gp = acc[ai][0][m > 0 ? m - 1 : 0][n]; vp = acc[ai][1][m > 0 ? m - 1 : 0][n]; }
;                     f32x4 f;
; #pragma unroll
;                     for (int j = 0; j < 4; ++j) {
;                         const float g1 = dpp_shr1(dpp_ror1(gp[j]), g0[j]), g2 = dpp_shr2(dpp_ror2(gp[j]), g0[j]);
;                         const float v1 = dpp_shr1(dpp_ror1(vp[j]), v0[j]), v2 = dpp_shr2(dpp_ror2(vp[j]), v0[j]);
;                         const float cg_ = bg[j] + g2 * wg0[j] + g1 * wg1[j] + g0[j] * wg2[j];
;                         const float cv_ = bv[j] + v2 * wv0[j] + v1 * wv1[j] + v0[j] * wv2[j];
;                         f[j] = gelu_tanh(cg_) * cv_; }
;                     u32x2 w; w.x = pk2(f[0], f[1]); w.y = pk2(f[2], f[3]);
;                     if (n == 0) res0[ai * 4 + m] = w;
;                     else if (m > 0 || fr >= 2) { u32x4 w4; w4.x = res0[ai * 4 + m].x; w4.y = res0[ai * 4 + m].y; w4.z = w.x; w4.w = w.y; *(u32x4*)(F + (size_t)row * DFF + j0) = w4; }
	v_fmac_f32_dpp v134, v126, v156 row_shl:15 row_mask:0xf bank_mask:0xf
	v_fmac_f32_dpp v135, v127, v157 row_shl:15 row_mask:0xf bank_mask:0xf
	v_fmac_f32_dpp v136, v112, v170 row_shl:15 row_mask:0xf bank_mask:0xf
	v_fmac_f32_dpp v137, v113, v171 row_shl:15 row_mask:0xf bank_mask:0xf
	v_fmac_f32_dpp v138, v114, v172 row_shl:15 row_mask:0xf bank_mask:0xf
	v_fmac_f32_dpp v139, v115, v173 row_shl:15 row_mask:0xf bank_mask:0xf
	v_fmac_f32_dpp v132, v116, v150 row_shr:2 row_mask:0xf bank_mask:0xf
	v_fmac_f32_dpp v133, v117, v151 row_shr:2 row_mask:0xf bank_mask:0xf
	v_fmac_f32_dpp v134, v118, v152 row_shr:2 row_mask:0xf bank_mask:0xf
	v_fmac_f32_dpp v135, v119, v153 row_shr:2 row_mask:0xf bank_mask:0xf
	v_fmac_f32_dpp v136, v96, v166 row_shr:2 row_mask:0xf bank_mask:0xf
	v_fmac_f32_dpp v137, v97, v167 row_shr:2 row_mask:0xf bank_mask:0xf
	v_fmac_f32_dpp v138, v98, v168 row_shr:2 row_mask:0xf bank_mask:0xf
	v_fmac_f32_dpp v139, v99, v169 row_shr:2 row_mask:0xf bank_mask:0xf
	v_fmac_f32_dpp v132, v124, v150 row_shl:14 row_mask:0xf bank_mask:0xf
	v_fmac_f32_dpp v133, v125, v151 row_shl:14 row_mask:0xf bank_mask:0xf
	v_fmac_f32_dpp v134, v126, v152 row_shl:14 row_mask:0xf bank_mask:0xf
	v_fmac_f32_dpp v135, v127, v153 row_shl:14 row_mask:0xf bank_mask:0xf
	v_fmac_f32_dpp v136, v112, v166 row_shl:14 row_mask:0xf bank_mask:0xf
	v_fmac_f32_dpp v137, v113, v167 row_shl:14 row_mask:0xf bank_mask:0xf
	v_fmac_f32_dpp v138, v114, v168 row_shl:14 row_mask:0xf bank_mask:0xf
	v_fmac_f32_dpp v139, v115, v169 row_shl:14 row_mask:0xf bank_mask:0xf
	v_pk_mul_f32 v[140:141], v[132:133], v[132:133]
	v_pk_mul_f32 v[142:143], v[134:135], v[134:135]
	v_pk_fma_f32 v[140:141], v[140:141], s[98:99], v[244:245]
	v_pk_fma_f32 v[142:143], v[142:143], s[98:99], v[244:245]
	v_pk_mul_f32 v[140:141], v[132:133], v[140:141]
	v_pk_mul_f32 v[142:143], v[134:135], v[142:143]
	v_exp_f32_e32 v140, v140
	v_exp_f32_e32 v141, v141
	v_exp_f32_e32 v142, v142
	v_exp_f32_e32 v143, v143
	v_pk_add_f32 v[140:141], v[140:141], s[100:101]
	v_pk_add_f32 v[142:143], v[142:143], s[100:101]
	v_rcp_f32_e32 v140, v140
	v_rcp_f32_e32 v141, v141
	v_rcp_f32_e32 v142, v142
	v_rcp_f32_e32 v143, v143
	v_pk_mul_f32 v[140:141], v[132:133], v[140:141]
	v_pk_mul_f32 v[142:143], v[134:135], v[142:143]
	v_pk_mul_f32 v[140:141], v[140:141], v[136:137]
	v_pk_mul_f32 v[142:143], v[142:143], v[138:139]
	v_cvt_pk_bf16_f32 v250, v140, v141
	v_cvt_pk_bf16_f32 v251, v142, v143
	v_pk_fma_f32 v[132:133], v[108:109], v[190:191], v[178:179]
	v_pk_fma_f32 v[136:137], v[88:89], v[206:207], v[194:195]
	v_pk_fma_f32 v[134:135], v[110:111], v[192:193], v[180:181]
	v_pk_fma_f32 v[138:139], v[90:91], v[208:209], v[196:197]
	v_fmac_f32_dpp v132, v108, v186 row_shr:1 row_mask:0xf bank_mask:0xf
	v_fmac_f32_dpp v133, v109, v187 row_shr:1 row_mask:0xf bank_mask:0xf
	v_fmac_f32_dpp v134, v110, v188 row_shr:1 row_mask:0xf bank_mask:0xf
	v_fmac_f32_dpp v135, v111, v189 row_shr:1 row_mask:0xf bank_mask:0xf
	v_fmac_f32_dpp v136, v88, v202 row_shr:1 row_mask:0xf bank_mask:0xf
	v_fmac_f32_dpp v137, v89, v203 row_shr:1 row_mask:0xf bank_mask:0xf
	v_fmac_f32_dpp v138, v90, v204 row_shr:1 row_mask:0xf bank_mask:0xf
	v_fmac_f32_dpp v139, v91, v205 row_shr:1 row_mask:0xf bank_mask:0xf
	v_fmac_f32_dpp v132, v120, v186 row_shl:15 row_mask:0xf bank_mask:0xf
	v_fmac_f32_dpp v133, v121, v187 row_shl:15 row_mask:0xf bank_mask:0xf
	v_fmac_f32_dpp v134, v122, v188 row_shl:15 row_mask:0xf bank_mask:0xf
	v_fmac_f32_dpp v135, v123, v189 row_shl:15 row_mask:0xf bank_mask:0xf
	v_fmac_f32_dpp v136, v104, v202 row_shl:15 row_mask:0xf bank_mask:0xf
	v_fmac_f32_dpp v137, v105, v203 row_shl:15 row_mask:0xf bank_mask:0xf
	v_fmac_f32_dpp v138, v106, v204 row_shl:15 row_mask:0xf bank_mask:0xf
	v_fmac_f32_dpp v139, v107, v205 row_shl:15 row_mask:0xf bank_mask:0xf
	v_fmac_f32_dpp v132, v108, v182 row_shr:2 row_mask:0xf bank_mask:0xf
	v_fmac_f32_dpp v133, v109, v183 row_shr:2 row_mask:0xf bank_mask:0xf
	v_fmac_f32_dpp v134, v110, v184 row_shr:2 row_mask:0xf bank_mask:0xf
	v_fmac_f32_dpp v135, v111, v185 row_shr:2 row_mask:0xf bank_mask:0xf
	v_fmac_f32_dpp v136, v88, v198 row_shr:2 row_mask:0xf bank_mask:0xf
	v_fmac_f32_dpp v137, v89, v199 row_shr:2 row_mask:0xf bank_mask:0xf
	v_fmac_f32_dpp v138, v90, v200 row_shr:2 row_mask:0xf bank_mask:0xf
	v_fmac_f32_dpp v139, v91, v201 row_shr:2 row_mask:0xf bank_mask:0xf
	v_fmac_f32_dpp v132, v120, v182 row_shl:14 row_mask:0xf bank_mask:0xf
	v_fmac_f32_dpp v133, v121, v183 row_shl:14 row_mask:0xf bank_mask:0xf
	v_fmac_f32_dpp v134, v122, v184 row_shl:14 row_mask:0xf bank_mask:0xf
	v_fmac_f32_dpp v135, v123, v185 row_shl:14 row_mask:0xf bank_mask:0xf
	v_fmac_f32_dpp v136, v104, v198 row_shl:14 row_mask:0xf bank_mask:0xf
	v_fmac_f32_dpp v137, v105, v199 row_shl:14 row_mask:0xf bank_mask:0xf
	v_fmac_f32_dpp v138, v106, v200 row_shl:14 row_mask:0xf bank_mask:0xf
	v_fmac_f32_dpp v139, v107, v201 row_shl:14 row_mask:0xf bank_mask:0xf
	v_pk_mul_f32 v[140:141], v[132:133], v[132:133]
	v_pk_mul_f32 v[142:143], v[134:135], v[134:135]
	v_pk_fma_f32 v[140:141], v[140:141], s[98:99], v[244:245]
	v_pk_fma_f32 v[142:143], v[142:143], s[98:99], v[244:245]
	v_pk_mul_f32 v[140:141], v[132:133], v[140:141]
	v_pk_mul_f32 v[142:143], v[134:135], v[142:143]
	v_exp_f32_e32 v140, v140
	v_exp_f32_e32 v141, v141
	v_exp_f32_e32 v142, v142
	v_exp_f32_e32 v143, v143
	v_pk_add_f32 v[140:141], v[140:141], s[100:101]
	v_pk_add_f32 v[142:143], v[142:143], s[100:101]
	v_rcp_f32_e32 v140, v140
	v_rcp_f32_e32 v141, v141
	v_rcp_f32_e32 v142, v142
	v_rcp_f32_e32 v143, v143
	v_pk_mul_f32 v[140:141], v[132:133], v[140:141]
	v_pk_mul_f32 v[142:143], v[134:135], v[142:143]
; __device__ __forceinline__ unsigned pk2(float lo, float hi) { unsigned r; asm("v_cvt_pk_bf16_f32 %0, %1, %2" : "=v"(r) : "v"(lo), "v"(hi)); return r; }
; __device__ __forceinline__ float gelu_tanh(float x) { const float y = 1.5957691216f * (x + 0.044715f * x * x * x); return x * __builtin_amdgcn_rcpf(1.0f + __expf(-y)); }
; __device__ __forceinline__ float dpp_shr1(float old, float src) { return __int_as_float(__builtin_amdgcn_update_dpp(__float_as_int(old), __float_as_int(src), 0x111, 0xf, 0xf, false)); }
; __device__ __forceinline__ float dpp_shr2(float old, float src) { return __int_as_float(__builtin_amdgcn_update_dpp(__float_as_int(old), __float_as_int(src), 0x112, 0xf, 0xf, false)); }
; __device__ __forceinline__ float dpp_ror1(float src) { return __int_as_float(__builtin_amdgcn_update_dpp(0, __float_as_int(src), 0x121, 0xf, 0xf, false)); }
;     __device__ __forceinline__ void operator()(const f32x4 (&acc)[2][2][4][2], const Unit& u, int wr, int wc, int fr, int fq) const {
;     ...
; #pragma unroll
;                 for (int m = 0; m < 4; ++m) { const int row = row0 + ai * HALF + m * 16;
;                     const f32x4 g0 = acc[ai][0][m][n], v0 = acc[ai][1][m][n];
;                     f32x4 gp = (f32x4){0.f, 0.f, 0.f, 0.f}, vp = gp;
;                     if (m > 0) { gp = acc[ai][0][m > 0 ? m - 1 : 0][n]; vp = acc[ai][1][m > 0 ? m - 1 : 0][n]; }
;                     f32x4 f;
; #pragma unroll
;                     for (int j = 0; j < 4; ++j) {
;                         const float g1 = dpp_shr1(dpp_ror1(gp[j]), g0[j]), g2 = dpp_shr2(dpp_ror2(gp[j]), g0[j]);
;                         const float v1 = dpp_shr1(dpp_ror1(vp[j]), v0[j]), v2 = dpp_shr2(dpp_ror2(vp[j]), v0[j]);
;                         const float cg_ = bg[j] + g2 * wg0[j] + g1 * wg1[j] + g0[j] * wg2[j];
;                         const float cv_ = bv[j] + v2 * wv0[j] + v1 * wv1[j] + v0[j] * wv2[j];
;                         f[j] = gelu_tanh(cg_) * cv_; }
;                     u32x2 w; w.x = pk2(f[0], f[1]); w.y = pk2(f[2], f[3]);
;                     if (n == 0) res0[ai * 4 + m] = w;
;                     else if (m > 0 || fr >= 2) { u32x4 w4; w4.x = res0[ai * 4 + m].x; w4.y = res0[ai * 4 + m].y; w4.z = w.x; w4.w = w.y; *(u32x4*)(F + (size_t)row * DFF + j0) = w4; }
	v_pk_mul_f32 v[140:141], v[140:141], v[136:137]
	v_pk_mul_f32 v[142:143], v[142:143], v[138:139]
	v_cvt_pk_bf16_f32 v252, v140, v141
	v_cvt_pk_bf16_f32 v253, v142, v143
	v_add_u32_e32 v144, 0x10, v248
	v_mad_u64_u32 v[144:145], vcc, v144, s4, v[242:243]
	global_store_dwordx4 v[144:145], v[250:253], off nt
	v_pk_fma_f32 v[132:133], v[100:101], v[158:159], v[146:147]
	v_pk_fma_f32 v[136:137], v[80:81], v[174:175], v[162:163]
	v_pk_fma_f32 v[134:135], v[102:103], v[160:161], v[148:149]
	v_pk_fma_f32 v[138:139], v[82:83], v[176:177], v[164:165]
	v_fmac_f32_dpp v132, v100, v154 row_shr:1 row_mask:0xf bank_mask:0xf
	v_fmac_f32_dpp v133, v101, v155 row_shr:1 row_mask:0xf bank_mask:0xf
	v_fmac_f32_dpp v134, v102, v156 row_shr:1 row_mask:0xf bank_mask:0xf
	v_fmac_f32_dpp v135, v103, v157 row_shr:1 row_mask:0xf bank_mask:0xf
	v_fmac_f32_dpp v136, v80, v170 row_shr:1 row_mask:0xf bank_mask:0xf
	v_fmac_f32_dpp v137, v81, v171 row_shr:1 row_mask:0xf bank_mask:0xf
	v_fmac_f32_dpp v138, v82, v172 row_shr:1 row_mask:0xf bank_mask:0xf
	v_fmac_f32_dpp v139, v83, v173 row_shr:1 row_mask:0xf bank_mask:0xf
	v_fmac_f32_dpp v132, v116, v154 row_shl:15 row_mask:0xf bank_mask:0xf
	v_fmac_f32_dpp v133, v117, v155 row_shl:15 row_mask:0xf bank_mask:0xf
	v_fmac_f32_dpp v134, v118, v156 row_shl:15 row_mask:0xf bank_mask:0xf
	v_fmac_f32_dpp v135, v119, v157 row_shl:15 row_mask:0xf bank_mask:0xf
	v_fmac_f32_dpp v136, v96, v170 row_shl:15 row_mask:0xf bank_mask:0xf
	v_fmac_f32_dpp v137, v97, v171 row_shl:15 row_mask:0xf bank_mask:0xf
	v_fmac_f32_dpp v138, v98, v172 row_shl:15 row_mask:0xf bank_mask:0xf
	v_fmac_f32_dpp v139, v99, v173 row_shl:15 row_mask:0xf bank_mask:0xf
	v_fmac_f32_dpp v132, v100, v150 row_shr:2 row_mask:0xf bank_mask:0xf
	v_fmac_f32_dpp v133, v101, v151 row_shr:2 row_mask:0xf bank_mask:0xf
	v_fmac_f32_dpp v134, v102, v152 row_shr:2 row_mask:0xf bank_mask:0xf
	v_fmac_f32_dpp v135, v103, v153 row_shr:2 row_mask:0xf bank_mask:0xf
	v_fmac_f32_dpp v136, v80, v166 row_shr:2 row_mask:0xf bank_mask:0xf
	v_fmac_f32_dpp v137, v81, v167 row_shr:2 row_mask:0xf bank_mask:0xf
	v_fmac_f32_dpp v138, v82, v168 row_shr:2 row_mask:0xf bank_mask:0xf
	v_fmac_f32_dpp v139, v83, v169 row_shr:2 row_mask:0xf bank_mask:0xf
	v_fmac_f32_dpp v132, v116, v150 row_shl:14 row_mask:0xf bank_mask:0xf
	v_fmac_f32_dpp v133, v117, v151 row_shl:14 row_mask:0xf bank_mask:0xf
	v_fmac_f32_dpp v134, v118, v152 row_shl:14 row_mask:0xf bank_mask:0xf
	v_fmac_f32_dpp v135, v119, v153 row_shl:14 row_mask:0xf bank_mask:0xf
	v_fmac_f32_dpp v136, v96, v166 row_shl:14 row_mask:0xf bank_mask:0xf
	v_fmac_f32_dpp v137, v97, v167 row_shl:14 row_mask:0xf bank_mask:0xf
	v_fmac_f32_dpp v138, v98, v168 row_shl:14 row_mask:0xf bank_mask:0xf
	v_fmac_f32_dpp v139, v99, v169 row_shl:14 row_mask:0xf bank_mask:0xf
	v_pk_mul_f32 v[140:141], v[132:133], v[132:133]
	v_pk_mul_f32 v[142:143], v[134:135], v[134:135]
	v_pk_fma_f32 v[140:141], v[140:141], s[98:99], v[244:245]
	v_pk_fma_f32 v[142:143], v[142:143], s[98:99], v[244:245]
	v_pk_mul_f32 v[140:141], v[132:133], v[140:141]
	v_pk_mul_f32 v[142:143], v[134:135], v[142:143]
	v_exp_f32_e32 v140, v140
	v_exp_f32_e32 v141, v141
	v_exp_f32_e32 v142, v142
	v_exp_f32_e32 v143, v143
	v_pk_add_f32 v[140:141], v[140:141], s[100:101]
	v_pk_add_f32 v[142:143], v[142:143], s[100:101]
	v_rcp_f32_e32 v140, v140
	v_rcp_f32_e32 v141, v141
	v_rcp_f32_e32 v142, v142
	v_rcp_f32_e32 v143, v143
	v_pk_mul_f32 v[140:141], v[132:133], v[140:141]
	v_pk_mul_f32 v[142:143], v[134:135], v[142:143]
	v_pk_mul_f32 v[140:141], v[140:141], v[136:137]
	v_pk_mul_f32 v[142:143], v[142:143], v[138:139]
	v_cvt_pk_bf16_f32 v128, v140, v141
	v_cvt_pk_bf16_f32 v129, v142, v143
	v_pk_fma_f32 v[132:133], v[92:93], v[190:191], v[178:179]
	v_pk_fma_f32 v[136:137], v[72:73], v[206:207], v[194:195]
	v_pk_fma_f32 v[134:135], v[94:95], v[192:193], v[180:181]
	v_pk_fma_f32 v[138:139], v[74:75], v[208:209], v[196:197]
	v_fmac_f32_dpp v132, v92, v186 row_shr:1 row_mask:0xf bank_mask:0xf
	v_fmac_f32_dpp v133, v93, v187 row_shr:1 row_mask:0xf bank_mask:0xf
	v_fmac_f32_dpp v134, v94, v188 row_shr:1 row_mask:0xf bank_mask:0xf
	v_fmac_f32_dpp v135, v95, v189 row_shr:1 row_mask:0xf bank_mask:0xf
	v_fmac_f32_dpp v136, v72, v202 row_shr:1 row_mask:0xf bank_mask:0xf
	v_fmac_f32_dpp v137, v73, v203 row_shr:1 row_mask:0xf bank_mask:0xf
	v_fmac_f32_dpp v138, v74, v204 row_shr:1 row_mask:0xf bank_mask:0xf
	v_fmac_f32_dpp v139, v75, v205 row_shr:1 row_mask:0xf bank_mask:0xf
	v_fmac_f32_dpp v132, v108, v186 row_shl:15 row_mask:0xf bank_mask:0xf
	v_fmac_f32_dpp v133, v109, v187 row_shl:15 row_mask:0xf bank_mask:0xf
	v_fmac_f32_dpp v134, v110, v188 row_shl:15 row_mask:0xf bank_mask:0xf
	v_fmac_f32_dpp v135, v111, v189 row_shl:15 row_mask:0xf bank_mask:0xf
	v_fmac_f32_dpp v136, v88, v202 row_shl:15 row_mask:0xf bank_mask:0xf
	v_fmac_f32_dpp v137, v89, v203 row_shl:15 row_mask:0xf bank_mask:0xf
	v_fmac_f32_dpp v138, v90, v204 row_shl:15 row_mask:0xf bank_mask:0xf
	v_fmac_f32_dpp v139, v91, v205 row_shl:15 row_mask:0xf bank_mask:0xf
	v_fmac_f32_dpp v132, v92, v182 row_shr:2 row_mask:0xf bank_mask:0xf
	v_fmac_f32_dpp v133, v93, v183 row_shr:2 row_mask:0xf bank_mask:0xf
	v_fmac_f32_dpp v134, v94, v184 row_shr:2 row_mask:0xf bank_mask:0xf
	v_fmac_f32_dpp v135, v95, v185 row_shr:2 row_mask:0xf bank_mask:0xf
	v_fmac_f32_dpp v136, v72, v198 row_shr:2 row_mask:0xf bank_mask:0xf
	v_fmac_f32_dpp v137, v73, v199 row_shr:2 row_mask:0xf bank_mask:0xf
	v_fmac_f32_dpp v138, v74, v200 row_shr:2 row_mask:0xf bank_mask:0xf
	v_fmac_f32_dpp v139, v75, v201 row_shr:2 row_mask:0xf bank_mask:0xf
	v_fmac_f32_dpp v132, v108, v182 row_shl:14 row_mask:0xf bank_mask:0xf
; __device__ __forceinline__ unsigned pk2(float lo, float hi) { unsigned r; asm("v_cvt_pk_bf16_f32 %0, %1, %2" : "=v"(r) : "v"(lo), "v"(hi)); return r; }
; __device__ __forceinline__ float gelu_tanh(float x) { const float y = 1.5957691216f * (x + 0.044715f * x * x * x); return x * __builtin_amdgcn_rcpf(1.0f + __expf(-y)); }
; __device__ __forceinline__ float dpp_shr1(float old, float src) { return __int_as_float(__builtin_amdgcn_update_dpp(__float_as_int(old), __float_as_int(src), 0x111, 0xf, 0xf, false)); }
; __device__ __forceinline__ float dpp_shr2(float old, float src) { return __int_as_float(__builtin_amdgcn_update_dpp(__float_as_int(old), __float_as_int(src), 0x112, 0xf, 0xf, false)); }
; __device__ __forceinline__ float dpp_ror1(float src) { return __int_as_float(__builtin_amdgcn_update_dpp(0, __float_as_int(src), 0x121, 0xf, 0xf, false)); }
;     __device__ __forceinline__ void operator()(const f32x4 (&acc)[2][2][4][2], const Unit& u, int wr, int wc, int fr, int fq) const {
;     ...
; #pragma unroll
;                 for (int m = 0; m < 4; ++m) { const int row = row0 + ai * HALF + m * 16;
;                     const f32x4 g0 = acc[ai][0][m][n], v0 = acc[ai][1][m][n];
;                     f32x4 gp = (f32x4){0.f, 0.f, 0.f, 0.f}, vp = gp;
;                     if (m > 0) { gp = acc[ai][0][m > 0 ? m - 1 : 0][n]; vp = acc[ai][1][m > 0 ? m - 1 : 0][n]; }
;                     f32x4 f;
; #pragma unroll
;                     for (int j = 0; j < 4; ++j) {
;                         const float g1 = dpp_shr1(dpp_ror1(gp[j]), g0[j]), g2 = dpp_shr2(dpp_ror2(gp[j]), g0[j]);
;                         const float v1 = dpp_shr1(dpp_ror1(vp[j]), v0[j]), v2 = dpp_shr2(dpp_ror2(vp[j]), v0[j]);
;                         const float cg_ = bg[j] + g2 * wg0[j] + g1 * wg1[j] + g0[j] * wg2[j];
;                         const float cv_ = bv[j] + v2 * wv0[j] + v1 * wv1[j] + v0[j] * wv2[j];
;                         f[j] = gelu_tanh(cg_) * cv_; }
;                     u32x2 w; w.x = pk2(f[0], f[1]); w.y = pk2(f[2], f[3]);
;                     if (n == 0) res0[ai * 4 + m] = w;
;                     else if (m > 0 || fr >= 2) { u32x4 w4; w4.x = res0[ai * 4 + m].x; w4.y = res0[ai * 4 + m].y; w4.z = w.x; w4.w = w.y; *(u32x4*)(F + (size_t)row * DFF + j0) = w4; }
	v_fmac_f32_dpp v133, v109, v183 row_shl:14 row_mask:0xf bank_mask:0xf
	v_fmac_f32_dpp v134, v110, v184 row_shl:14 row_mask:0xf bank_mask:0xf
	v_fmac_f32_dpp v135, v111, v185 row_shl:14 row_mask:0xf bank_mask:0xf
	v_fmac_f32_dpp v136, v88, v198 row_shl:14 row_mask:0xf bank_mask:0xf
	v_fmac_f32_dpp v137, v89, v199 row_shl:14 row_mask:0xf bank_mask:0xf
	v_fmac_f32_dpp v138, v90, v200 row_shl:14 row_mask:0xf bank_mask:0xf
	v_fmac_f32_dpp v139, v91, v201 row_shl:14 row_mask:0xf bank_mask:0xf
	v_pk_mul_f32 v[140:141], v[132:133], v[132:133]
	v_pk_mul_f32 v[142:143], v[134:135], v[134:135]
	v_pk_fma_f32 v[140:141], v[140:141], s[98:99], v[244:245]
	v_pk_fma_f32 v[142:143], v[142:143], s[98:99], v[244:245]
	v_pk_mul_f32 v[140:141], v[132:133], v[140:141]
	v_pk_mul_f32 v[142:143], v[134:135], v[142:143]
	v_exp_f32_e32 v140, v140
	v_exp_f32_e32 v141, v141
	v_exp_f32_e32 v142, v142
	v_exp_f32_e32 v143, v143
	v_pk_add_f32 v[140:141], v[140:141], s[100:101]
	v_pk_add_f32 v[142:143], v[142:143], s[100:101]
	v_rcp_f32_e32 v140, v140
	v_rcp_f32_e32 v141, v141
	v_rcp_f32_e32 v142, v142
	v_rcp_f32_e32 v143, v143
	v_pk_mul_f32 v[140:141], v[132:133], v[140:141]
	v_pk_mul_f32 v[142:143], v[134:135], v[142:143]
	v_pk_mul_f32 v[140:141], v[140:141], v[136:137]
	v_pk_mul_f32 v[142:143], v[142:143], v[138:139]
	v_cvt_pk_bf16_f32 v130, v140, v141
	v_cvt_pk_bf16_f32 v131, v142, v143
	v_add_u32_e32 v144, 0x20, v248
	v_mad_u64_u32 v[144:145], vcc, v144, s4, v[242:243]
	global_store_dwordx4 v[144:145], v[128:131], off nt
	v_pk_fma_f32 v[132:133], v[84:85], v[158:159], v[146:147]
	v_pk_fma_f32 v[136:137], v[68:69], v[174:175], v[162:163]
	v_pk_fma_f32 v[134:135], v[86:87], v[160:161], v[148:149]
	v_pk_fma_f32 v[138:139], v[70:71], v[176:177], v[164:165]
	v_fmac_f32_dpp v132, v84, v154 row_shr:1 row_mask:0xf bank_mask:0xf
	v_fmac_f32_dpp v133, v85, v155 row_shr:1 row_mask:0xf bank_mask:0xf
	v_fmac_f32_dpp v134, v86, v156 row_shr:1 row_mask:0xf bank_mask:0xf
	v_fmac_f32_dpp v135, v87, v157 row_shr:1 row_mask:0xf bank_mask:0xf
	v_fmac_f32_dpp v136, v68, v170 row_shr:1 row_mask:0xf bank_mask:0xf
	v_fmac_f32_dpp v137, v69, v171 row_shr:1 row_mask:0xf bank_mask:0xf
	v_fmac_f32_dpp v138, v70, v172 row_shr:1 row_mask:0xf bank_mask:0xf
	v_fmac_f32_dpp v139, v71, v173 row_shr:1 row_mask:0xf bank_mask:0xf
	v_fmac_f32_dpp v132, v100, v154 row_shl:15 row_mask:0xf bank_mask:0xf
	v_fmac_f32_dpp v133, v101, v155 row_shl:15 row_mask:0xf bank_mask:0xf
	v_fmac_f32_dpp v134, v102, v156 row_shl:15 row_mask:0xf bank_mask:0xf
	v_fmac_f32_dpp v135, v103, v157 row_shl:15 row_mask:0xf bank_mask:0xf
	v_fmac_f32_dpp v136, v80, v170 row_shl:15 row_mask:0xf bank_mask:0xf
	v_fmac_f32_dpp v137, v81, v171 row_shl:15 row_mask:0xf bank_mask:0xf
	v_fmac_f32_dpp v138, v82, v172 row_shl:15 row_mask:0xf bank_mask:0xf
	v_fmac_f32_dpp v139, v83, v173 row_shl:15 row_mask:0xf bank_mask:0xf
	v_fmac_f32_dpp v132, v84, v150 row_shr:2 row_mask:0xf bank_mask:0xf
	v_fmac_f32_dpp v133, v85, v151 row_shr:2 row_mask:0xf bank_mask:0xf
	v_fmac_f32_dpp v134, v86, v152 row_shr:2 row_mask:0xf bank_mask:0xf
	v_fmac_f32_dpp v135, v87, v153 row_shr:2 row_mask:0xf bank_mask:0xf
	v_fmac_f32_dpp v136, v68, v166 row_shr:2 row_mask:0xf bank_mask:0xf
	v_fmac_f32_dpp v137, v69, v167 row_shr:2 row_mask:0xf bank_mask:0xf
	v_fmac_f32_dpp v138, v70, v168 row_shr:2 row_mask:0xf bank_mask:0xf
	v_fmac_f32_dpp v139, v71, v169 row_shr:2 row_mask:0xf bank_mask:0xf
	v_fmac_f32_dpp v132, v100, v150 row_shl:14 row_mask:0xf bank_mask:0xf
	v_fmac_f32_dpp v133, v101, v151 row_shl:14 row_mask:0xf bank_mask:0xf
	v_fmac_f32_dpp v134, v102, v152 row_shl:14 row_mask:0xf bank_mask:0xf
	v_fmac_f32_dpp v135, v103, v153 row_shl:14 row_mask:0xf bank_mask:0xf
	v_fmac_f32_dpp v136, v80, v166 row_shl:14 row_mask:0xf bank_mask:0xf
	v_fmac_f32_dpp v137, v81, v167 row_shl:14 row_mask:0xf bank_mask:0xf
	v_fmac_f32_dpp v138, v82, v168 row_shl:14 row_mask:0xf bank_mask:0xf
	v_fmac_f32_dpp v139, v83, v169 row_shl:14 row_mask:0xf bank_mask:0xf
	v_pk_mul_f32 v[140:141], v[132:133], v[132:133]
	v_pk_mul_f32 v[142:143], v[134:135], v[134:135]
	v_pk_fma_f32 v[140:141], v[140:141], s[98:99], v[244:245]
	v_pk_fma_f32 v[142:143], v[142:143], s[98:99], v[244:245]
	v_pk_mul_f32 v[140:141], v[132:133], v[140:141]
	v_pk_mul_f32 v[142:143], v[134:135], v[142:143]
	v_exp_f32_e32 v140, v140
	v_exp_f32_e32 v141, v141
	v_exp_f32_e32 v142, v142
	v_exp_f32_e32 v143, v143
	v_pk_add_f32 v[140:141], v[140:141], s[100:101]
	v_pk_add_f32 v[142:143], v[142:143], s[100:101]
	v_rcp_f32_e32 v140, v140
	v_rcp_f32_e32 v141, v141
	v_rcp_f32_e32 v142, v142
	v_rcp_f32_e32 v143, v143
	v_pk_mul_f32 v[140:141], v[132:133], v[140:141]
	v_pk_mul_f32 v[142:143], v[134:135], v[142:143]
	v_pk_mul_f32 v[140:141], v[140:141], v[136:137]
	v_pk_mul_f32 v[142:143], v[142:143], v[138:139]
	v_cvt_pk_bf16_f32 v250, v140, v141
	v_cvt_pk_bf16_f32 v251, v142, v143
	v_pk_fma_f32 v[132:133], v[76:77], v[190:191], v[178:179]
	v_pk_fma_f32 v[136:137], v[64:65], v[206:207], v[194:195]
	v_pk_fma_f32 v[134:135], v[78:79], v[192:193], v[180:181]
	v_pk_fma_f32 v[138:139], v[66:67], v[208:209], v[196:197]
	v_fmac_f32_dpp v132, v76, v186 row_shr:1 row_mask:0xf bank_mask:0xf
	v_fmac_f32_dpp v133, v77, v187 row_shr:1 row_mask:0xf bank_mask:0xf
	v_fmac_f32_dpp v134, v78, v188 row_shr:1 row_mask:0xf bank_mask:0xf
	v_fmac_f32_dpp v135, v79, v189 row_shr:1 row_mask:0xf bank_mask:0xf
	v_fmac_f32_dpp v136, v64, v202 row_shr:1 row_mask:0xf bank_mask:0xf
	v_fmac_f32_dpp v137, v65, v203 row_shr:1 row_mask:0xf bank_mask:0xf
	v_fmac_f32_dpp v138, v66, v204 row_shr:1 row_mask:0xf bank_mask:0xf
	v_fmac_f32_dpp v139, v67, v205 row_shr:1 row_mask:0xf bank_mask:0xf
; __device__ __forceinline__ unsigned pk2(float lo, float hi) { unsigned r; asm("v_cvt_pk_bf16_f32 %0, %1, %2" : "=v"(r) : "v"(lo), "v"(hi)); return r; }
; __device__ __forceinline__ float gelu_tanh(float x) { const float y = 1.5957691216f * (x + 0.044715f * x * x * x); return x * __builtin_amdgcn_rcpf(1.0f + __expf(-y)); }
; __device__ __forceinline__ float dpp_shr1(float old, float src) { return __int_as_float(__builtin_amdgcn_update_dpp(__float_as_int(old), __float_as_int(src), 0x111, 0xf, 0xf, false)); }
; __device__ __forceinline__ float dpp_shr2(float old, float src) { return __int_as_float(__builtin_amdgcn_update_dpp(__float_as_int(old), __float_as_int(src), 0x112, 0xf, 0xf, false)); }
; __device__ __forceinline__ float dpp_ror1(float src) { return __int_as_float(__builtin_amdgcn_update_dpp(0, __float_as_int(src), 0x121, 0xf, 0xf, false)); }
;     __device__ __forceinline__ void operator()(const f32x4 (&acc)[2][2][4][2], const Unit& u, int wr, int wc, int fr, int fq) const {
;     ...
; #pragma unroll
;                 for (int m = 0; m < 4; ++m) { const int row = row0 + ai * HALF + m * 16;
;                     const f32x4 g0 = acc[ai][0][m][n], v0 = acc[ai][1][m][n];
;                     f32x4 gp = (f32x4){0.f, 0.f, 0.f, 0.f}, vp = gp;
;                     if (m > 0) { gp = acc[ai][0][m > 0 ? m - 1 : 0][n]; vp = acc[ai][1][m > 0 ? m - 1 : 0][n]; }
;                     f32x4 f;
; #pragma unroll
;                     for (int j = 0; j < 4; ++j) {
;                         const float g1 = dpp_shr1(dpp_ror1(gp[j]), g0[j]), g2 = dpp_shr2(dpp_ror2(gp[j]), g0[j]);
;                         const float v1 = dpp_shr1(dpp_ror1(vp[j]), v0[j]), v2 = dpp_shr2(dpp_ror2(vp[j]), v0[j]);
;                         const float cg_ = bg[j] + g2 * wg0[j] + g1 * wg1[j] + g0[j] * wg2[j];
;                         const float cv_ = bv[j] + v2 * wv0[j] + v1 * wv1[j] + v0[j] * wv2[j];
;                         f[j] = gelu_tanh(cg_) * cv_; }
;                     u32x2 w; w.x = pk2(f[0], f[1]); w.y = pk2(f[2], f[3]);
;                     if (n == 0) res0[ai * 4 + m] = w;
;                     else if (m > 0 || fr >= 2) { u32x4 w4; w4.x = res0[ai * 4 + m].x; w4.y = res0[ai * 4 + m].y; w4.z = w.x; w4.w = w.y; *(u32x4*)(F + (size_t)row * DFF + j0) = w4; }
	v_fmac_f32_dpp v132, v92, v186 row_shl:15 row_mask:0xf bank_mask:0xf
	v_fmac_f32_dpp v133, v93, v187 row_shl:15 row_mask:0xf bank_mask:0xf
	v_fmac_f32_dpp v134, v94, v188 row_shl:15 row_mask:0xf bank_mask:0xf
	v_fmac_f32_dpp v135, v95, v189 row_shl:15 row_mask:0xf bank_mask:0xf
	v_fmac_f32_dpp v136, v72, v202 row_shl:15 row_mask:0xf bank_mask:0xf
	v_fmac_f32_dpp v137, v73, v203 row_shl:15 row_mask:0xf bank_mask:0xf
	v_fmac_f32_dpp v138, v74, v204 row_shl:15 row_mask:0xf bank_mask:0xf
	v_fmac_f32_dpp v139, v75, v205 row_shl:15 row_mask:0xf bank_mask:0xf
	v_fmac_f32_dpp v132, v76, v182 row_shr:2 row_mask:0xf bank_mask:0xf
	v_fmac_f32_dpp v133, v77, v183 row_shr:2 row_mask:0xf bank_mask:0xf
	v_fmac_f32_dpp v134, v78, v184 row_shr:2 row_mask:0xf bank_mask:0xf
	v_fmac_f32_dpp v135, v79, v185 row_shr:2 row_mask:0xf bank_mask:0xf
	v_fmac_f32_dpp v136, v64, v198 row_shr:2 row_mask:0xf bank_mask:0xf
	v_fmac_f32_dpp v137, v65, v199 row_shr:2 row_mask:0xf bank_mask:0xf
	v_fmac_f32_dpp v138, v66, v200 row_shr:2 row_mask:0xf bank_mask:0xf
	v_fmac_f32_dpp v139, v67, v201 row_shr:2 row_mask:0xf bank_mask:0xf
	v_fmac_f32_dpp v132, v92, v182 row_shl:14 row_mask:0xf bank_mask:0xf
	v_fmac_f32_dpp v133, v93, v183 row_shl:14 row_mask:0xf bank_mask:0xf
	v_fmac_f32_dpp v134, v94, v184 row_shl:14 row_mask:0xf bank_mask:0xf
	v_fmac_f32_dpp v135, v95, v185 row_shl:14 row_mask:0xf bank_mask:0xf
	v_fmac_f32_dpp v136, v72, v198 row_shl:14 row_mask:0xf bank_mask:0xf
	v_fmac_f32_dpp v137, v73, v199 row_shl:14 row_mask:0xf bank_mask:0xf
	v_fmac_f32_dpp v138, v74, v200 row_shl:14 row_mask:0xf bank_mask:0xf
	v_fmac_f32_dpp v139, v75, v201 row_shl:14 row_mask:0xf bank_mask:0xf
	v_pk_mul_f32 v[140:141], v[132:133], v[132:133]
	v_pk_mul_f32 v[142:143], v[134:135], v[134:135]
	v_pk_fma_f32 v[140:141], v[140:141], s[98:99], v[244:245]
	v_pk_fma_f32 v[142:143], v[142:143], s[98:99], v[244:245]
	v_pk_mul_f32 v[140:141], v[132:133], v[140:141]
	v_pk_mul_f32 v[142:143], v[134:135], v[142:143]
	v_exp_f32_e32 v140, v140
	v_exp_f32_e32 v141, v141
	v_exp_f32_e32 v142, v142
	v_exp_f32_e32 v143, v143
	v_pk_add_f32 v[140:141], v[140:141], s[100:101]
	v_pk_add_f32 v[142:143], v[142:143], s[100:101]
	v_rcp_f32_e32 v140, v140
	v_rcp_f32_e32 v141, v141
	v_rcp_f32_e32 v142, v142
	v_rcp_f32_e32 v143, v143
	v_pk_mul_f32 v[140:141], v[132:133], v[140:141]
	v_pk_mul_f32 v[142:143], v[134:135], v[142:143]
	v_pk_mul_f32 v[140:141], v[140:141], v[136:137]
	v_pk_mul_f32 v[142:143], v[142:143], v[138:139]
	v_cvt_pk_bf16_f32 v252, v140, v141
	v_cvt_pk_bf16_f32 v253, v142, v143
	v_add_u32_e32 v144, 0x30, v248
	v_mad_u64_u32 v[144:145], vcc, v144, s4, v[242:243]
	global_store_dwordx4 v[144:145], v[250:253], off nt
	v_pk_fma_f32 v[132:133], v[60:61], v[158:159], v[146:147]
	v_pk_fma_f32 v[136:137], v[48:49], v[174:175], v[162:163]
	v_pk_fma_f32 v[134:135], v[62:63], v[160:161], v[148:149]
	v_pk_fma_f32 v[138:139], v[50:51], v[176:177], v[164:165]
	v_fmac_f32_dpp v132, v60, v154 row_shr:1 row_mask:0xf bank_mask:0xf
	v_fmac_f32_dpp v133, v61, v155 row_shr:1 row_mask:0xf bank_mask:0xf
	v_fmac_f32_dpp v134, v62, v156 row_shr:1 row_mask:0xf bank_mask:0xf
	v_fmac_f32_dpp v135, v63, v157 row_shr:1 row_mask:0xf bank_mask:0xf
	v_fmac_f32_dpp v136, v48, v170 row_shr:1 row_mask:0xf bank_mask:0xf
	v_fmac_f32_dpp v137, v49, v171 row_shr:1 row_mask:0xf bank_mask:0xf
	v_fmac_f32_dpp v138, v50, v172 row_shr:1 row_mask:0xf bank_mask:0xf
	v_fmac_f32_dpp v139, v51, v173 row_shr:1 row_mask:0xf bank_mask:0xf
	v_fmac_f32_dpp v132, v60, v150 row_shr:2 row_mask:0xf bank_mask:0xf
	v_fmac_f32_dpp v133, v61, v151 row_shr:2 row_mask:0xf bank_mask:0xf
	v_fmac_f32_dpp v134, v62, v152 row_shr:2 row_mask:0xf bank_mask:0xf
	v_fmac_f32_dpp v135, v63, v153 row_shr:2 row_mask:0xf bank_mask:0xf
	v_fmac_f32_dpp v136, v48, v166 row_shr:2 row_mask:0xf bank_mask:0xf
	v_fmac_f32_dpp v137, v49, v167 row_shr:2 row_mask:0xf bank_mask:0xf
	v_fmac_f32_dpp v138, v50, v168 row_shr:2 row_mask:0xf bank_mask:0xf
	v_fmac_f32_dpp v139, v51, v169 row_shr:2 row_mask:0xf bank_mask:0xf
	v_pk_mul_f32 v[140:141], v[132:133], v[132:133]
	v_pk_mul_f32 v[142:143], v[134:135], v[134:135]
	v_pk_fma_f32 v[140:141], v[140:141], s[98:99], v[244:245]
	v_pk_fma_f32 v[142:143], v[142:143], s[98:99], v[244:245]
	v_pk_mul_f32 v[140:141], v[132:133], v[140:141]
	v_pk_mul_f32 v[142:143], v[134:135], v[142:143]
	v_exp_f32_e32 v140, v140
	v_exp_f32_e32 v141, v141
	v_exp_f32_e32 v142, v142
	v_exp_f32_e32 v143, v143
	v_pk_add_f32 v[140:141], v[140:141], s[100:101]
	v_pk_add_f32 v[142:143], v[142:143], s[100:101]
	v_rcp_f32_e32 v140, v140
	v_rcp_f32_e32 v141, v141
	v_rcp_f32_e32 v142, v142
	v_rcp_f32_e32 v143, v143
	v_pk_mul_f32 v[140:141], v[132:133], v[140:141]
	v_pk_mul_f32 v[142:143], v[134:135], v[142:143]
	v_pk_mul_f32 v[140:141], v[140:141], v[136:137]
	v_pk_mul_f32 v[142:143], v[142:143], v[138:139]
	v_cvt_pk_bf16_f32 v128, v140, v141
	v_cvt_pk_bf16_f32 v129, v142, v143
	v_pk_fma_f32 v[132:133], v[56:57], v[190:191], v[178:179]
	v_pk_fma_f32 v[136:137], v[40:41], v[206:207], v[194:195]
	v_pk_fma_f32 v[134:135], v[58:59], v[192:193], v[180:181]
	v_pk_fma_f32 v[138:139], v[42:43], v[208:209], v[196:197]
	v_fmac_f32_dpp v132, v56, v186 row_shr:1 row_mask:0xf bank_mask:0xf
	v_fmac_f32_dpp v133, v57, v187 row_shr:1 row_mask:0xf bank_mask:0xf
	v_fmac_f32_dpp v134, v58, v188 row_shr:1 row_mask:0xf bank_mask:0xf
	v_fmac_f32_dpp v135, v59, v189 row_shr:1 row_mask:0xf bank_mask:0xf
	v_fmac_f32_dpp v136, v40, v202 row_shr:1 row_mask:0xf bank_mask:0xf
	v_fmac_f32_dpp v137, v41, v203 row_shr:1 row_mask:0xf bank_mask:0xf
	v_fmac_f32_dpp v138, v42, v204 row_shr:1 row_mask:0xf bank_mask:0xf
; __device__ __forceinline__ unsigned pk2(float lo, float hi) { unsigned r; asm("v_cvt_pk_bf16_f32 %0, %1, %2" : "=v"(r) : "v"(lo), "v"(hi)); return r; }
; __device__ __forceinline__ float gelu_tanh(float x) { const float y = 1.5957691216f * (x + 0.044715f * x * x * x); return x * __builtin_amdgcn_rcpf(1.0f + __expf(-y)); }
; __device__ __forceinline__ float dpp_shr1(float old, float src) { return __int_as_float(__builtin_amdgcn_update_dpp(__float_as_int(old), __float_as_int(src), 0x111, 0xf, 0xf, false)); }
; __device__ __forceinline__ float dpp_shr2(float old, float src) { return __int_as_float(__builtin_amdgcn_update_dpp(__float_as_int(old), __float_as_int(src), 0x112, 0xf, 0xf, false)); }
; __device__ __forceinline__ float dpp_ror1(float src) { return __int_as_float(__builtin_amdgcn_update_dpp(0, __float_as_int(src), 0x121, 0xf, 0xf, false)); }
;     __device__ __forceinline__ void operator()(const f32x4 (&acc)[2][2][4][2], const Unit& u, int wr, int wc, int fr, int fq) const {
;     ...
; #pragma unroll
;                 for (int m = 0; m < 4; ++m) { const int row = row0 + ai * HALF + m * 16;
;                     const f32x4 g0 = acc[ai][0][m][n], v0 = acc[ai][1][m][n];
;                     f32x4 gp = (f32x4){0.f, 0.f, 0.f, 0.f}, vp = gp;
;                     if (m > 0) { gp = acc[ai][0][m > 0 ? m - 1 : 0][n]; vp = acc[ai][1][m > 0 ? m - 1 : 0][n]; }
;                     f32x4 f;
; #pragma unroll
;                     for (int j = 0; j < 4; ++j) {
;                         const float g1 = dpp_shr1(dpp_ror1(gp[j]), g0[j]), g2 = dpp_shr2(dpp_ror2(gp[j]), g0[j]);
;                         const float v1 = dpp_shr1(dpp_ror1(vp[j]), v0[j]), v2 = dpp_shr2(dpp_ror2(vp[j]), v0[j]);
;                         const float cg_ = bg[j] + g2 * wg0[j] + g1 * wg1[j] + g0[j] * wg2[j];
;                         const float cv_ = bv[j] + v2 * wv0[j] + v1 * wv1[j] + v0[j] * wv2[j];
;                         f[j] = gelu_tanh(cg_) * cv_; }
;                     u32x2 w; w.x = pk2(f[0], f[1]); w.y = pk2(f[2], f[3]);
;                     if (n == 0) res0[ai * 4 + m] = w;
;                     else if (m > 0 || fr >= 2) { u32x4 w4; w4.x = res0[ai * 4 + m].x; w4.y = res0[ai * 4 + m].y; w4.z = w.x; w4.w = w.y; *(u32x4*)(F + (size_t)row * DFF + j0) = w4; }
	v_fmac_f32_dpp v139, v43, v205 row_shr:1 row_mask:0xf bank_mask:0xf
	v_fmac_f32_dpp v132, v56, v182 row_shr:2 row_mask:0xf bank_mask:0xf
	v_fmac_f32_dpp v133, v57, v183 row_shr:2 row_mask:0xf bank_mask:0xf
	v_fmac_f32_dpp v134, v58, v184 row_shr:2 row_mask:0xf bank_mask:0xf
	v_fmac_f32_dpp v135, v59, v185 row_shr:2 row_mask:0xf bank_mask:0xf
	v_fmac_f32_dpp v136, v40, v198 row_shr:2 row_mask:0xf bank_mask:0xf
	v_fmac_f32_dpp v137, v41, v199 row_shr:2 row_mask:0xf bank_mask:0xf
	v_fmac_f32_dpp v138, v42, v200 row_shr:2 row_mask:0xf bank_mask:0xf
	v_fmac_f32_dpp v139, v43, v201 row_shr:2 row_mask:0xf bank_mask:0xf
	v_pk_mul_f32 v[140:141], v[132:133], v[132:133]
	v_pk_mul_f32 v[142:143], v[134:135], v[134:135]
	v_pk_fma_f32 v[140:141], v[140:141], s[98:99], v[244:245]
	v_pk_fma_f32 v[142:143], v[142:143], s[98:99], v[244:245]
	v_pk_mul_f32 v[140:141], v[132:133], v[140:141]
	v_pk_mul_f32 v[142:143], v[134:135], v[142:143]
	v_exp_f32_e32 v140, v140
	v_exp_f32_e32 v141, v141
	v_exp_f32_e32 v142, v142
	v_exp_f32_e32 v143, v143
	v_pk_add_f32 v[140:141], v[140:141], s[100:101]
	v_pk_add_f32 v[142:143], v[142:143], s[100:101]
	v_rcp_f32_e32 v140, v140
	v_rcp_f32_e32 v141, v141
	v_rcp_f32_e32 v142, v142
	v_rcp_f32_e32 v143, v143
	v_pk_mul_f32 v[140:141], v[132:133], v[140:141]
	v_pk_mul_f32 v[142:143], v[134:135], v[142:143]
	v_pk_mul_f32 v[140:141], v[140:141], v[136:137]
	v_pk_mul_f32 v[142:143], v[142:143], v[138:139]
	v_cvt_pk_bf16_f32 v130, v140, v141
	v_cvt_pk_bf16_f32 v131, v142, v143
	s_and_saveexec_b64 s[42:43], s[8:9]
	v_add_u32_e32 v144, 0x80, v248
	v_mad_u64_u32 v[144:145], vcc, v144, s4, v[242:243]
	global_store_dwordx4 v[144:145], v[128:131], off nt
	s_or_b64 exec, exec, s[42:43]
	s_nop 4
	v_pk_fma_f32 v[132:133], v[52:53], v[158:159], v[146:147]
	v_pk_fma_f32 v[136:137], v[32:33], v[174:175], v[162:163]
	v_pk_fma_f32 v[134:135], v[54:55], v[160:161], v[148:149]
	v_pk_fma_f32 v[138:139], v[34:35], v[176:177], v[164:165]
	v_fmac_f32_dpp v132, v52, v154 row_shr:1 row_mask:0xf bank_mask:0xf
	v_fmac_f32_dpp v133, v53, v155 row_shr:1 row_mask:0xf bank_mask:0xf
	v_fmac_f32_dpp v134, v54, v156 row_shr:1 row_mask:0xf bank_mask:0xf
	v_fmac_f32_dpp v135, v55, v157 row_shr:1 row_mask:0xf bank_mask:0xf
	v_fmac_f32_dpp v136, v32, v170 row_shr:1 row_mask:0xf bank_mask:0xf
	v_fmac_f32_dpp v137, v33, v171 row_shr:1 row_mask:0xf bank_mask:0xf
	v_fmac_f32_dpp v138, v34, v172 row_shr:1 row_mask:0xf bank_mask:0xf
	v_fmac_f32_dpp v139, v35, v173 row_shr:1 row_mask:0xf bank_mask:0xf
	v_fmac_f32_dpp v132, v60, v154 row_shl:15 row_mask:0xf bank_mask:0xf
	v_fmac_f32_dpp v133, v61, v155 row_shl:15 row_mask:0xf bank_mask:0xf
	v_fmac_f32_dpp v134, v62, v156 row_shl:15 row_mask:0xf bank_mask:0xf
	v_fmac_f32_dpp v135, v63, v157 row_shl:15 row_mask:0xf bank_mask:0xf
	v_fmac_f32_dpp v136, v48, v170 row_shl:15 row_mask:0xf bank_mask:0xf
	v_fmac_f32_dpp v137, v49, v171 row_shl:15 row_mask:0xf bank_mask:0xf
	v_fmac_f32_dpp v138, v50, v172 row_shl:15 row_mask:0xf bank_mask:0xf
	v_fmac_f32_dpp v139, v51, v173 row_shl:15 row_mask:0xf bank_mask:0xf
	v_fmac_f32_dpp v132, v52, v150 row_shr:2 row_mask:0xf bank_mask:0xf
	v_fmac_f32_dpp v133, v53, v151 row_shr:2 row_mask:0xf bank_mask:0xf
	v_fmac_f32_dpp v134, v54, v152 row_shr:2 row_mask:0xf bank_mask:0xf
	v_fmac_f32_dpp v135, v55, v153 row_shr:2 row_mask:0xf bank_mask:0xf
	v_fmac_f32_dpp v136, v32, v166 row_shr:2 row_mask:0xf bank_mask:0xf
	v_fmac_f32_dpp v137, v33, v167 row_shr:2 row_mask:0xf bank_mask:0xf
	v_fmac_f32_dpp v138, v34, v168 row_shr:2 row_mask:0xf bank_mask:0xf
	v_fmac_f32_dpp v139, v35, v169 row_shr:2 row_mask:0xf bank_mask:0xf
	v_fmac_f32_dpp v132, v60, v150 row_shl:14 row_mask:0xf bank_mask:0xf
	v_fmac_f32_dpp v133, v61, v151 row_shl:14 row_mask:0xf bank_mask:0xf
	v_fmac_f32_dpp v134, v62, v152 row_shl:14 row_mask:0xf bank_mask:0xf
	v_fmac_f32_dpp v135, v63, v153 row_shl:14 row_mask:0xf bank_mask:0xf
	v_fmac_f32_dpp v136, v48, v166 row_shl:14 row_mask:0xf bank_mask:0xf
	v_fmac_f32_dpp v137, v49, v167 row_shl:14 row_mask:0xf bank_mask:0xf
	v_fmac_f32_dpp v138, v50, v168 row_shl:14 row_mask:0xf bank_mask:0xf
	v_fmac_f32_dpp v139, v51, v169 row_shl:14 row_mask:0xf bank_mask:0xf
	v_pk_mul_f32 v[140:141], v[132:133], v[132:133]
	v_pk_mul_f32 v[142:143], v[134:135], v[134:135]
	v_pk_fma_f32 v[140:141], v[140:141], s[98:99], v[244:245]
	v_pk_fma_f32 v[142:143], v[142:143], s[98:99], v[244:245]
	v_pk_mul_f32 v[140:141], v[132:133], v[140:141]
	v_pk_mul_f32 v[142:143], v[134:135], v[142:143]
	v_exp_f32_e32 v140, v140
	v_exp_f32_e32 v141, v141
	v_exp_f32_e32 v142, v142
	v_exp_f32_e32 v143, v143
	v_pk_add_f32 v[140:141], v[140:141], s[100:101]
	v_pk_add_f32 v[142:143], v[142:143], s[100:101]
	v_rcp_f32_e32 v140, v140
	v_rcp_f32_e32 v141, v141
	v_rcp_f32_e32 v142, v142
	v_rcp_f32_e32 v143, v143
	v_pk_mul_f32 v[140:141], v[132:133], v[140:141]
	v_pk_mul_f32 v[142:143], v[134:135], v[142:143]
	v_pk_mul_f32 v[140:141], v[140:141], v[136:137]
	v_pk_mul_f32 v[142:143], v[142:143], v[138:139]
	v_cvt_pk_bf16_f32 v250, v140, v141
	v_cvt_pk_bf16_f32 v251, v142, v143
	v_pk_fma_f32 v[132:133], v[44:45], v[190:191], v[178:179]
	v_pk_fma_f32 v[136:137], v[24:25], v[206:207], v[194:195]
	v_pk_fma_f32 v[134:135], v[46:47], v[192:193], v[180:181]
	v_pk_fma_f32 v[138:139], v[26:27], v[208:209], v[196:197]
	v_fmac_f32_dpp v132, v44, v186 row_shr:1 row_mask:0xf bank_mask:0xf
	v_fmac_f32_dpp v133, v45, v187 row_shr:1 row_mask:0xf bank_mask:0xf
	v_fmac_f32_dpp v134, v46, v188 row_shr:1 row_mask:0xf bank_mask:0xf
	v_fmac_f32_dpp v135, v47, v189 row_shr:1 row_mask:0xf bank_mask:0xf
	v_fmac_f32_dpp v136, v24, v202 row_shr:1 row_mask:0xf bank_mask:0xf
; __device__ __forceinline__ unsigned pk2(float lo, float hi) { unsigned r; asm("v_cvt_pk_bf16_f32 %0, %1, %2" : "=v"(r) : "v"(lo), "v"(hi)); return r; }
; __device__ __forceinline__ float gelu_tanh(float x) { const float y = 1.5957691216f * (x + 0.044715f * x * x * x); return x * __builtin_amdgcn_rcpf(1.0f + __expf(-y)); }
; __device__ __forceinline__ float dpp_shr1(float old, float src) { return __int_as_float(__builtin_amdgcn_update_dpp(__float_as_int(old), __float_as_int(src), 0x111, 0xf, 0xf, false)); }
; __device__ __forceinline__ float dpp_shr2(float old, float src) { return __int_as_float(__builtin_amdgcn_update_dpp(__float_as_int(old), __float_as_int(src), 0x112, 0xf, 0xf, false)); }
; __device__ __forceinline__ float dpp_ror1(float src) { return __int_as_float(__builtin_amdgcn_update_dpp(0, __float_as_int(src), 0x121, 0xf, 0xf, false)); }
;     __device__ __forceinline__ void operator()(const f32x4 (&acc)[2][2][4][2], const Unit& u, int wr, int wc, int fr, int fq) const {
;     ...
; #pragma unroll
;                 for (int m = 0; m < 4; ++m) { const int row = row0 + ai * HALF + m * 16;
;                     const f32x4 g0 = acc[ai][0][m][n], v0 = acc[ai][1][m][n];
;                     f32x4 gp = (f32x4){0.f, 0.f, 0.f, 0.f}, vp = gp;
;                     if (m > 0) { gp = acc[ai][0][m > 0 ? m - 1 : 0][n]; vp = acc[ai][1][m > 0 ? m - 1 : 0][n]; }
;                     f32x4 f;
; #pragma unroll
;                     for (int j = 0; j < 4; ++j) {
;                         const float g1 = dpp_shr1(dpp_ror1(gp[j]), g0[j]), g2 = dpp_shr2(dpp_ror2(gp[j]), g0[j]);
;                         const float v1 = dpp_shr1(dpp_ror1(vp[j]), v0[j]), v2 = dpp_shr2(dpp_ror2(vp[j]), v0[j]);
;                         const float cg_ = bg[j] + g2 * wg0[j] + g1 * wg1[j] + g0[j] * wg2[j];
;                         const float cv_ = bv[j] + v2 * wv0[j] + v1 * wv1[j] + v0[j] * wv2[j];
;                         f[j] = gelu_tanh(cg_) * cv_; }
;                     u32x2 w; w.x = pk2(f[0], f[1]); w.y = pk2(f[2], f[3]);
;                     if (n == 0) res0[ai * 4 + m] = w;
;                     else if (m > 0 || fr >= 2) { u32x4 w4; w4.x = res0[ai * 4 + m].x; w4.y = res0[ai * 4 + m].y; w4.z = w.x; w4.w = w.y; *(u32x4*)(F + (size_t)row * DFF + j0) = w4; }
	v_fmac_f32_dpp v137, v25, v203 row_shr:1 row_mask:0xf bank_mask:0xf
	v_fmac_f32_dpp v138, v26, v204 row_shr:1 row_mask:0xf bank_mask:0xf
	v_fmac_f32_dpp v139, v27, v205 row_shr:1 row_mask:0xf bank_mask:0xf
	v_fmac_f32_dpp v132, v56, v186 row_shl:15 row_mask:0xf bank_mask:0xf
	v_fmac_f32_dpp v133, v57, v187 row_shl:15 row_mask:0xf bank_mask:0xf
	v_fmac_f32_dpp v134, v58, v188 row_shl:15 row_mask:0xf bank_mask:0xf
	v_fmac_f32_dpp v135, v59, v189 row_shl:15 row_mask:0xf bank_mask:0xf
	v_fmac_f32_dpp v136, v40, v202 row_shl:15 row_mask:0xf bank_mask:0xf
	v_fmac_f32_dpp v137, v41, v203 row_shl:15 row_mask:0xf bank_mask:0xf
	v_fmac_f32_dpp v138, v42, v204 row_shl:15 row_mask:0xf bank_mask:0xf
	v_fmac_f32_dpp v139, v43, v205 row_shl:15 row_mask:0xf bank_mask:0xf
	v_fmac_f32_dpp v132, v44, v182 row_shr:2 row_mask:0xf bank_mask:0xf
	v_fmac_f32_dpp v133, v45, v183 row_shr:2 row_mask:0xf bank_mask:0xf
	v_fmac_f32_dpp v134, v46, v184 row_shr:2 row_mask:0xf bank_mask:0xf
	v_fmac_f32_dpp v135, v47, v185 row_shr:2 row_mask:0xf bank_mask:0xf
	v_fmac_f32_dpp v136, v24, v198 row_shr:2 row_mask:0xf bank_mask:0xf
	v_fmac_f32_dpp v137, v25, v199 row_shr:2 row_mask:0xf bank_mask:0xf
	v_fmac_f32_dpp v138, v26, v200 row_shr:2 row_mask:0xf bank_mask:0xf
	v_fmac_f32_dpp v139, v27, v201 row_shr:2 row_mask:0xf bank_mask:0xf
	v_fmac_f32_dpp v132, v56, v182 row_shl:14 row_mask:0xf bank_mask:0xf
	v_fmac_f32_dpp v133, v57, v183 row_shl:14 row_mask:0xf bank_mask:0xf
	v_fmac_f32_dpp v134, v58, v184 row_shl:14 row_mask:0xf bank_mask:0xf
	v_fmac_f32_dpp v135, v59, v185 row_shl:14 row_mask:0xf bank_mask:0xf
	v_fmac_f32_dpp v136, v40, v198 row_shl:14 row_mask:0xf bank_mask:0xf
	v_fmac_f32_dpp v137, v41, v199 row_shl:14 row_mask:0xf bank_mask:0xf
	v_fmac_f32_dpp v138, v42, v200 row_shl:14 row_mask:0xf bank_mask:0xf
	v_fmac_f32_dpp v139, v43, v201 row_shl:14 row_mask:0xf bank_mask:0xf
	v_pk_mul_f32 v[140:141], v[132:133], v[132:133]
	v_pk_mul_f32 v[142:143], v[134:135], v[134:135]
	v_pk_fma_f32 v[140:141], v[140:141], s[98:99], v[244:245]
	v_pk_fma_f32 v[142:143], v[142:143], s[98:99], v[244:245]
	v_pk_mul_f32 v[140:141], v[132:133], v[140:141]
	v_pk_mul_f32 v[142:143], v[134:135], v[142:143]
	v_exp_f32_e32 v140, v140
	v_exp_f32_e32 v141, v141
	v_exp_f32_e32 v142, v142
	v_exp_f32_e32 v143, v143
	v_pk_add_f32 v[140:141], v[140:141], s[100:101]
	v_pk_add_f32 v[142:143], v[142:143], s[100:101]
	v_rcp_f32_e32 v140, v140
	v_rcp_f32_e32 v141, v141
	v_rcp_f32_e32 v142, v142
	v_rcp_f32_e32 v143, v143
	v_pk_mul_f32 v[140:141], v[132:133], v[140:141]
	v_pk_mul_f32 v[142:143], v[134:135], v[142:143]
	v_pk_mul_f32 v[140:141], v[140:141], v[136:137]
	v_pk_mul_f32 v[142:143], v[142:143], v[138:139]
	v_cvt_pk_bf16_f32 v252, v140, v141
	v_cvt_pk_bf16_f32 v253, v142, v143
	v_add_u32_e32 v144, 0x90, v248
	v_mad_u64_u32 v[144:145], vcc, v144, s4, v[242:243]
	global_store_dwordx4 v[144:145], v[250:253], off nt
	v_pk_fma_f32 v[132:133], v[36:37], v[158:159], v[146:147]
	v_pk_fma_f32 v[136:137], v[16:17], v[174:175], v[162:163]
	v_pk_fma_f32 v[134:135], v[38:39], v[160:161], v[148:149]
	v_pk_fma_f32 v[138:139], v[18:19], v[176:177], v[164:165]
	v_fmac_f32_dpp v132, v36, v154 row_shr:1 row_mask:0xf bank_mask:0xf
	v_fmac_f32_dpp v133, v37, v155 row_shr:1 row_mask:0xf bank_mask:0xf
	v_fmac_f32_dpp v134, v38, v156 row_shr:1 row_mask:0xf bank_mask:0xf
	v_fmac_f32_dpp v135, v39, v157 row_shr:1 row_mask:0xf bank_mask:0xf
	v_fmac_f32_dpp v136, v16, v170 row_shr:1 row_mask:0xf bank_mask:0xf
	v_fmac_f32_dpp v137, v17, v171 row_shr:1 row_mask:0xf bank_mask:0xf
	v_fmac_f32_dpp v138, v18, v172 row_shr:1 row_mask:0xf bank_mask:0xf
	v_fmac_f32_dpp v139, v19, v173 row_shr:1 row_mask:0xf bank_mask:0xf
	v_fmac_f32_dpp v132, v52, v154 row_shl:15 row_mask:0xf bank_mask:0xf
	v_fmac_f32_dpp v133, v53, v155 row_shl:15 row_mask:0xf bank_mask:0xf
	v_fmac_f32_dpp v134, v54, v156 row_shl:15 row_mask:0xf bank_mask:0xf
	v_fmac_f32_dpp v135, v55, v157 row_shl:15 row_mask:0xf bank_mask:0xf
	v_fmac_f32_dpp v136, v32, v170 row_shl:15 row_mask:0xf bank_mask:0xf
	v_fmac_f32_dpp v137, v33, v171 row_shl:15 row_mask:0xf bank_mask:0xf
	v_fmac_f32_dpp v138, v34, v172 row_shl:15 row_mask:0xf bank_mask:0xf
	v_fmac_f32_dpp v139, v35, v173 row_shl:15 row_mask:0xf bank_mask:0xf
	v_fmac_f32_dpp v132, v36, v150 row_shr:2 row_mask:0xf bank_mask:0xf
	v_fmac_f32_dpp v133, v37, v151 row_shr:2 row_mask:0xf bank_mask:0xf
	v_fmac_f32_dpp v134, v38, v152 row_shr:2 row_mask:0xf bank_mask:0xf
	v_fmac_f32_dpp v135, v39, v153 row_shr:2 row_mask:0xf bank_mask:0xf
	v_fmac_f32_dpp v136, v16, v166 row_shr:2 row_mask:0xf bank_mask:0xf
	v_fmac_f32_dpp v137, v17, v167 row_shr:2 row_mask:0xf bank_mask:0xf
	v_fmac_f32_dpp v138, v18, v168 row_shr:2 row_mask:0xf bank_mask:0xf
	v_fmac_f32_dpp v139, v19, v169 row_shr:2 row_mask:0xf bank_mask:0xf
	v_fmac_f32_dpp v132, v52, v150 row_shl:14 row_mask:0xf bank_mask:0xf
	v_fmac_f32_dpp v133, v53, v151 row_shl:14 row_mask:0xf bank_mask:0xf
	v_fmac_f32_dpp v134, v54, v152 row_shl:14 row_mask:0xf bank_mask:0xf
	v_fmac_f32_dpp v135, v55, v153 row_shl:14 row_mask:0xf bank_mask:0xf
	v_fmac_f32_dpp v136, v32, v166 row_shl:14 row_mask:0xf bank_mask:0xf
	v_fmac_f32_dpp v137, v33, v167 row_shl:14 row_mask:0xf bank_mask:0xf
	v_fmac_f32_dpp v138, v34, v168 row_shl:14 row_mask:0xf bank_mask:0xf
	v_fmac_f32_dpp v139, v35, v169 row_shl:14 row_mask:0xf bank_mask:0xf
	v_pk_mul_f32 v[140:141], v[132:133], v[132:133]
	v_pk_mul_f32 v[142:143], v[134:135], v[134:135]
	v_pk_fma_f32 v[140:141], v[140:141], s[98:99], v[244:245]
	v_pk_fma_f32 v[142:143], v[142:143], s[98:99], v[244:245]
	v_pk_mul_f32 v[140:141], v[132:133], v[140:141]
; __device__ __forceinline__ unsigned pk2(float lo, float hi) { unsigned r; asm("v_cvt_pk_bf16_f32 %0, %1, %2" : "=v"(r) : "v"(lo), "v"(hi)); return r; }
; __device__ __forceinline__ float gelu_tanh(float x) { const float y = 1.5957691216f * (x + 0.044715f * x * x * x); return x * __builtin_amdgcn_rcpf(1.0f + __expf(-y)); }
; __device__ __forceinline__ float dpp_shr1(float old, float src) { return __int_as_float(__builtin_amdgcn_update_dpp(__float_as_int(old), __float_as_int(src), 0x111, 0xf, 0xf, false)); }
; __device__ __forceinline__ float dpp_shr2(float old, float src) { return __int_as_float(__builtin_amdgcn_update_dpp(__float_as_int(old), __float_as_int(src), 0x112, 0xf, 0xf, false)); }
; __device__ __forceinline__ float dpp_ror1(float src) { return __int_as_float(__builtin_amdgcn_update_dpp(0, __float_as_int(src), 0x121, 0xf, 0xf, false)); }
;     __device__ __forceinline__ void operator()(const f32x4 (&acc)[2][2][4][2], const Unit& u, int wr, int wc, int fr, int fq) const {
;     ...
; #pragma unroll
;                 for (int m = 0; m < 4; ++m) { const int row = row0 + ai * HALF + m * 16;
;                     const f32x4 g0 = acc[ai][0][m][n], v0 = acc[ai][1][m][n];
;                     f32x4 gp = (f32x4){0.f, 0.f, 0.f, 0.f}, vp = gp;
;                     if (m > 0) { gp = acc[ai][0][m > 0 ? m - 1 : 0][n]; vp = acc[ai][1][m > 0 ? m - 1 : 0][n]; }
;                     f32x4 f;
; #pragma unroll
;                     for (int j = 0; j < 4; ++j) {
;                         const float g1 = dpp_shr1(dpp_ror1(gp[j]), g0[j]), g2 = dpp_shr2(dpp_ror2(gp[j]), g0[j]);
;                         const float v1 = dpp_shr1(dpp_ror1(vp[j]), v0[j]), v2 = dpp_shr2(dpp_ror2(vp[j]), v0[j]);
;                         const float cg_ = bg[j] + g2 * wg0[j] + g1 * wg1[j] + g0[j] * wg2[j];
;                         const float cv_ = bv[j] + v2 * wv0[j] + v1 * wv1[j] + v0[j] * wv2[j];
;                         f[j] = gelu_tanh(cg_) * cv_; }
;                     u32x2 w; w.x = pk2(f[0], f[1]); w.y = pk2(f[2], f[3]);
;                     if (n == 0) res0[ai * 4 + m] = w;
;                     else if (m > 0 || fr >= 2) { u32x4 w4; w4.x = res0[ai * 4 + m].x; w4.y = res0[ai * 4 + m].y; w4.z = w.x; w4.w = w.y; *(u32x4*)(F + (size_t)row * DFF + j0) = w4; }
	v_pk_mul_f32 v[142:143], v[134:135], v[142:143]
	v_exp_f32_e32 v140, v140
	v_exp_f32_e32 v141, v141
	v_exp_f32_e32 v142, v142
	v_exp_f32_e32 v143, v143
	v_pk_add_f32 v[140:141], v[140:141], s[100:101]
	v_pk_add_f32 v[142:143], v[142:143], s[100:101]
	v_rcp_f32_e32 v140, v140
	v_rcp_f32_e32 v141, v141
	v_rcp_f32_e32 v142, v142
	v_rcp_f32_e32 v143, v143
	v_pk_mul_f32 v[140:141], v[132:133], v[140:141]
	v_pk_mul_f32 v[142:143], v[134:135], v[142:143]
	v_pk_mul_f32 v[140:141], v[140:141], v[136:137]
	v_pk_mul_f32 v[142:143], v[142:143], v[138:139]
	v_cvt_pk_bf16_f32 v128, v140, v141
	v_cvt_pk_bf16_f32 v129, v142, v143
	v_pk_fma_f32 v[132:133], v[28:29], v[190:191], v[178:179]
	v_pk_fma_f32 v[136:137], v[8:9], v[206:207], v[194:195]
	v_pk_fma_f32 v[134:135], v[30:31], v[192:193], v[180:181]
	v_pk_fma_f32 v[138:139], v[10:11], v[208:209], v[196:197]
	v_fmac_f32_dpp v132, v28, v186 row_shr:1 row_mask:0xf bank_mask:0xf
	v_fmac_f32_dpp v133, v29, v187 row_shr:1 row_mask:0xf bank_mask:0xf
	v_fmac_f32_dpp v134, v30, v188 row_shr:1 row_mask:0xf bank_mask:0xf
	v_fmac_f32_dpp v135, v31, v189 row_shr:1 row_mask:0xf bank_mask:0xf
	v_fmac_f32_dpp v136, v8, v202 row_shr:1 row_mask:0xf bank_mask:0xf
	v_fmac_f32_dpp v137, v9, v203 row_shr:1 row_mask:0xf bank_mask:0xf
	v_fmac_f32_dpp v138, v10, v204 row_shr:1 row_mask:0xf bank_mask:0xf
	v_fmac_f32_dpp v139, v11, v205 row_shr:1 row_mask:0xf bank_mask:0xf
	v_fmac_f32_dpp v132, v44, v186 row_shl:15 row_mask:0xf bank_mask:0xf
	v_fmac_f32_dpp v133, v45, v187 row_shl:15 row_mask:0xf bank_mask:0xf
	v_fmac_f32_dpp v134, v46, v188 row_shl:15 row_mask:0xf bank_mask:0xf
	v_fmac_f32_dpp v135, v47, v189 row_shl:15 row_mask:0xf bank_mask:0xf
	v_fmac_f32_dpp v136, v24, v202 row_shl:15 row_mask:0xf bank_mask:0xf
	v_fmac_f32_dpp v137, v25, v203 row_shl:15 row_mask:0xf bank_mask:0xf
	v_fmac_f32_dpp v138, v26, v204 row_shl:15 row_mask:0xf bank_mask:0xf
	v_fmac_f32_dpp v139, v27, v205 row_shl:15 row_mask:0xf bank_mask:0xf
	v_fmac_f32_dpp v132, v28, v182 row_shr:2 row_mask:0xf bank_mask:0xf
	v_fmac_f32_dpp v133, v29, v183 row_shr:2 row_mask:0xf bank_mask:0xf
	v_fmac_f32_dpp v134, v30, v184 row_shr:2 row_mask:0xf bank_mask:0xf
	v_fmac_f32_dpp v135, v31, v185 row_shr:2 row_mask:0xf bank_mask:0xf
	v_fmac_f32_dpp v136, v8, v198 row_shr:2 row_mask:0xf bank_mask:0xf
	v_fmac_f32_dpp v137, v9, v199 row_shr:2 row_mask:0xf bank_mask:0xf
	v_fmac_f32_dpp v138, v10, v200 row_shr:2 row_mask:0xf bank_mask:0xf
	v_fmac_f32_dpp v139, v11, v201 row_shr:2 row_mask:0xf bank_mask:0xf
	v_fmac_f32_dpp v132, v44, v182 row_shl:14 row_mask:0xf bank_mask:0xf
	v_fmac_f32_dpp v133, v45, v183 row_shl:14 row_mask:0xf bank_mask:0xf
	v_fmac_f32_dpp v134, v46, v184 row_shl:14 row_mask:0xf bank_mask:0xf
	v_fmac_f32_dpp v135, v47, v185 row_shl:14 row_mask:0xf bank_mask:0xf
	v_fmac_f32_dpp v136, v24, v198 row_shl:14 row_mask:0xf bank_mask:0xf
	v_fmac_f32_dpp v137, v25, v199 row_shl:14 row_mask:0xf bank_mask:0xf
	v_fmac_f32_dpp v138, v26, v200 row_shl:14 row_mask:0xf bank_mask:0xf
	v_fmac_f32_dpp v139, v27, v201 row_shl:14 row_mask:0xf bank_mask:0xf
	v_pk_mul_f32 v[140:141], v[132:133], v[132:133]
	v_pk_mul_f32 v[142:143], v[134:135], v[134:135]
	v_pk_fma_f32 v[140:141], v[140:141], s[98:99], v[244:245]
	v_pk_fma_f32 v[142:143], v[142:143], s[98:99], v[244:245]
	v_pk_mul_f32 v[140:141], v[132:133], v[140:141]
	v_pk_mul_f32 v[142:143], v[134:135], v[142:143]
	v_exp_f32_e32 v140, v140
	v_exp_f32_e32 v141, v141
	v_exp_f32_e32 v142, v142
	v_exp_f32_e32 v143, v143
	v_pk_add_f32 v[140:141], v[140:141], s[100:101]
	v_pk_add_f32 v[142:143], v[142:143], s[100:101]
	v_rcp_f32_e32 v140, v140
	v_rcp_f32_e32 v141, v141
	v_rcp_f32_e32 v142, v142
	v_rcp_f32_e32 v143, v143
	v_pk_mul_f32 v[140:141], v[132:133], v[140:141]
	v_pk_mul_f32 v[142:143], v[134:135], v[142:143]
	v_pk_mul_f32 v[140:141], v[140:141], v[136:137]
	v_pk_mul_f32 v[142:143], v[142:143], v[138:139]
	v_cvt_pk_bf16_f32 v130, v140, v141
	v_cvt_pk_bf16_f32 v131, v142, v143
	v_add_u32_e32 v144, 0xa0, v248
	v_mad_u64_u32 v[144:145], vcc, v144, s4, v[242:243]
	global_store_dwordx4 v[144:145], v[128:131], off nt
	v_pk_fma_f32 v[132:133], v[20:21], v[158:159], v[146:147]
	v_pk_fma_f32 v[136:137], v[4:5], v[174:175], v[162:163]
	v_pk_fma_f32 v[134:135], v[22:23], v[160:161], v[148:149]
	v_pk_fma_f32 v[138:139], v[6:7], v[176:177], v[164:165]
	v_fmac_f32_dpp v132, v20, v154 row_shr:1 row_mask:0xf bank_mask:0xf
	v_fmac_f32_dpp v133, v21, v155 row_shr:1 row_mask:0xf bank_mask:0xf
	v_fmac_f32_dpp v134, v22, v156 row_shr:1 row_mask:0xf bank_mask:0xf
	v_fmac_f32_dpp v135, v23, v157 row_shr:1 row_mask:0xf bank_mask:0xf
	v_fmac_f32_dpp v136, v4, v170 row_shr:1 row_mask:0xf bank_mask:0xf
	v_fmac_f32_dpp v137, v5, v171 row_shr:1 row_mask:0xf bank_mask:0xf
	v_fmac_f32_dpp v138, v6, v172 row_shr:1 row_mask:0xf bank_mask:0xf
	v_fmac_f32_dpp v139, v7, v173 row_shr:1 row_mask:0xf bank_mask:0xf
	v_fmac_f32_dpp v132, v36, v154 row_shl:15 row_mask:0xf bank_mask:0xf
	v_fmac_f32_dpp v133, v37, v155 row_shl:15 row_mask:0xf bank_mask:0xf
	v_fmac_f32_dpp v134, v38, v156 row_shl:15 row_mask:0xf bank_mask:0xf
	v_fmac_f32_dpp v135, v39, v157 row_shl:15 row_mask:0xf bank_mask:0xf
	v_fmac_f32_dpp v136, v16, v170 row_shl:15 row_mask:0xf bank_mask:0xf
	v_fmac_f32_dpp v137, v17, v171 row_shl:15 row_mask:0xf bank_mask:0xf
	v_fmac_f32_dpp v138, v18, v172 row_shl:15 row_mask:0xf bank_mask:0xf
	v_fmac_f32_dpp v139, v19, v173 row_shl:15 row_mask:0xf bank_mask:0xf
	v_fmac_f32_dpp v132, v20, v150 row_shr:2 row_mask:0xf bank_mask:0xf
	v_fmac_f32_dpp v133, v21, v151 row_shr:2 row_mask:0xf bank_mask:0xf
	v_fmac_f32_dpp v134, v22, v152 row_shr:2 row_mask:0xf bank_mask:0xf
; __device__ __forceinline__ unsigned pk2(float lo, float hi) { unsigned r; asm("v_cvt_pk_bf16_f32 %0, %1, %2" : "=v"(r) : "v"(lo), "v"(hi)); return r; }
; __device__ __forceinline__ float gelu_tanh(float x) { const float y = 1.5957691216f * (x + 0.044715f * x * x * x); return x * __builtin_amdgcn_rcpf(1.0f + __expf(-y)); }
; __device__ __forceinline__ float dpp_shr1(float old, float src) { return __int_as_float(__builtin_amdgcn_update_dpp(__float_as_int(old), __float_as_int(src), 0x111, 0xf, 0xf, false)); }
; __device__ __forceinline__ float dpp_shr2(float old, float src) { return __int_as_float(__builtin_amdgcn_update_dpp(__float_as_int(old), __float_as_int(src), 0x112, 0xf, 0xf, false)); }
;     __device__ __forceinline__ void operator()(const f32x4 (&acc)[2][2][4][2], const Unit& u, int wr, int wc, int fr, int fq) const {
;     ...
;                     for (int j = 0; j < 4; ++j) {
;                         const float g1 = dpp_shr1(dpp_ror1(gp[j]), g0[j]), g2 = dpp_shr2(dpp_ror2(gp[j]), g0[j]);
;                         const float v1 = dpp_shr1(dpp_ror1(vp[j]), v0[j]), v2 = dpp_shr2(dpp_ror2(vp[j]), v0[j]);
;                         const float cg_ = bg[j] + g2 * wg0[j] + g1 * wg1[j] + g0[j] * wg2[j];
;                         const float cv_ = bv[j] + v2 * wv0[j] + v1 * wv1[j] + v0[j] * wv2[j];
;                         f[j] = gelu_tanh(cg_) * cv_; }
;                     u32x2 w; w.x = pk2(f[0], f[1]); w.y = pk2(f[2], f[3]);
;                     if (n == 0) res0[ai * 4 + m] = w;
;                     else if (m > 0 || fr >= 2) { u32x4 w4; w4.x = res0[ai * 4 + m].x; w4.y = res0[ai * 4 + m].y; w4.z = w.x; w4.w = w.y; *(u32x4*)(F + (size_t)row * DFF + j0) = w4; }
;                     if (n == 1 && ((m == 0 && fr < 2) || (m == 3 && fr >= 14))) { const int slot = m == 0 ? fr : fr - 12;
;                         const f32x4 ga = acc[ai][0][m][0], va = acc[ai][1][m][0];
;                         bf16_t* bp = UPB + ((size_t)(row >> 6) * 4 + slot) * (2 * DFF) + col0;
;                         u32x4 wg_, wv_; wg_.x = pk2(ga[0], ga[1]); wg_.y = pk2(ga[2], ga[3]); wg_.z = pk2(g0[0], g0[1]); wg_.w = pk2(g0[2], g0[3]);
;                         wv_.x = pk2(va[0], va[1]); wv_.y = pk2(va[2], va[3]); wv_.z = pk2(v0[0], v0[1]); wv_.w = pk2(v0[2], v0[3]);
;                         *(u32x4*)bp = wg_; *(u32x4*)(bp + HALF) = wv_; } }
	v_fmac_f32_dpp v135, v23, v153 row_shr:2 row_mask:0xf bank_mask:0xf
	v_fmac_f32_dpp v136, v4, v166 row_shr:2 row_mask:0xf bank_mask:0xf
	v_fmac_f32_dpp v137, v5, v167 row_shr:2 row_mask:0xf bank_mask:0xf
	v_fmac_f32_dpp v138, v6, v168 row_shr:2 row_mask:0xf bank_mask:0xf
	v_fmac_f32_dpp v139, v7, v169 row_shr:2 row_mask:0xf bank_mask:0xf
	v_fmac_f32_dpp v132, v36, v150 row_shl:14 row_mask:0xf bank_mask:0xf
	v_fmac_f32_dpp v133, v37, v151 row_shl:14 row_mask:0xf bank_mask:0xf
	v_fmac_f32_dpp v134, v38, v152 row_shl:14 row_mask:0xf bank_mask:0xf
	v_fmac_f32_dpp v135, v39, v153 row_shl:14 row_mask:0xf bank_mask:0xf
	v_fmac_f32_dpp v136, v16, v166 row_shl:14 row_mask:0xf bank_mask:0xf
	v_fmac_f32_dpp v137, v17, v167 row_shl:14 row_mask:0xf bank_mask:0xf
	v_fmac_f32_dpp v138, v18, v168 row_shl:14 row_mask:0xf bank_mask:0xf
	v_fmac_f32_dpp v139, v19, v169 row_shl:14 row_mask:0xf bank_mask:0xf
	v_pk_mul_f32 v[140:141], v[132:133], v[132:133]
	v_pk_mul_f32 v[142:143], v[134:135], v[134:135]
	v_pk_fma_f32 v[140:141], v[140:141], s[98:99], v[244:245]
	v_pk_fma_f32 v[142:143], v[142:143], s[98:99], v[244:245]
	v_pk_mul_f32 v[140:141], v[132:133], v[140:141]
	v_pk_mul_f32 v[142:143], v[134:135], v[142:143]
	v_exp_f32_e32 v140, v140
	v_exp_f32_e32 v141, v141
	v_exp_f32_e32 v142, v142
	v_exp_f32_e32 v143, v143
	v_pk_add_f32 v[140:141], v[140:141], s[100:101]
	v_pk_add_f32 v[142:143], v[142:143], s[100:101]
	v_rcp_f32_e32 v140, v140
	v_rcp_f32_e32 v141, v141
	v_rcp_f32_e32 v142, v142
	v_rcp_f32_e32 v143, v143
	v_pk_mul_f32 v[140:141], v[132:133], v[140:141]
	v_pk_mul_f32 v[142:143], v[134:135], v[142:143]
	v_pk_mul_f32 v[140:141], v[140:141], v[136:137]
	v_pk_mul_f32 v[142:143], v[142:143], v[138:139]
	v_cvt_pk_bf16_f32 v250, v140, v141
	v_cvt_pk_bf16_f32 v251, v142, v143
	v_pk_fma_f32 v[132:133], v[12:13], v[190:191], v[178:179]
	v_pk_fma_f32 v[136:137], v[0:1], v[206:207], v[194:195]
	v_pk_fma_f32 v[134:135], v[14:15], v[192:193], v[180:181]
	v_pk_fma_f32 v[138:139], v[2:3], v[208:209], v[196:197]
	v_fmac_f32_dpp v132, v12, v186 row_shr:1 row_mask:0xf bank_mask:0xf
	v_fmac_f32_dpp v133, v13, v187 row_shr:1 row_mask:0xf bank_mask:0xf
	v_fmac_f32_dpp v134, v14, v188 row_shr:1 row_mask:0xf bank_mask:0xf
	v_fmac_f32_dpp v135, v15, v189 row_shr:1 row_mask:0xf bank_mask:0xf
	v_fmac_f32_dpp v136, v0, v202 row_shr:1 row_mask:0xf bank_mask:0xf
	v_fmac_f32_dpp v137, v1, v203 row_shr:1 row_mask:0xf bank_mask:0xf
	v_fmac_f32_dpp v138, v2, v204 row_shr:1 row_mask:0xf bank_mask:0xf
	v_fmac_f32_dpp v139, v3, v205 row_shr:1 row_mask:0xf bank_mask:0xf
	v_fmac_f32_dpp v132, v28, v186 row_shl:15 row_mask:0xf bank_mask:0xf
	v_fmac_f32_dpp v133, v29, v187 row_shl:15 row_mask:0xf bank_mask:0xf
	v_fmac_f32_dpp v134, v30, v188 row_shl:15 row_mask:0xf bank_mask:0xf
	v_fmac_f32_dpp v135, v31, v189 row_shl:15 row_mask:0xf bank_mask:0xf
	v_fmac_f32_dpp v136, v8, v202 row_shl:15 row_mask:0xf bank_mask:0xf
	v_fmac_f32_dpp v137, v9, v203 row_shl:15 row_mask:0xf bank_mask:0xf
	v_fmac_f32_dpp v138, v10, v204 row_shl:15 row_mask:0xf bank_mask:0xf
	v_fmac_f32_dpp v139, v11, v205 row_shl:15 row_mask:0xf bank_mask:0xf
	v_fmac_f32_dpp v132, v12, v182 row_shr:2 row_mask:0xf bank_mask:0xf
	v_fmac_f32_dpp v133, v13, v183 row_shr:2 row_mask:0xf bank_mask:0xf
	v_fmac_f32_dpp v134, v14, v184 row_shr:2 row_mask:0xf bank_mask:0xf
	v_fmac_f32_dpp v135, v15, v185 row_shr:2 row_mask:0xf bank_mask:0xf
	v_fmac_f32_dpp v136, v0, v198 row_shr:2 row_mask:0xf bank_mask:0xf
	v_fmac_f32_dpp v137, v1, v199 row_shr:2 row_mask:0xf bank_mask:0xf
	v_fmac_f32_dpp v138, v2, v200 row_shr:2 row_mask:0xf bank_mask:0xf
	v_fmac_f32_dpp v139, v3, v201 row_shr:2 row_mask:0xf bank_mask:0xf
	v_fmac_f32_dpp v132, v28, v182 row_shl:14 row_mask:0xf bank_mask:0xf
	v_fmac_f32_dpp v133, v29, v183 row_shl:14 row_mask:0xf bank_mask:0xf
	v_fmac_f32_dpp v134, v30, v184 row_shl:14 row_mask:0xf bank_mask:0xf
	v_fmac_f32_dpp v135, v31, v185 row_shl:14 row_mask:0xf bank_mask:0xf
	v_fmac_f32_dpp v136, v8, v198 row_shl:14 row_mask:0xf bank_mask:0xf
	v_fmac_f32_dpp v137, v9, v199 row_shl:14 row_mask:0xf bank_mask:0xf
	v_fmac_f32_dpp v138, v10, v200 row_shl:14 row_mask:0xf bank_mask:0xf
	v_fmac_f32_dpp v139, v11, v201 row_shl:14 row_mask:0xf bank_mask:0xf
	v_pk_mul_f32 v[140:141], v[132:133], v[132:133]
	v_pk_mul_f32 v[142:143], v[134:135], v[134:135]
	v_pk_fma_f32 v[140:141], v[140:141], s[98:99], v[244:245]
	v_pk_fma_f32 v[142:143], v[142:143], s[98:99], v[244:245]
	v_pk_mul_f32 v[140:141], v[132:133], v[140:141]
	v_pk_mul_f32 v[142:143], v[134:135], v[142:143]
	v_exp_f32_e32 v140, v140
	v_exp_f32_e32 v141, v141
	v_exp_f32_e32 v142, v142
	v_exp_f32_e32 v143, v143
	v_pk_add_f32 v[140:141], v[140:141], s[100:101]
	v_pk_add_f32 v[142:143], v[142:143], s[100:101]
	v_rcp_f32_e32 v140, v140
	v_rcp_f32_e32 v141, v141
	v_rcp_f32_e32 v142, v142
	v_rcp_f32_e32 v143, v143
	v_pk_mul_f32 v[140:141], v[132:133], v[140:141]
	v_pk_mul_f32 v[142:143], v[134:135], v[142:143]
	v_pk_mul_f32 v[140:141], v[140:141], v[136:137]
	v_pk_mul_f32 v[142:143], v[142:143], v[138:139]
	v_cvt_pk_bf16_f32 v252, v140, v141
	v_cvt_pk_bf16_f32 v253, v142, v143
	v_add_u32_e32 v144, 0xb0, v248
	v_mad_u64_u32 v[144:145], vcc, v144, s4, v[242:243]
	global_store_dwordx4 v[144:145], v[250:253], off nt
	s_mov_b64 s[0:1], 0
	s_and_saveexec_b64 s[42:43], s[12:13]
	s_xor_b64 s[52:53], exec, s[42:43]
	s_cbranch_execz .LBB0_1214
	v_add_u32_e32 v144, s73, v234
	v_mov_b64_e32 v[132:133], s[80:81]
	v_mad_u64_u32 v[132:133], vcc, v144, s83, v[132:133]
	v_lshl_add_u64 v[132:133], v[240:241], 1, v[132:133]
	s_mov_b64 s[72:73], exec
	v_cvt_pk_bf16_f32 v134, v20, v21
	v_cvt_pk_bf16_f32 v135, v22, v23
	v_cvt_pk_bf16_f32 v136, v12, v13
	v_cvt_pk_bf16_f32 v137, v14, v15
	v_cvt_pk_bf16_f32 v128, v4, v5
	v_cvt_pk_bf16_f32 v129, v6, v7
	v_cvt_pk_bf16_f32 v130, v0, v1
	v_cvt_pk_bf16_f32 v131, v2, v3
	global_store_dwordx4 v[132:133], v[134:137], off

; template <class Epi, class S_t>
; __device__ __forceinline__ void gemm_phase(LAS unsigned char* lds, int lda, int ldb, const S_t& S, const Epi& E) {
;     ...
;     for (;;) {
;         const bool has_next = S.next(ui + 1, nxt);
;         const char* nA = has_next ? nxt.A : cA; const char* nB = has_next ? nxt.B : cB;
;         const int nt = cur.nt;
;         for (int t = 0; t < nt; t += 2) {
;             const bool last = (t == nt - 2);
;             const char* a1 = cA + (size_t)(t + 1) * kstep;
;             const char* a2 = last ? nA : cA + (size_t)(t + 2) * kstep; const char* b2 = last ? nB : cB + (size_t)(t + 2) * kstep;
;             const char* a3 = a2 + kstep; const char* b3 = b2 + kstep;
;     ...
; #pragma unroll
;         for (int a = 0; a < 2; ++a)
; #pragma unroll
;             for (int b = 0; b < 2; ++b)
; #pragma unroll
;                 for (int m = 0; m < 4; ++m)
; #pragma unroll
;                     for (int n = 0; n < 2; ++n) acc[a][b][m][n] = (f32x4){0.f, 0.f, 0.f, 0.f};
;         cur = nxt; cA = nA; cB = nB; ++ui;
.LBB0_1382:
	s_add_i32 s0, s69, -2
	s_add_u32 s1, s48, 0x100
	s_addc_u32 s70, s49, 0
	s_mov_b32 s50, 0
	v_mov_b64_e32 v[0:1], 0
	v_mov_b64_e32 v[2:3], 0
	v_mov_b64_e32 v[4:5], 0
	v_mov_b64_e32 v[6:7], 0
	v_mov_b64_e32 v[8:9], 0
	v_mov_b64_e32 v[10:11], 0
	v_mov_b64_e32 v[12:13], 0
	v_mov_b64_e32 v[14:15], 0
	v_mov_b64_e32 v[16:17], 0
	v_mov_b64_e32 v[18:19], 0
	v_mov_b64_e32 v[20:21], 0
	v_mov_b64_e32 v[22:23], 0
	v_mov_b64_e32 v[24:25], 0
	v_mov_b64_e32 v[26:27], 0
	v_mov_b64_e32 v[28:29], 0
	v_mov_b64_e32 v[30:31], 0
	v_mov_b64_e32 v[32:33], 0
	v_mov_b64_e32 v[34:35], 0
	v_mov_b64_e32 v[36:37], 0
	v_mov_b64_e32 v[38:39], 0
	v_mov_b64_e32 v[40:41], 0
	v_mov_b64_e32 v[42:43], 0
	v_mov_b64_e32 v[44:45], 0
	v_mov_b64_e32 v[46:47], 0
	v_mov_b64_e32 v[48:49], 0
	v_mov_b64_e32 v[50:51], 0
	v_mov_b64_e32 v[52:53], 0
	v_mov_b64_e32 v[54:55], 0
	v_mov_b64_e32 v[56:57], 0
	v_mov_b64_e32 v[58:59], 0
	v_mov_b64_e32 v[60:61], 0
	v_mov_b64_e32 v[62:63], 0
	v_mov_b64_e32 v[64:65], 0
	v_mov_b64_e32 v[66:67], 0
	v_mov_b64_e32 v[68:69], 0
	v_mov_b64_e32 v[70:71], 0
	v_mov_b64_e32 v[72:73], 0
	v_mov_b64_e32 v[74:75], 0
	v_mov_b64_e32 v[76:77], 0
	v_mov_b64_e32 v[78:79], 0
	v_mov_b64_e32 v[80:81], 0
	v_mov_b64_e32 v[82:83], 0
	v_mov_b64_e32 v[84:85], 0
	v_mov_b64_e32 v[86:87], 0
	v_mov_b64_e32 v[88:89], 0
	v_mov_b64_e32 v[90:91], 0
	v_mov_b64_e32 v[92:93], 0
	v_mov_b64_e32 v[94:95], 0
	v_mov_b64_e32 v[96:97], 0
	v_mov_b64_e32 v[98:99], 0
	v_mov_b64_e32 v[100:101], 0
	v_mov_b64_e32 v[102:103], 0
	v_mov_b64_e32 v[104:105], 0
	v_mov_b64_e32 v[106:107], 0
	v_mov_b64_e32 v[108:109], 0
	v_mov_b64_e32 v[110:111], 0
	v_mov_b64_e32 v[112:113], 0
	v_mov_b64_e32 v[114:115], 0
	v_mov_b64_e32 v[116:117], 0
	v_mov_b64_e32 v[118:119], 0
	v_mov_b64_e32 v[120:121], 0
	v_mov_b64_e32 v[122:123], 0
	v_mov_b64_e32 v[124:125], 0
	v_mov_b64_e32 v[126:127], 0
	s_branch .LBB0_1383

; #define PG8_STAGE(bufoff, gbase, voff) do { _Pragma("unroll") for (int _i = 0; _i < 2; ++_i) \
;         __builtin_amdgcn_global_load_lds((const unsigned*)((const char*)(gbase) + (voff)[_i]), (LAS unsigned*)(lds + (bufoff) + ldsw + _i * 8192), 16, 0, 0); } while (0)
; #define PG8_LDA(dst, b, h) do { _Pragma("unroll") for (int m = 0; m < 4; ++m) _Pragma("unroll") for (int k = 0; k < 2; ++k) dst[m][k] = *(const LAS bf16x8*)(lds + PG8_SA(b, h) + aoff + m * 2048 + k * 1024); } while (0)
; #define PG8_LDB(dst, b, h) do { _Pragma("unroll") for (int n = 0; n < 2; ++n) _Pragma("unroll") for (int k = 0; k < 2; ++k) dst[n][k] = *(const LAS bf16x8*)(lds + PG8_SB(b, h) + boff + n * 2048 + k * 1024); } while (0)
; #define PG8_MMA(ai, bj, At, Bt) do { __builtin_amdgcn_s_setprio(1); _Pragma("unroll") for (int m = 0; m < 4; ++m) _Pragma("unroll") for (int n = 0; n < 2; ++n) _Pragma("unroll") for (int k = 0; k < 2; ++k) \
;         acc[ai][bj][m][n] = __builtin_amdgcn_mfma_f32_16x16x32_bf16(Bt[n][k], At[m][k], acc[ai][bj][m][n], 0, 0, 0); __builtin_amdgcn_s_setprio(0); } while (0)
; #define PG8_WAIT_V(n) asm volatile("s_waitcnt vmcnt(" #n ")" ::: "memory")
; #define PG8_WAIT_L(n) asm volatile("s_waitcnt lgkmcnt(" #n ")" ::: "memory")
; #define PG8_BAR __builtin_amdgcn_s_barrier()
; #define PG8_SCHED __builtin_amdgcn_sched_barrier(0)
; template <class Epi, class S_t>
; __device__ __forceinline__ void gemm_phase(LAS unsigned char* lds, int lda, int ldb, const S_t& S, const Epi& E) {
;     ...
;             PG8_LDB(B0, 0, 0); PG8_SCHED; PG8_LDA(At, 0, 0); PG8_STAGE(PG8_SA(1, 1), a1 + hstepA, voffA);
;             PG8_WAIT_L(8); PG8_BAR; PG8_WAIT_L(0); PG8_MMA(0, 0, At, B0); PG8_BAR; PG8_SCHED;
;             PG8_LDB(B1, 0, 1); PG8_STAGE(PG8_SB(0, 0), b2, voffB);
;             PG8_BAR; PG8_WAIT_L(0); PG8_MMA(0, 1, At, B1); PG8_BAR;
;             PG8_LDA(At, 0, 1); PG8_STAGE(PG8_SA(0, 0), a2, voffA);
;             PG8_BAR; PG8_WAIT_L(0); PG8_MMA(1, 0, At, B0); PG8_BAR; PG8_SCHED;
;             PG8_STAGE(PG8_SB(0, 1), b2 + hstepB, voffB);
;             PG8_WAIT_V(6); PG8_BAR; PG8_MMA(1, 1, At, B1); PG8_BAR;
.LBB0_1383:
	ds_read_b128 v[150:153], v146
	ds_read_b128 v[154:157], v146 offset:1024
	ds_read_b128 v[158:161], v146 offset:2048
	ds_read_b128 v[162:165], v146 offset:3072
	s_add_i32 s71, s50, 2
	s_add_u32 s48, s46, 0x100
	s_addc_u32 s49, s47, 0
	s_cmp_eq_u32 s0, s50
	s_cselect_b32 s50, s40, s1
	s_cselect_b32 s53, s43, s49
	s_cselect_b32 s52, s42, s48
	s_cselect_b32 s51, s41, s70
	s_add_i32 m0, s20, 0xc000
	ds_read_b128 v[166:169], v147
	ds_read_b128 v[170:173], v147 offset:1024
	ds_read_b128 v[174:177], v147 offset:2048
	ds_read_b128 v[178:181], v147 offset:3072
	ds_read_b128 v[182:185], v147 offset:4096
	ds_read_b128 v[186:189], v147 offset:5120
	ds_read_b128 v[190:193], v147 offset:6144
	ds_read_b128 v[194:197], v147 offset:7168
	global_load_lds_dwordx4 v136, s[46:47]
	s_add_i32 m0, s20, 0xe000
	s_nop 0
	global_load_lds_dwordx4 v138, s[46:47]
	s_waitcnt lgkmcnt(8)
	s_barrier
	s_waitcnt lgkmcnt(0)
	s_setprio 1
	v_mfma_f32_16x16x32_bf16 v[124:127], v[150:153], v[166:169], v[124:127]
	v_mfma_f32_16x16x32_bf16 v[120:123], v[158:161], v[166:169], v[120:123]
	v_mfma_f32_16x16x32_bf16 v[112:115], v[150:153], v[174:177], v[112:115]
	v_mfma_f32_16x16x32_bf16 v[104:107], v[158:161], v[174:177], v[104:107]
	v_mfma_f32_16x16x32_bf16 v[96:99], v[150:153], v[182:185], v[96:99]
	v_mfma_f32_16x16x32_bf16 v[88:91], v[158:161], v[182:185], v[88:91]
	v_mfma_f32_16x16x32_bf16 v[80:83], v[150:153], v[190:193], v[80:83]
	v_mfma_f32_16x16x32_bf16 v[72:75], v[158:161], v[190:193], v[72:75]
	v_mfma_f32_16x16x32_bf16 v[124:127], v[154:157], v[170:173], v[124:127]
	v_mfma_f32_16x16x32_bf16 v[120:123], v[162:165], v[170:173], v[120:123]
	v_mfma_f32_16x16x32_bf16 v[112:115], v[154:157], v[178:181], v[112:115]
	v_mfma_f32_16x16x32_bf16 v[104:107], v[162:165], v[178:181], v[104:107]
	v_mfma_f32_16x16x32_bf16 v[96:99], v[154:157], v[186:189], v[96:99]
	v_mfma_f32_16x16x32_bf16 v[88:91], v[162:165], v[186:189], v[88:91]
	v_mfma_f32_16x16x32_bf16 v[80:83], v[154:157], v[194:197], v[80:83]
	v_mfma_f32_16x16x32_bf16 v[72:75], v[162:165], v[194:197], v[72:75]
	s_setprio 0
	s_barrier
	s_add_i32 s33, s88, s17
	s_add_u32 s98, s50, s4
	s_addc_u32 s99, s51, s5
	s_mov_b32 m0, s33
	ds_read_b128 v[198:201], v148
	ds_read_b128 v[202:205], v148 offset:1024
	ds_read_b128 v[206:209], v148 offset:2048
	ds_read_b128 v[224:227], v148 offset:3072
	global_load_lds_dwordx4 v130, s[50:51]
	s_add_i32 m0, s33, 0x2000
	s_nop 0
	global_load_lds_dwordx4 v134, s[50:51]
	s_barrier
	s_waitcnt lgkmcnt(0)
	s_setprio 1
	v_mfma_f32_16x16x32_bf16 v[116:119], v[198:201], v[166:169], v[116:119]
	v_mfma_f32_16x16x32_bf16 v[108:111], v[206:209], v[166:169], v[108:111]
	v_mfma_f32_16x16x32_bf16 v[100:103], v[198:201], v[174:177], v[100:103]
	v_mfma_f32_16x16x32_bf16 v[92:95], v[206:209], v[174:177], v[92:95]
	v_mfma_f32_16x16x32_bf16 v[84:87], v[198:201], v[182:185], v[84:87]
	v_mfma_f32_16x16x32_bf16 v[76:79], v[206:209], v[182:185], v[76:79]
	v_mfma_f32_16x16x32_bf16 v[68:71], v[198:201], v[190:193], v[68:71]
	v_mfma_f32_16x16x32_bf16 v[64:67], v[206:209], v[190:193], v[64:67]
	v_mfma_f32_16x16x32_bf16 v[116:119], v[202:205], v[170:173], v[116:119]
	v_mfma_f32_16x16x32_bf16 v[108:111], v[224:227], v[170:173], v[108:111]
	v_mfma_f32_16x16x32_bf16 v[100:103], v[202:205], v[178:181], v[100:103]
	v_mfma_f32_16x16x32_bf16 v[92:95], v[224:227], v[178:181], v[92:95]
	v_mfma_f32_16x16x32_bf16 v[84:87], v[202:205], v[186:189], v[84:87]
	v_mfma_f32_16x16x32_bf16 v[76:79], v[224:227], v[186:189], v[76:79]
	v_mfma_f32_16x16x32_bf16 v[68:71], v[202:205], v[194:197], v[68:71]
	v_mfma_f32_16x16x32_bf16 v[64:67], v[224:227], v[194:197], v[64:67]
	s_setprio 0
	s_mov_b32 m0, s20
	s_add_u32 s100, s52, s4
	s_addc_u32 s101, s53, s5
	s_barrier
	ds_read_b128 v[166:169], v147 offset:16384
	ds_read_b128 v[170:173], v147 offset:17408
	ds_read_b128 v[174:177], v147 offset:18432
	ds_read_b128 v[178:181], v147 offset:19456
	ds_read_b128 v[182:185], v147 offset:20480
	ds_read_b128 v[186:189], v147 offset:21504
	ds_read_b128 v[190:193], v147 offset:22528
	ds_read_b128 v[194:197], v147 offset:23552
	global_load_lds_dwordx4 v128, s[52:53]
	s_mov_b32 m0, s21
	s_nop 0
	global_load_lds_dwordx4 v132, s[52:53]
	s_barrier
	s_waitcnt lgkmcnt(0)
	s_setprio 1
	v_mfma_f32_16x16x32_bf16 v[60:63], v[150:153], v[166:169], v[60:63]
	v_mfma_f32_16x16x32_bf16 v[56:59], v[158:161], v[166:169], v[56:59]
	v_mfma_f32_16x16x32_bf16 v[52:55], v[150:153], v[174:177], v[52:55]
	v_mfma_f32_16x16x32_bf16 v[44:47], v[158:161], v[174:177], v[44:47]
	v_mfma_f32_16x16x32_bf16 v[36:39], v[150:153], v[182:185], v[36:39]
	v_mfma_f32_16x16x32_bf16 v[28:31], v[158:161], v[182:185], v[28:31]
	v_mfma_f32_16x16x32_bf16 v[20:23], v[150:153], v[190:193], v[20:23]
	v_mfma_f32_16x16x32_bf16 v[12:15], v[158:161], v[190:193], v[12:15]
	v_mfma_f32_16x16x32_bf16 v[60:63], v[154:157], v[170:173], v[60:63]
	v_mfma_f32_16x16x32_bf16 v[56:59], v[162:165], v[170:173], v[56:59]
	v_mfma_f32_16x16x32_bf16 v[52:55], v[154:157], v[178:181], v[52:55]
	v_mfma_f32_16x16x32_bf16 v[44:47], v[162:165], v[178:181], v[44:47]
	v_mfma_f32_16x16x32_bf16 v[36:39], v[154:157], v[186:189], v[36:39]
	v_mfma_f32_16x16x32_bf16 v[28:31], v[162:165], v[186:189], v[28:31]
	v_mfma_f32_16x16x32_bf16 v[20:23], v[154:157], v[194:197], v[20:23]
	v_mfma_f32_16x16x32_bf16 v[12:15], v[162:165], v[194:197], v[12:15]
	s_setprio 0
	s_barrier
	s_add_u32 s46, s50, 0x180000
	s_addc_u32 s47, s51, 0
	s_add_i32 s33, s89, s17
	s_mov_b32 m0, s33
	s_nop 0
	global_load_lds_dwordx4 v130, s[46:47]
	s_add_i32 m0, s33, 0x2000
	s_nop 0
	global_load_lds_dwordx4 v134, s[46:47]
	s_waitcnt vmcnt(6)
	s_barrier
; #define PG8_STAGE(bufoff, gbase, voff) do { _Pragma("unroll") for (int _i = 0; _i < 2; ++_i) \
;         __builtin_amdgcn_global_load_lds((const unsigned*)((const char*)(gbase) + (voff)[_i]), (LAS unsigned*)(lds + (bufoff) + ldsw + _i * 8192), 16, 0, 0); } while (0)
; #define PG8_LDA(dst, b, h) do { _Pragma("unroll") for (int m = 0; m < 4; ++m) _Pragma("unroll") for (int k = 0; k < 2; ++k) dst[m][k] = *(const LAS bf16x8*)(lds + PG8_SA(b, h) + aoff + m * 2048 + k * 1024); } while (0)
; #define PG8_LDB(dst, b, h) do { _Pragma("unroll") for (int n = 0; n < 2; ++n) _Pragma("unroll") for (int k = 0; k < 2; ++k) dst[n][k] = *(const LAS bf16x8*)(lds + PG8_SB(b, h) + boff + n * 2048 + k * 1024); } while (0)
; #define PG8_MMA(ai, bj, At, Bt) do { __builtin_amdgcn_s_setprio(1); _Pragma("unroll") for (int m = 0; m < 4; ++m) _Pragma("unroll") for (int n = 0; n < 2; ++n) _Pragma("unroll") for (int k = 0; k < 2; ++k) \
;         acc[ai][bj][m][n] = __builtin_amdgcn_mfma_f32_16x16x32_bf16(Bt[n][k], At[m][k], acc[ai][bj][m][n], 0, 0, 0); __builtin_amdgcn_s_setprio(0); } while (0)
; #define PG8_WAIT_V(n) asm volatile("s_waitcnt vmcnt(" #n ")" ::: "memory")
; #define PG8_WAIT_L(n) asm volatile("s_waitcnt lgkmcnt(" #n ")" ::: "memory")
; #define PG8_BAR __builtin_amdgcn_s_barrier()
; #define PG8_SCHED __builtin_amdgcn_sched_barrier(0)
; template <class Epi, class S_t>
; __device__ __forceinline__ void gemm_phase(LAS unsigned char* lds, int lda, int ldb, const S_t& S, const Epi& E) {
;     ...
;             PG8_LDB(B0, 1, 0); PG8_SCHED; PG8_LDA(At, 1, 0); PG8_STAGE(PG8_SA(0, 1), a2 + hstepA, voffA);
;             PG8_WAIT_L(8); PG8_BAR; PG8_WAIT_L(0); PG8_MMA(0, 0, At, B0); PG8_BAR; PG8_SCHED;
;             PG8_LDB(B1, 1, 1); PG8_STAGE(PG8_SB(1, 0), b3, voffB);
;             PG8_BAR; PG8_WAIT_L(0); PG8_MMA(0, 1, At, B1); PG8_BAR;
;             PG8_LDA(At, 1, 1); PG8_STAGE(PG8_SA(1, 0), a3, voffA);
;             PG8_BAR; PG8_WAIT_L(0); PG8_MMA(1, 0, At, B0); PG8_BAR; PG8_SCHED;
;             PG8_STAGE(PG8_SB(1, 1), b3 + hstepB, voffB);
;             PG8_WAIT_V(6); PG8_BAR; PG8_MMA(1, 1, At, B1); PG8_BAR;
	s_setprio 1
	v_mfma_f32_16x16x32_bf16 v[48:51], v[198:201], v[166:169], v[48:51]
	v_mfma_f32_16x16x32_bf16 v[40:43], v[206:209], v[166:169], v[40:43]
	v_mfma_f32_16x16x32_bf16 v[32:35], v[198:201], v[174:177], v[32:35]
	v_mfma_f32_16x16x32_bf16 v[24:27], v[206:209], v[174:177], v[24:27]
	v_mfma_f32_16x16x32_bf16 v[16:19], v[198:201], v[182:185], v[16:19]
	v_mfma_f32_16x16x32_bf16 v[8:11], v[206:209], v[182:185], v[8:11]
	v_mfma_f32_16x16x32_bf16 v[4:7], v[198:201], v[190:193], v[4:7]
	v_mfma_f32_16x16x32_bf16 v[0:3], v[206:209], v[190:193], v[0:3]
	v_mfma_f32_16x16x32_bf16 v[48:51], v[202:205], v[170:173], v[48:51]
	v_mfma_f32_16x16x32_bf16 v[40:43], v[224:227], v[170:173], v[40:43]
	v_mfma_f32_16x16x32_bf16 v[32:35], v[202:205], v[178:181], v[32:35]
	v_mfma_f32_16x16x32_bf16 v[24:27], v[224:227], v[178:181], v[24:27]
	v_mfma_f32_16x16x32_bf16 v[16:19], v[202:205], v[186:189], v[16:19]
	v_mfma_f32_16x16x32_bf16 v[8:11], v[224:227], v[186:189], v[8:11]
	v_mfma_f32_16x16x32_bf16 v[4:7], v[202:205], v[194:197], v[4:7]
	v_mfma_f32_16x16x32_bf16 v[0:3], v[224:227], v[194:197], v[0:3]
	s_setprio 0
	v_add_u32_e32 v149, s90, v143
	s_barrier
	ds_read_b128 v[150:153], v149
	ds_read_b128 v[154:157], v149 offset:1024
	ds_read_b128 v[158:161], v149 offset:2048
	ds_read_b128 v[162:165], v149 offset:3072
	s_add_u32 s46, s52, 0x180000
	s_addc_u32 s47, s53, 0
	s_mov_b32 m0, s35
	ds_read_b128 v[166:169], v147 offset:32768
	ds_read_b128 v[170:173], v147 offset:33792
	ds_read_b128 v[174:177], v147 offset:34816
	ds_read_b128 v[178:181], v147 offset:35840
	ds_read_b128 v[182:185], v147 offset:36864
	ds_read_b128 v[186:189], v147 offset:37888
	ds_read_b128 v[190:193], v147 offset:38912
	ds_read_b128 v[194:197], v147 offset:39936
	global_load_lds_dwordx4 v128, s[46:47]
	s_mov_b32 m0, s54
	s_nop 0
	global_load_lds_dwordx4 v132, s[46:47]
	s_waitcnt lgkmcnt(8)
	s_barrier
	s_waitcnt lgkmcnt(0)
	s_setprio 1
	v_mfma_f32_16x16x32_bf16 v[124:127], v[150:153], v[166:169], v[124:127]
	v_mfma_f32_16x16x32_bf16 v[120:123], v[158:161], v[166:169], v[120:123]
	v_mfma_f32_16x16x32_bf16 v[112:115], v[150:153], v[174:177], v[112:115]
	v_mfma_f32_16x16x32_bf16 v[104:107], v[158:161], v[174:177], v[104:107]
	v_mfma_f32_16x16x32_bf16 v[96:99], v[150:153], v[182:185], v[96:99]
	v_mfma_f32_16x16x32_bf16 v[88:91], v[158:161], v[182:185], v[88:91]
	v_mfma_f32_16x16x32_bf16 v[80:83], v[150:153], v[190:193], v[80:83]
	v_mfma_f32_16x16x32_bf16 v[72:75], v[158:161], v[190:193], v[72:75]
	v_mfma_f32_16x16x32_bf16 v[124:127], v[154:157], v[170:173], v[124:127]
	v_mfma_f32_16x16x32_bf16 v[120:123], v[162:165], v[170:173], v[120:123]
	v_mfma_f32_16x16x32_bf16 v[112:115], v[154:157], v[178:181], v[112:115]
	v_mfma_f32_16x16x32_bf16 v[104:107], v[162:165], v[178:181], v[104:107]
	v_mfma_f32_16x16x32_bf16 v[96:99], v[154:157], v[186:189], v[96:99]
	v_mfma_f32_16x16x32_bf16 v[88:91], v[162:165], v[186:189], v[88:91]
	v_mfma_f32_16x16x32_bf16 v[80:83], v[154:157], v[194:197], v[80:83]
	v_mfma_f32_16x16x32_bf16 v[72:75], v[162:165], v[194:197], v[72:75]
	s_setprio 0
	s_barrier
	s_add_i32 s33, s90, s17
	v_add_u32_e32 v149, s91, v143
	s_mov_b32 m0, s33
	ds_read_b128 v[198:201], v149
	ds_read_b128 v[202:205], v149 offset:1024
	ds_read_b128 v[206:209], v149 offset:2048
	ds_read_b128 v[224:227], v149 offset:3072
	global_load_lds_dwordx4 v130, s[98:99]
	s_add_i32 m0, s33, 0x2000
	s_nop 0
	global_load_lds_dwordx4 v134, s[98:99]
	s_barrier
	s_waitcnt lgkmcnt(0)
	s_setprio 1
	v_mfma_f32_16x16x32_bf16 v[116:119], v[198:201], v[166:169], v[116:119]
	v_mfma_f32_16x16x32_bf16 v[108:111], v[206:209], v[166:169], v[108:111]
	v_mfma_f32_16x16x32_bf16 v[100:103], v[198:201], v[174:177], v[100:103]
	v_mfma_f32_16x16x32_bf16 v[92:95], v[206:209], v[174:177], v[92:95]
	v_mfma_f32_16x16x32_bf16 v[84:87], v[198:201], v[182:185], v[84:87]
	v_mfma_f32_16x16x32_bf16 v[76:79], v[206:209], v[182:185], v[76:79]
	v_mfma_f32_16x16x32_bf16 v[68:71], v[198:201], v[190:193], v[68:71]
	v_mfma_f32_16x16x32_bf16 v[64:67], v[206:209], v[190:193], v[64:67]
	v_mfma_f32_16x16x32_bf16 v[116:119], v[202:205], v[170:173], v[116:119]
	v_mfma_f32_16x16x32_bf16 v[108:111], v[224:227], v[170:173], v[108:111]
	v_mfma_f32_16x16x32_bf16 v[100:103], v[202:205], v[178:181], v[100:103]
	v_mfma_f32_16x16x32_bf16 v[92:95], v[224:227], v[178:181], v[92:95]
	v_mfma_f32_16x16x32_bf16 v[84:87], v[202:205], v[186:189], v[84:87]
	v_mfma_f32_16x16x32_bf16 v[76:79], v[224:227], v[186:189], v[76:79]
	v_mfma_f32_16x16x32_bf16 v[68:71], v[202:205], v[194:197], v[68:71]
	v_mfma_f32_16x16x32_bf16 v[64:67], v[224:227], v[194:197], v[64:67]
	s_setprio 0
	s_mov_b32 m0, s55
	s_barrier
	ds_read_b128 v[166:169], v147 offset:49152
	ds_read_b128 v[170:173], v147 offset:50176
	ds_read_b128 v[174:177], v147 offset:51200
	ds_read_b128 v[178:181], v147 offset:52224
	ds_read_b128 v[182:185], v147 offset:53248
	ds_read_b128 v[186:189], v147 offset:54272
	ds_read_b128 v[190:193], v147 offset:55296
	ds_read_b128 v[194:197], v147 offset:56320
	global_load_lds_dwordx4 v128, s[100:101]
	s_mov_b32 m0, s56
	s_nop 0
	global_load_lds_dwordx4 v132, s[100:101]
	s_barrier
; #define PG8_STAGE(bufoff, gbase, voff) do { _Pragma("unroll") for (int _i = 0; _i < 2; ++_i) \
;         __builtin_amdgcn_global_load_lds((const unsigned*)((const char*)(gbase) + (voff)[_i]), (LAS unsigned*)(lds + (bufoff) + ldsw + _i * 8192), 16, 0, 0); } while (0)
; #define PG8_MMA(ai, bj, At, Bt) do { __builtin_amdgcn_s_setprio(1); _Pragma("unroll") for (int m = 0; m < 4; ++m) _Pragma("unroll") for (int n = 0; n < 2; ++n) _Pragma("unroll") for (int k = 0; k < 2; ++k) \
;         acc[ai][bj][m][n] = __builtin_amdgcn_mfma_f32_16x16x32_bf16(Bt[n][k], At[m][k], acc[ai][bj][m][n], 0, 0, 0); __builtin_amdgcn_s_setprio(0); } while (0)
; #define PG8_WAIT_V(n) asm volatile("s_waitcnt vmcnt(" #n ")" ::: "memory")
; #define PG8_WAIT_L(n) asm volatile("s_waitcnt lgkmcnt(" #n ")" ::: "memory")
; #define PG8_BAR __builtin_amdgcn_s_barrier()
; #define PG8_SCHED __builtin_amdgcn_sched_barrier(0)
; template <class Epi, class S_t>
; __device__ __forceinline__ void gemm_phase(LAS unsigned char* lds, int lda, int ldb, const S_t& S, const Epi& E) {
;     ...
;             PG8_BAR; PG8_WAIT_L(0); PG8_MMA(1, 0, At, B0); PG8_BAR; PG8_SCHED;
;             PG8_STAGE(PG8_SB(1, 1), b3 + hstepB, voffB);
;             PG8_WAIT_V(6); PG8_BAR; PG8_MMA(1, 1, At, B1); PG8_BAR;
;         }
;         E(acc, cur, wr, wc, fr, fq);
;         if (!has_next) break;
;     __device__ __forceinline__ void operator()(const f32x4 (&acc)[2][2][4][2], const Unit& u, int wr, int wc, int fr, int fq) const {
;     ...
;             const int row0 = (u.pm - 32) * BM + wr * 64 + fr;
;             float* Op = Os + (size_t)(u.tag - 1) * (1024ull * DM);
; #pragma unroll
;             for (int ai = 0; ai < 2; ++ai)
; #pragma unroll
;                 for (int m = 0; m < 4; ++m) { float* rowp = Op + (size_t)(row0 + ai * HALF + m * 16) * DM + col0;
; #pragma unroll
;                     for (int bj = 0; bj < 2; ++bj)
; #pragma unroll
;                         for (int n = 0; n < 2; ++n) *(f32x4*)(rowp + bj * HALF + 4 * n) = acc[ai][bj][m][n]; }
	s_waitcnt lgkmcnt(0)
	s_setprio 1
	v_mfma_f32_16x16x32_bf16 v[60:63], v[150:153], v[166:169], v[60:63]
	v_mfma_f32_16x16x32_bf16 v[56:59], v[158:161], v[166:169], v[56:59]
	v_mfma_f32_16x16x32_bf16 v[52:55], v[150:153], v[174:177], v[52:55]
	v_mfma_f32_16x16x32_bf16 v[44:47], v[158:161], v[174:177], v[44:47]
	v_mfma_f32_16x16x32_bf16 v[36:39], v[150:153], v[182:185], v[36:39]
	v_mfma_f32_16x16x32_bf16 v[28:31], v[158:161], v[182:185], v[28:31]
	v_mfma_f32_16x16x32_bf16 v[20:23], v[150:153], v[190:193], v[20:23]
	v_mfma_f32_16x16x32_bf16 v[12:15], v[158:161], v[190:193], v[12:15]
	v_mfma_f32_16x16x32_bf16 v[60:63], v[154:157], v[170:173], v[60:63]
	v_mfma_f32_16x16x32_bf16 v[56:59], v[162:165], v[170:173], v[56:59]
	v_mfma_f32_16x16x32_bf16 v[52:55], v[154:157], v[178:181], v[52:55]
	v_mfma_f32_16x16x32_bf16 v[44:47], v[162:165], v[178:181], v[44:47]
	v_mfma_f32_16x16x32_bf16 v[36:39], v[154:157], v[186:189], v[36:39]
	v_mfma_f32_16x16x32_bf16 v[28:31], v[162:165], v[186:189], v[28:31]
	v_mfma_f32_16x16x32_bf16 v[20:23], v[154:157], v[194:197], v[20:23]
	v_mfma_f32_16x16x32_bf16 v[12:15], v[162:165], v[194:197], v[12:15]
	s_setprio 0
	s_barrier
	s_add_u32 s46, s50, 0x180080
	s_addc_u32 s47, s51, 0
	s_add_i32 s33, s91, s17
	s_mov_b32 m0, s33
	s_nop 0
	global_load_lds_dwordx4 v130, s[46:47]
	s_add_i32 m0, s33, 0x2000
	s_nop 0
	global_load_lds_dwordx4 v134, s[46:47]
	s_waitcnt vmcnt(6)
	s_barrier
	s_setprio 1
	v_mfma_f32_16x16x32_bf16 v[48:51], v[198:201], v[166:169], v[48:51]
	v_mfma_f32_16x16x32_bf16 v[40:43], v[206:209], v[166:169], v[40:43]
	v_mfma_f32_16x16x32_bf16 v[32:35], v[198:201], v[174:177], v[32:35]
	v_mfma_f32_16x16x32_bf16 v[24:27], v[206:209], v[174:177], v[24:27]
	v_mfma_f32_16x16x32_bf16 v[16:19], v[198:201], v[182:185], v[16:19]
	v_mfma_f32_16x16x32_bf16 v[8:11], v[206:209], v[182:185], v[8:11]
	v_mfma_f32_16x16x32_bf16 v[4:7], v[198:201], v[190:193], v[4:7]
	v_mfma_f32_16x16x32_bf16 v[0:3], v[206:209], v[190:193], v[0:3]
	v_mfma_f32_16x16x32_bf16 v[48:51], v[202:205], v[170:173], v[48:51]
	v_mfma_f32_16x16x32_bf16 v[40:43], v[224:227], v[170:173], v[40:43]
	v_mfma_f32_16x16x32_bf16 v[32:35], v[202:205], v[178:181], v[32:35]
	v_mfma_f32_16x16x32_bf16 v[24:27], v[224:227], v[178:181], v[24:27]
	v_mfma_f32_16x16x32_bf16 v[16:19], v[202:205], v[186:189], v[16:19]
	v_mfma_f32_16x16x32_bf16 v[8:11], v[224:227], v[186:189], v[8:11]
	v_mfma_f32_16x16x32_bf16 v[4:7], v[202:205], v[194:197], v[4:7]
	v_mfma_f32_16x16x32_bf16 v[0:3], v[224:227], v[194:197], v[0:3]
	s_setprio 0
	s_add_u32 s1, s1, 0x100
	s_addc_u32 s70, s70, 0
	s_cmp_ge_u32 s71, s69
	s_mov_b64 s[46:47], s[48:49]
	s_mov_b32 s50, s71
	s_cbranch_scc0 .Lrot_1383
	s_barrier
	v_lshl_or_b32 v140, s68, 8, v145
	s_lshl_b32 s33, s67, 8
	s_cmp_lg_u32 s2, 0
	v_ashrrev_i32_e32 v141, 31, v140
	s_cbranch_scc0 .LBB0_1386
	s_add_i32 s2, s2, -1
	s_lshl_b64 s[0:1], s[2:3], 23
	v_add_u32_e32 v150, s33, v144
	s_add_u32 s0, s6, s0
	v_or_b32_e32 v156, 16, v150
	s_addc_u32 s1, s7, s1
	v_ashrrev_i32_e32 v151, 31, v150
	v_ashrrev_i32_e32 v157, 31, v156
	v_lshl_add_u64 v[152:153], v[140:141], 2, s[0:1]
	v_lshlrev_b64 v[154:155], 13, v[150:151]
	v_lshlrev_b64 v[156:157], 13, v[156:157]
	v_lshl_add_u64 v[154:155], v[152:153], 0, v[154:155]
	v_lshl_add_u64 v[156:157], v[152:153], 0, v[156:157]
	global_store_dwordx4 v[154:155], v[124:127], off
	global_store_dwordx4 v[154:155], v[120:123], off offset:16
	global_store_dwordx4 v[154:155], v[116:119], off offset:512
	global_store_dwordx4 v[154:155], v[108:111], off offset:528
	global_store_dwordx4 v[156:157], v[112:115], off
	global_store_dwordx4 v[156:157], v[104:107], off offset:16
	global_store_dwordx4 v[156:157], v[100:103], off offset:512
	global_store_dwordx4 v[156:157], v[92:95], off offset:528
	v_or_b32_e32 v156, 32, v150
	v_or_b32_e32 v150, 48, v150
	v_ashrrev_i32_e32 v157, 31, v156
	v_ashrrev_i32_e32 v151, 31, v150
	v_lshlrev_b64 v[156:157], 13, v[156:157]
	v_lshlrev_b64 v[150:151], 13, v[150:151]
	v_lshl_add_u64 v[156:157], v[152:153], 0, v[156:157]
	v_lshl_add_u64 v[150:151], v[152:153], 0, v[150:151]
	v_add_co_u32_e32 v152, vcc, s60, v154
	global_store_dwordx4 v[156:157], v[96:99], off
	global_store_dwordx4 v[156:157], v[88:91], off offset:16
	global_store_dwordx4 v[156:157], v[84:87], off offset:512
	global_store_dwordx4 v[156:157], v[76:79], off offset:528
	v_addc_co_u32_e32 v153, vcc, 0, v155, vcc
	global_store_dwordx4 v[150:151], v[80:83], off
	global_store_dwordx4 v[150:151], v[72:75], off offset:16
	global_store_dwordx4 v[150:151], v[68:71], off offset:512
	global_store_dwordx4 v[150:151], v[64:67], off offset:528
	v_lshl_add_u64 v[150:151], v[154:155], 0, s[12:13]
	global_store_dwordx4 v[152:153], v[60:63], off
	global_store_dwordx4 v[150:151], v[56:59], off offset:16
	global_store_dwordx4 v[150:151], v[48:51], off offset:512
	global_store_dwordx4 v[150:151], v[40:43], off offset:528
	v_add_co_u32_e32 v152, vcc, s61, v154
	v_lshl_add_u64 v[150:151], v[154:155], 0, s[14:15]
	s_nop 0
	v_addc_co_u32_e32 v153, vcc, 0, v155, vcc
	global_store_dwordx4 v[152:153], v[52:55], off
	global_store_dwordx4 v[150:151], v[44:47], off offset:16
	global_store_dwordx4 v[150:151], v[32:35], off offset:512
	global_store_dwordx4 v[150:151], v[24:27], off offset:528
	v_add_co_u32_e32 v152, vcc, s62, v154
	v_lshl_add_u64 v[150:151], v[154:155], 0, s[18:19]
	s_nop 0
	v_addc_co_u32_e32 v153, vcc, 0, v155, vcc
	global_store_dwordx4 v[152:153], v[36:39], off
	global_store_dwordx4 v[150:151], v[28:31], off offset:16
	global_store_dwordx4 v[150:151], v[16:19], off offset:512
	global_store_dwordx4 v[150:151], v[8:11], off offset:528
	v_add_co_u32_e32 v152, vcc, 0x160000, v154
	v_lshl_add_u64 v[150:151], v[154:155], 0, s[22:23]
	s_nop 0
	v_addc_co_u32_e32 v153, vcc, 0, v155, vcc
	global_store_dwordx4 v[152:153], v[20:23], off
	global_store_dwordx4 v[150:151], v[12:15], off offset:16
	global_store_dwordx4 v[150:151], v[4:7], off offset:512
	global_store_dwordx4 v[150:151], v[0:3], off offset:528
	s_cbranch_execnz .LBB0_1379
	s_branch .LBB0_1378
